# speedup vs baseline: 1.0110x; 1.0110x over previous
; __device__ __forceinline__ void hgrn_pre_phase(KP p, char* smem, int wv, const int seg, const int gw, const int nw) {
;     ...
;   for (int idx = gw; idx < 2048; idx += nw) {
;     const int bh = idx >> 6, c = seg * 64 + (idx & 63), task = bh * 256 + c, b = bh >> 4, h = bh & 15;
;     const long r0 = (long)b * SEQ + c * 16;
;     const float* qsrc = p->proj + r0 * PW + h * 128 + lane * 2;
;     float2 qv[16], fv[16];
; #pragma unroll
;     for (int i = 0; i < 16; ++i) { qv[i] = *(const float2*)(qsrc + (long)i * PW); fv[i] = *(const float2*)(qsrc + 2048 + (long)i * PW); }
.LBB0_777:
	s_ashr_i32 s12, s61, 10
	s_and_b32 s62, s61, 63
	s_ashr_i32 s13, s12, 31
	s_lshl_b64 s[12:13], s[12:13], 12
	s_lshl_b32 s65, s62, 4
	s_or_b32 s12, s12, s65
	s_ashr_i32 s64, s61, 6
	s_mul_i32 s13, s13, 0xe080
	s_mul_hi_u32 s65, s12, 0xe080
	s_lshl_b32 s63, s64, 8
	s_add_i32 s65, s65, s13
	s_mul_i32 s12, s12, 0xe080
	s_waitcnt lgkmcnt(0)
	s_add_u32 s12, s14, s12
	s_addc_u32 s13, s15, s65
	s_lshl_b32 s64, s64, 9
	s_and_b32 s64, s64, 0x1e00
	s_add_u32 s12, s12, s64
	s_addc_u32 s13, s13, 0
	v_lshl_add_u64 v[2:3], s[12:13], 0, v[22:23]
	v_add_co_u32_e32 v0, vcc, s18, v2
	global_load_dwordx2 v[70:71], v22, s[12:13]
	s_nop 0
	v_addc_co_u32_e32 v1, vcc, 0, v3, vcc
	global_load_dwordx2 v[64:65], v[0:1], off nt
	v_add_co_u32_e32 v0, vcc, s19, v2
	s_nop 1
	v_addc_co_u32_e32 v1, vcc, 0, v3, vcc
	global_load_dwordx2 v[68:69], v[0:1], off offset:128 nt
	v_add_co_u32_e32 v0, vcc, s20, v2
	s_nop 1
	v_addc_co_u32_e32 v1, vcc, 0, v3, vcc
	global_load_dwordx2 v[66:67], v[0:1], off offset:128 nt
	v_add_co_u32_e32 v0, vcc, s21, v2
	s_nop 1
	v_addc_co_u32_e32 v1, vcc, 0, v3, vcc
	global_load_dwordx2 v[62:63], v[0:1], off offset:256 nt
	v_add_co_u32_e32 v0, vcc, s22, v2
	s_nop 1
	v_addc_co_u32_e32 v1, vcc, 0, v3, vcc
	global_load_dwordx2 v[56:57], v[0:1], off offset:256 nt
	v_add_co_u32_e32 v0, vcc, s23, v2
	s_nop 1
	v_addc_co_u32_e32 v1, vcc, 0, v3, vcc
	global_load_dwordx2 v[60:61], v[0:1], off offset:384 nt
	v_add_co_u32_e32 v0, vcc, s24, v2
	s_nop 1
	v_addc_co_u32_e32 v1, vcc, 0, v3, vcc
	global_load_dwordx2 v[58:59], v[0:1], off offset:384 nt
	v_add_co_u32_e32 v0, vcc, s25, v2
	s_nop 1
	v_addc_co_u32_e32 v1, vcc, 0, v3, vcc
	global_load_dwordx2 v[54:55], v[0:1], off offset:512 nt
	v_add_co_u32_e32 v0, vcc, s26, v2
	s_nop 1
	v_addc_co_u32_e32 v1, vcc, 0, v3, vcc
	global_load_dwordx2 v[48:49], v[0:1], off offset:512 nt
	v_add_co_u32_e32 v0, vcc, s27, v2
	s_nop 1
	v_addc_co_u32_e32 v1, vcc, 0, v3, vcc
	global_load_dwordx2 v[52:53], v[0:1], off offset:640 nt
	v_add_co_u32_e32 v0, vcc, s28, v2
	s_nop 1
	v_addc_co_u32_e32 v1, vcc, 0, v3, vcc
	global_load_dwordx2 v[50:51], v[0:1], off offset:640 nt
	v_add_co_u32_e32 v0, vcc, s29, v2
	s_nop 1
	v_addc_co_u32_e32 v1, vcc, 0, v3, vcc
	global_load_dwordx2 v[46:47], v[0:1], off offset:768 nt
	v_add_co_u32_e32 v0, vcc, s30, v2
	s_nop 1
	v_addc_co_u32_e32 v1, vcc, 0, v3, vcc
	global_load_dwordx2 v[40:41], v[0:1], off offset:768 nt
	v_add_co_u32_e32 v0, vcc, s31, v2
	s_nop 1
	v_addc_co_u32_e32 v1, vcc, 0, v3, vcc
	global_load_dwordx2 v[44:45], v[0:1], off offset:896 nt
	v_add_co_u32_e32 v0, vcc, s34, v2
	s_nop 1
	v_addc_co_u32_e32 v1, vcc, 0, v3, vcc
	global_load_dwordx2 v[42:43], v[0:1], off offset:896 nt
	v_add_co_u32_e32 v0, vcc, s35, v2
	s_nop 1
	v_addc_co_u32_e32 v1, vcc, 0, v3, vcc
	global_load_dwordx2 v[38:39], v[0:1], off offset:1024 nt
	v_add_co_u32_e32 v0, vcc, s36, v2
	s_nop 1
	v_addc_co_u32_e32 v1, vcc, 0, v3, vcc
	global_load_dwordx2 v[32:33], v[0:1], off offset:1024 nt
	v_add_co_u32_e32 v0, vcc, s37, v2
	s_nop 1
	v_addc_co_u32_e32 v1, vcc, 0, v3, vcc
	global_load_dwordx2 v[36:37], v[0:1], off offset:1152 nt
	v_add_co_u32_e32 v0, vcc, s38, v2
	s_nop 1
	v_addc_co_u32_e32 v1, vcc, 0, v3, vcc
	global_load_dwordx2 v[34:35], v[0:1], off offset:1152 nt
	v_add_co_u32_e32 v0, vcc, s40, v2
	s_nop 1
	v_addc_co_u32_e32 v1, vcc, 0, v3, vcc
	global_load_dwordx2 v[30:31], v[0:1], off offset:1280 nt
	v_add_co_u32_e32 v0, vcc, s41, v2
	s_nop 1
	v_addc_co_u32_e32 v1, vcc, 0, v3, vcc
	global_load_dwordx2 v[24:25], v[0:1], off offset:1280 nt
	v_add_co_u32_e32 v0, vcc, s42, v2
	s_nop 1
	v_addc_co_u32_e32 v1, vcc, 0, v3, vcc
	global_load_dwordx2 v[28:29], v[0:1], off offset:1408 nt
	v_add_co_u32_e32 v0, vcc, s43, v2
	s_nop 1
	v_addc_co_u32_e32 v1, vcc, 0, v3, vcc
	global_load_dwordx2 v[26:27], v[0:1], off offset:1408 nt
	v_add_co_u32_e32 v0, vcc, s44, v2
	s_nop 1
	v_addc_co_u32_e32 v1, vcc, 0, v3, vcc
	global_load_dwordx2 v[14:15], v[0:1], off offset:1536 nt
	v_add_co_u32_e32 v0, vcc, s45, v2
	s_nop 1
	v_addc_co_u32_e32 v1, vcc, 0, v3, vcc
	global_load_dwordx2 v[8:9], v[0:1], off offset:1536 nt
	v_add_co_u32_e32 v0, vcc, s46, v2
	s_nop 1
	v_addc_co_u32_e32 v1, vcc, 0, v3, vcc
	global_load_dwordx2 v[12:13], v[0:1], off offset:1664 nt
	v_add_co_u32_e32 v0, vcc, s47, v2
	s_nop 1
	v_addc_co_u32_e32 v1, vcc, 0, v3, vcc
	global_load_dwordx2 v[10:11], v[0:1], off offset:1664 nt
	v_add_co_u32_e32 v0, vcc, s49, v2
	s_nop 1
	v_addc_co_u32_e32 v1, vcc, 0, v3, vcc
	global_load_dwordx2 v[6:7], v[0:1], off offset:1792 nt
	v_add_co_u32_e32 v0, vcc, s50, v2
	s_nop 1
	v_addc_co_u32_e32 v1, vcc, 0, v3, vcc
	v_add_co_u32_e32 v4, vcc, s51, v2
	global_load_dwordx2 v[0:1], v[0:1], off offset:1792 nt
	s_nop 0
	v_addc_co_u32_e32 v5, vcc, 0, v3, vcc
	v_add_co_u32_e32 v2, vcc, s53, v2
	global_load_dwordx2 v[4:5], v[4:5], off offset:1920 nt
	s_nop 0
	v_addc_co_u32_e32 v3, vcc, 0, v3, vcc
	s_waitcnt vmcnt(0)
; __device__ __forceinline__ void hgrn_pre_phase(KP p, char* smem, int wv, const int seg, const int gw, const int nw) {
;     ...
;     for (int i = 0; i < 16; ++i) { qv[i] = *(const float2*)(qsrc + (long)i * PW); fv[i] = *(const float2*)(qsrc + 2048 + (long)i * PW); }
;     float lb0[16], lb1[16];
;     float c0 = 0.f, c1 = 0.f;
; #pragma unroll
;     for (int i = 0; i < 16; ++i) { c0 += __logf(fv[i].x); c1 += __logf(fv[i].y); lb0[i] = c0; lb1[i] = c1; }
	v_cmp_gt_f32_e32 vcc, s54, v64
	global_load_dwordx2 v[2:3], v[2:3], off offset:1920 nt
	s_nop 0
	v_cndmask_b32_e64 v72, 0, 32, vcc
	v_ldexp_f32 v72, v64, v72
	v_log_f32_e32 v72, v72
	s_nop 0
	v_mul_f32_e32 v73, 0x3f317217, v72
	v_fma_f32 v73, v72, s55, -v73
	v_fmac_f32_e32 v73, 0x3377d1cf, v72
	v_fmac_f32_e32 v73, 0x3f317217, v72
	v_cmp_lt_f32_e64 s[12:13], |v72|, s56
	s_nop 1
	v_cndmask_b32_e64 v72, v72, v73, s[12:13]
	v_cndmask_b32_e32 v73, 0, v76, vcc
	v_sub_f32_e32 v72, v72, v73
	v_cmp_gt_f32_e32 vcc, s54, v65
	v_add_f32_e32 v118, 0, v72
	s_nop 0
	v_cndmask_b32_e64 v72, 0, 32, vcc
	v_ldexp_f32 v72, v65, v72
	v_log_f32_e32 v72, v72
	s_nop 0
	v_mul_f32_e32 v73, 0x3f317217, v72
	v_fma_f32 v73, v72, s55, -v73
	v_fmac_f32_e32 v73, 0x3377d1cf, v72
	v_fmac_f32_e32 v73, 0x3f317217, v72
	v_cmp_lt_f32_e64 s[12:13], |v72|, s56
	s_nop 1
	v_cndmask_b32_e64 v72, v72, v73, s[12:13]
	v_cndmask_b32_e32 v73, 0, v76, vcc
	v_sub_f32_e32 v72, v72, v73
	v_cmp_gt_f32_e32 vcc, s54, v66
	v_add_f32_e32 v119, 0, v72
	s_nop 0
	v_cndmask_b32_e64 v72, 0, 32, vcc
	v_ldexp_f32 v72, v66, v72
	v_log_f32_e32 v72, v72
	s_nop 0
	v_mul_f32_e32 v73, 0x3f317217, v72
	v_fma_f32 v73, v72, s55, -v73
	v_fmac_f32_e32 v73, 0x3377d1cf, v72
	v_fmac_f32_e32 v73, 0x3f317217, v72
	v_cmp_lt_f32_e64 s[12:13], |v72|, s56
	s_nop 1
	v_cndmask_b32_e64 v72, v72, v73, s[12:13]
	v_cndmask_b32_e32 v73, 0, v76, vcc
	v_sub_f32_e32 v72, v72, v73
	v_cmp_gt_f32_e32 vcc, s54, v67
	v_add_f32_e32 v120, v118, v72
	v_mul_f32_e32 v118, 0x3fb8aa3b, v118
	v_cndmask_b32_e64 v72, 0, 32, vcc
	v_ldexp_f32 v72, v67, v72
	v_log_f32_e32 v72, v72
	v_exp_f32_e32 v118, v118
	v_mul_f32_e32 v73, 0x3f317217, v72
	v_fma_f32 v73, v72, s55, -v73
	v_fmac_f32_e32 v73, 0x3377d1cf, v72
	v_fmac_f32_e32 v73, 0x3f317217, v72
	v_cmp_lt_f32_e64 s[12:13], |v72|, s56
	v_mul_f32_e32 v70, v70, v118
	s_nop 0
	v_cndmask_b32_e64 v72, v72, v73, s[12:13]
	v_cndmask_b32_e32 v73, 0, v76, vcc
	v_sub_f32_e32 v72, v72, v73
	v_cmp_gt_f32_e32 vcc, s54, v56
	v_add_f32_e32 v121, v119, v72
	v_mul_f32_e32 v119, 0x3fb8aa3b, v119
	v_cndmask_b32_e64 v72, 0, 32, vcc
	v_ldexp_f32 v72, v56, v72
	v_log_f32_e32 v72, v72
	v_exp_f32_e32 v119, v119
	v_mul_f32_e32 v73, 0x3f317217, v72
	v_fma_f32 v73, v72, s55, -v73
	v_fmac_f32_e32 v73, 0x3377d1cf, v72
	v_fmac_f32_e32 v73, 0x3f317217, v72
	v_cmp_lt_f32_e64 s[12:13], |v72|, s56
	v_mul_f32_e32 v71, v71, v119
	s_nop 0
	v_cndmask_b32_e64 v72, v72, v73, s[12:13]
	v_cndmask_b32_e32 v73, 0, v76, vcc
	v_sub_f32_e32 v72, v72, v73
	v_cmp_gt_f32_e32 vcc, s54, v57
	v_add_f32_e32 v114, v120, v72
	s_nop 0
	v_cndmask_b32_e64 v72, 0, 32, vcc
	v_ldexp_f32 v72, v57, v72
	v_log_f32_e32 v72, v72
	s_nop 0
	v_mul_f32_e32 v73, 0x3f317217, v72
	v_fma_f32 v73, v72, s55, -v73
	v_fmac_f32_e32 v73, 0x3377d1cf, v72
	v_fmac_f32_e32 v73, 0x3f317217, v72
	v_cmp_lt_f32_e64 s[12:13], |v72|, s56
	s_nop 1
	v_cndmask_b32_e64 v72, v72, v73, s[12:13]
	v_cndmask_b32_e32 v73, 0, v76, vcc
	v_sub_f32_e32 v72, v72, v73
	v_cmp_gt_f32_e32 vcc, s54, v58
	v_add_f32_e32 v115, v121, v72
	s_nop 0
	v_cndmask_b32_e64 v72, 0, 32, vcc
	v_ldexp_f32 v72, v58, v72
	v_log_f32_e32 v72, v72
	s_nop 0
	v_mul_f32_e32 v73, 0x3f317217, v72
	v_fma_f32 v73, v72, s55, -v73
	v_fmac_f32_e32 v73, 0x3377d1cf, v72
	v_fmac_f32_e32 v73, 0x3f317217, v72
	v_cmp_lt_f32_e64 s[12:13], |v72|, s56
	s_nop 1
	v_cndmask_b32_e64 v72, v72, v73, s[12:13]
	v_cndmask_b32_e32 v73, 0, v76, vcc
	v_sub_f32_e32 v72, v72, v73
	v_cmp_gt_f32_e32 vcc, s54, v59
	v_add_f32_e32 v116, v114, v72
	s_nop 0
	v_cndmask_b32_e64 v72, 0, 32, vcc
	v_ldexp_f32 v72, v59, v72
	v_log_f32_e32 v72, v72
	s_nop 0
	v_mul_f32_e32 v73, 0x3f317217, v72
	v_fma_f32 v73, v72, s55, -v73
	v_fmac_f32_e32 v73, 0x3377d1cf, v72
	v_fmac_f32_e32 v73, 0x3f317217, v72
	v_cmp_lt_f32_e64 s[12:13], |v72|, s56
	s_nop 1
	v_cndmask_b32_e64 v72, v72, v73, s[12:13]
	v_cndmask_b32_e32 v73, 0, v76, vcc
	v_sub_f32_e32 v72, v72, v73
	v_cmp_gt_f32_e32 vcc, s54, v48
	v_add_f32_e32 v117, v115, v72
	s_nop 0
	v_cndmask_b32_e64 v72, 0, 32, vcc
	v_ldexp_f32 v72, v48, v72
	v_log_f32_e32 v72, v72
	s_nop 0
	v_mul_f32_e32 v73, 0x3f317217, v72
	v_fma_f32 v73, v72, s55, -v73
	v_fmac_f32_e32 v73, 0x3377d1cf, v72
	v_fmac_f32_e32 v73, 0x3f317217, v72
	v_cmp_lt_f32_e64 s[12:13], |v72|, s56
	s_nop 1
	v_cndmask_b32_e64 v72, v72, v73, s[12:13]
	v_cndmask_b32_e32 v73, 0, v76, vcc
	v_sub_f32_e32 v72, v72, v73
	v_cmp_gt_f32_e32 vcc, s54, v49
	v_add_f32_e32 v110, v116, v72
	s_nop 0
	v_cndmask_b32_e64 v72, 0, 32, vcc
	v_ldexp_f32 v72, v49, v72
	v_log_f32_e32 v72, v72
	s_nop 0
	v_mul_f32_e32 v73, 0x3f317217, v72
	v_fma_f32 v73, v72, s55, -v73
	v_fmac_f32_e32 v73, 0x3377d1cf, v72
	v_fmac_f32_e32 v73, 0x3f317217, v72
	v_cmp_lt_f32_e64 s[12:13], |v72|, s56
	s_nop 1
	v_cndmask_b32_e64 v72, v72, v73, s[12:13]
	v_cndmask_b32_e32 v73, 0, v76, vcc
	v_sub_f32_e32 v72, v72, v73
	v_cmp_gt_f32_e32 vcc, s54, v50
	v_add_f32_e32 v111, v117, v72
	s_nop 0
	v_cndmask_b32_e64 v72, 0, 32, vcc
	v_ldexp_f32 v72, v50, v72
	v_log_f32_e32 v72, v72
	s_nop 0
	v_mul_f32_e32 v73, 0x3f317217, v72
	v_fma_f32 v73, v72, s55, -v73
	v_fmac_f32_e32 v73, 0x3377d1cf, v72
	v_fmac_f32_e32 v73, 0x3f317217, v72
	v_cmp_lt_f32_e64 s[12:13], |v72|, s56
	s_nop 1
	v_cndmask_b32_e64 v72, v72, v73, s[12:13]
	v_cndmask_b32_e32 v73, 0, v76, vcc
	v_sub_f32_e32 v72, v72, v73
	v_cmp_gt_f32_e32 vcc, s54, v51
	v_add_f32_e32 v112, v110, v72
	s_nop 0
	v_cndmask_b32_e64 v72, 0, 32, vcc
	v_ldexp_f32 v72, v51, v72
	v_log_f32_e32 v72, v72
	s_nop 0
	v_mul_f32_e32 v73, 0x3f317217, v72
	v_fma_f32 v73, v72, s55, -v73
	v_fmac_f32_e32 v73, 0x3377d1cf, v72
	v_fmac_f32_e32 v73, 0x3f317217, v72
	v_cmp_lt_f32_e64 s[12:13], |v72|, s56
	s_nop 1
; __device__ __forceinline__ void hgrn_pre_phase(KP p, char* smem, int wv, const int seg, const int gw, const int nw) {
;     ...
;     for (int i = 0; i < 16; ++i) { c0 += __logf(fv[i].x); c1 += __logf(fv[i].y); lb0[i] = c0; lb1[i] = c1; }
	v_cndmask_b32_e64 v72, v72, v73, s[12:13]
	v_cndmask_b32_e32 v73, 0, v76, vcc
	v_sub_f32_e32 v72, v72, v73
	v_cmp_gt_f32_e32 vcc, s54, v40
	v_add_f32_e32 v113, v111, v72
	s_nop 0
	v_cndmask_b32_e64 v72, 0, 32, vcc
	v_ldexp_f32 v72, v40, v72
	v_log_f32_e32 v72, v72
	s_nop 0
	v_mul_f32_e32 v73, 0x3f317217, v72
	v_fma_f32 v73, v72, s55, -v73
	v_fmac_f32_e32 v73, 0x3377d1cf, v72
	v_fmac_f32_e32 v73, 0x3f317217, v72
	v_cmp_lt_f32_e64 s[12:13], |v72|, s56
	s_nop 1
	v_cndmask_b32_e64 v72, v72, v73, s[12:13]
	v_cndmask_b32_e32 v73, 0, v76, vcc
	v_sub_f32_e32 v72, v72, v73
	v_cmp_gt_f32_e32 vcc, s54, v41
	v_add_f32_e32 v106, v112, v72
	s_nop 0
	v_cndmask_b32_e64 v72, 0, 32, vcc
	v_ldexp_f32 v72, v41, v72
	v_log_f32_e32 v72, v72
	s_nop 0
	v_mul_f32_e32 v73, 0x3f317217, v72
	v_fma_f32 v73, v72, s55, -v73
	v_fmac_f32_e32 v73, 0x3377d1cf, v72
	v_fmac_f32_e32 v73, 0x3f317217, v72
	v_cmp_lt_f32_e64 s[12:13], |v72|, s56
	s_nop 1
	v_cndmask_b32_e64 v72, v72, v73, s[12:13]
	v_cndmask_b32_e32 v73, 0, v76, vcc
	v_sub_f32_e32 v72, v72, v73
	v_cmp_gt_f32_e32 vcc, s54, v42
	v_add_f32_e32 v107, v113, v72
	s_nop 0
	v_cndmask_b32_e64 v72, 0, 32, vcc
	v_ldexp_f32 v72, v42, v72
	v_log_f32_e32 v72, v72
	s_nop 0
	v_mul_f32_e32 v73, 0x3f317217, v72
	v_fma_f32 v73, v72, s55, -v73
	v_fmac_f32_e32 v73, 0x3377d1cf, v72
	v_fmac_f32_e32 v73, 0x3f317217, v72
	v_cmp_lt_f32_e64 s[12:13], |v72|, s56
	s_nop 1
	v_cndmask_b32_e64 v72, v72, v73, s[12:13]
	v_cndmask_b32_e32 v73, 0, v76, vcc
	v_sub_f32_e32 v72, v72, v73
	v_cmp_gt_f32_e32 vcc, s54, v43
	v_add_f32_e32 v108, v106, v72
	s_nop 0
	v_cndmask_b32_e64 v72, 0, 32, vcc
	v_ldexp_f32 v72, v43, v72
	v_log_f32_e32 v72, v72
	s_nop 0
	v_mul_f32_e32 v73, 0x3f317217, v72
	v_fma_f32 v73, v72, s55, -v73
	v_fmac_f32_e32 v73, 0x3377d1cf, v72
	v_fmac_f32_e32 v73, 0x3f317217, v72
	v_cmp_lt_f32_e64 s[12:13], |v72|, s56
	s_nop 1
	v_cndmask_b32_e64 v72, v72, v73, s[12:13]
	v_cndmask_b32_e32 v73, 0, v76, vcc
	v_sub_f32_e32 v72, v72, v73
	v_cmp_gt_f32_e32 vcc, s54, v32
	v_add_f32_e32 v109, v107, v72
	s_nop 0
	v_cndmask_b32_e64 v72, 0, 32, vcc
	v_ldexp_f32 v72, v32, v72
	v_log_f32_e32 v72, v72
	s_nop 0
	v_mul_f32_e32 v73, 0x3f317217, v72
	v_fma_f32 v73, v72, s55, -v73
	v_fmac_f32_e32 v73, 0x3377d1cf, v72
	v_fmac_f32_e32 v73, 0x3f317217, v72
	v_cmp_lt_f32_e64 s[12:13], |v72|, s56
	s_nop 1
	v_cndmask_b32_e64 v72, v72, v73, s[12:13]
	v_cndmask_b32_e32 v73, 0, v76, vcc
	v_sub_f32_e32 v72, v72, v73
	v_cmp_gt_f32_e32 vcc, s54, v33
	v_add_f32_e32 v102, v108, v72
	s_nop 0
	v_cndmask_b32_e64 v72, 0, 32, vcc
	v_ldexp_f32 v72, v33, v72
	v_log_f32_e32 v72, v72
	s_nop 0
	v_mul_f32_e32 v73, 0x3f317217, v72
	v_fma_f32 v73, v72, s55, -v73
	v_fmac_f32_e32 v73, 0x3377d1cf, v72
	v_fmac_f32_e32 v73, 0x3f317217, v72
	v_cmp_lt_f32_e64 s[12:13], |v72|, s56
	s_nop 1
	v_cndmask_b32_e64 v72, v72, v73, s[12:13]
	v_cndmask_b32_e32 v73, 0, v76, vcc
	v_sub_f32_e32 v72, v72, v73
	v_cmp_gt_f32_e32 vcc, s54, v34
	v_add_f32_e32 v103, v109, v72
	s_nop 0
	v_cndmask_b32_e64 v72, 0, 32, vcc
	v_ldexp_f32 v72, v34, v72
	v_log_f32_e32 v72, v72
	s_nop 0
	v_mul_f32_e32 v73, 0x3f317217, v72
	v_fma_f32 v73, v72, s55, -v73
	v_fmac_f32_e32 v73, 0x3377d1cf, v72
	v_fmac_f32_e32 v73, 0x3f317217, v72
	v_cmp_lt_f32_e64 s[12:13], |v72|, s56
	s_nop 1
	v_cndmask_b32_e64 v72, v72, v73, s[12:13]
	v_cndmask_b32_e32 v73, 0, v76, vcc
	v_sub_f32_e32 v72, v72, v73
	v_cmp_gt_f32_e32 vcc, s54, v35
	v_add_f32_e32 v104, v102, v72
	s_nop 0
	v_cndmask_b32_e64 v72, 0, 32, vcc
	v_ldexp_f32 v72, v35, v72
	v_log_f32_e32 v72, v72
	s_nop 0
	v_mul_f32_e32 v73, 0x3f317217, v72
	v_fma_f32 v73, v72, s55, -v73
	v_fmac_f32_e32 v73, 0x3377d1cf, v72
	v_fmac_f32_e32 v73, 0x3f317217, v72
	v_cmp_lt_f32_e64 s[12:13], |v72|, s56
	s_nop 1
	v_cndmask_b32_e64 v72, v72, v73, s[12:13]
	v_cndmask_b32_e32 v73, 0, v76, vcc
	v_sub_f32_e32 v72, v72, v73
	v_cmp_gt_f32_e32 vcc, s54, v24
	v_add_f32_e32 v105, v103, v72
	s_nop 0
	v_cndmask_b32_e64 v72, 0, 32, vcc
	v_ldexp_f32 v72, v24, v72
	v_log_f32_e32 v72, v72
	s_nop 0
	v_mul_f32_e32 v73, 0x3f317217, v72
	v_fma_f32 v73, v72, s55, -v73
	v_fmac_f32_e32 v73, 0x3377d1cf, v72
	v_fmac_f32_e32 v73, 0x3f317217, v72
	v_cmp_lt_f32_e64 s[12:13], |v72|, s56
	s_nop 1
	v_cndmask_b32_e64 v72, v72, v73, s[12:13]
	v_cndmask_b32_e32 v73, 0, v76, vcc
	v_sub_f32_e32 v72, v72, v73
	v_cmp_gt_f32_e32 vcc, s54, v25
	v_add_f32_e32 v98, v104, v72
	s_nop 0
	v_cndmask_b32_e64 v72, 0, 32, vcc
	v_ldexp_f32 v72, v25, v72
	v_log_f32_e32 v72, v72
	s_nop 0
	v_mul_f32_e32 v73, 0x3f317217, v72
	v_fma_f32 v73, v72, s55, -v73
	v_fmac_f32_e32 v73, 0x3377d1cf, v72
	v_fmac_f32_e32 v73, 0x3f317217, v72
	v_cmp_lt_f32_e64 s[12:13], |v72|, s56
	s_nop 1
	v_cndmask_b32_e64 v72, v72, v73, s[12:13]
	v_cndmask_b32_e32 v73, 0, v76, vcc
	v_sub_f32_e32 v72, v72, v73
	v_cmp_gt_f32_e32 vcc, s54, v26
	v_add_f32_e32 v99, v105, v72
	s_nop 0
	v_cndmask_b32_e64 v72, 0, 32, vcc
	v_ldexp_f32 v72, v26, v72
	v_log_f32_e32 v72, v72
	s_nop 0
	v_mul_f32_e32 v73, 0x3f317217, v72
	v_fma_f32 v73, v72, s55, -v73
	v_fmac_f32_e32 v73, 0x3377d1cf, v72
	v_fmac_f32_e32 v73, 0x3f317217, v72
	v_cmp_lt_f32_e64 s[12:13], |v72|, s56
	s_nop 1
	v_cndmask_b32_e64 v72, v72, v73, s[12:13]
	v_cndmask_b32_e32 v73, 0, v76, vcc
	v_sub_f32_e32 v72, v72, v73
	v_cmp_gt_f32_e32 vcc, s54, v27
	v_add_f32_e32 v100, v98, v72
	s_nop 0
	v_cndmask_b32_e64 v72, 0, 32, vcc
	v_ldexp_f32 v72, v27, v72
	v_log_f32_e32 v72, v72
	s_nop 0
	v_mul_f32_e32 v73, 0x3f317217, v72
	v_fma_f32 v73, v72, s55, -v73
	v_fmac_f32_e32 v73, 0x3377d1cf, v72
	v_fmac_f32_e32 v73, 0x3f317217, v72
	v_cmp_lt_f32_e64 s[12:13], |v72|, s56
	s_nop 1
	v_cndmask_b32_e64 v72, v72, v73, s[12:13]
	v_cndmask_b32_e32 v73, 0, v76, vcc
; __device__ __forceinline__ void hgrn_pre_phase(KP p, char* smem, int wv, const int seg, const int gw, const int nw) {
;     ...
;     for (int i = 0; i < 16; ++i) { c0 += __logf(fv[i].x); c1 += __logf(fv[i].y); lb0[i] = c0; lb1[i] = c1; }
;     char* tb = scr + (long)task * HG_TASK_B;
;     *(float2*)(tb + 8704 + lane * 8) = make_float2(__expf(c0), __expf(c1));
;     unsigned short kh0[16], kh1[16];
;     const float ec0 = __expf(c0), ec1 = __expf(c1);
; #pragma unroll
;     for (int i = 0; i < 16; ++i) {
;       const float e0 = __expf(lb0[i]), e1 = __expf(lb1[i]);
;       const float k0 = (1.f - fv[i].x) * __frcp_rn(e0), k1 = (1.f - fv[i].y) * __frcp_rn(e1);
;       const unsigned qt = (unsigned)f2bf(qv[i].x * e0) | ((unsigned)f2bf(qv[i].y * e1) << 16);
;       const unsigned kt = (unsigned)f2bf(k0) | ((unsigned)f2bf(k1) << 16);
;       *(unsigned*)(wl + i * 136 + lane * 2) = qt;
;       *(unsigned*)(wl + 2176 + i * 136 + lane * 2) = kt;
;       kh0[i] = f2bf(k0 * ec0);
;       kh1[i] = f2bf(k1 * ec1);
	v_sub_f32_e32 v72, v72, v73
	v_cmp_gt_f32_e32 vcc, s54, v8
	v_add_f32_e32 v101, v99, v72
	s_nop 0
	v_cndmask_b32_e64 v72, 0, 32, vcc
	v_ldexp_f32 v72, v8, v72
	v_log_f32_e32 v72, v72
	s_nop 0
	v_mul_f32_e32 v73, 0x3f317217, v72
	v_fma_f32 v73, v72, s55, -v73
	v_fmac_f32_e32 v73, 0x3377d1cf, v72
	v_fmac_f32_e32 v73, 0x3f317217, v72
	v_cmp_lt_f32_e64 s[12:13], |v72|, s56
	s_nop 1
	v_cndmask_b32_e64 v72, v72, v73, s[12:13]
	v_cndmask_b32_e32 v73, 0, v76, vcc
	v_sub_f32_e32 v72, v72, v73
	v_cmp_gt_f32_e32 vcc, s54, v9
	v_add_f32_e32 v94, v100, v72
	s_nop 0
	v_cndmask_b32_e64 v72, 0, 32, vcc
	v_ldexp_f32 v72, v9, v72
	v_log_f32_e32 v72, v72
	s_nop 0
	v_mul_f32_e32 v73, 0x3f317217, v72
	v_fma_f32 v73, v72, s55, -v73
	v_fmac_f32_e32 v73, 0x3377d1cf, v72
	v_fmac_f32_e32 v73, 0x3f317217, v72
	v_cmp_lt_f32_e64 s[12:13], |v72|, s56
	s_nop 1
	v_cndmask_b32_e64 v72, v72, v73, s[12:13]
	v_cndmask_b32_e32 v73, 0, v76, vcc
	v_sub_f32_e32 v72, v72, v73
	v_cmp_gt_f32_e32 vcc, s54, v10
	v_add_f32_e32 v95, v101, v72
	s_nop 0
	v_cndmask_b32_e64 v72, 0, 32, vcc
	v_ldexp_f32 v72, v10, v72
	v_log_f32_e32 v72, v72
	s_nop 0
	v_mul_f32_e32 v73, 0x3f317217, v72
	v_fma_f32 v73, v72, s55, -v73
	v_fmac_f32_e32 v73, 0x3377d1cf, v72
	v_fmac_f32_e32 v73, 0x3f317217, v72
	v_cmp_lt_f32_e64 s[12:13], |v72|, s56
	s_nop 1
	v_cndmask_b32_e64 v72, v72, v73, s[12:13]
	v_cndmask_b32_e32 v73, 0, v76, vcc
	v_sub_f32_e32 v72, v72, v73
	v_cmp_gt_f32_e32 vcc, s54, v11
	v_add_f32_e32 v96, v94, v72
	s_nop 0
	v_cndmask_b32_e64 v72, 0, 32, vcc
	v_ldexp_f32 v72, v11, v72
	v_log_f32_e32 v72, v72
	s_nop 0
	v_mul_f32_e32 v73, 0x3f317217, v72
	v_fma_f32 v73, v72, s55, -v73
	v_fmac_f32_e32 v73, 0x3377d1cf, v72
	v_fmac_f32_e32 v73, 0x3f317217, v72
	v_cmp_lt_f32_e64 s[12:13], |v72|, s56
	s_nop 1
	v_cndmask_b32_e64 v72, v72, v73, s[12:13]
	v_cndmask_b32_e32 v73, 0, v76, vcc
	v_sub_f32_e32 v72, v72, v73
	v_cmp_gt_f32_e32 vcc, s54, v0
	v_add_f32_e32 v97, v95, v72
	s_nop 0
	v_cndmask_b32_e64 v72, 0, 32, vcc
	v_ldexp_f32 v72, v0, v72
	v_log_f32_e32 v72, v72
	s_nop 0
	v_mul_f32_e32 v73, 0x3f317217, v72
	v_fma_f32 v73, v72, s55, -v73
	v_fmac_f32_e32 v73, 0x3377d1cf, v72
	v_fmac_f32_e32 v73, 0x3f317217, v72
	v_cmp_lt_f32_e64 s[12:13], |v72|, s56
	s_nop 1
	v_cndmask_b32_e64 v72, v72, v73, s[12:13]
	v_cndmask_b32_e32 v73, 0, v76, vcc
	v_sub_f32_e32 v72, v72, v73
	v_cmp_gt_f32_e32 vcc, s54, v1
	v_add_f32_e32 v92, v96, v72
	s_nop 0
	v_cndmask_b32_e64 v72, 0, 32, vcc
	v_ldexp_f32 v72, v1, v72
	v_log_f32_e32 v72, v72
	s_nop 0
	v_mul_f32_e32 v73, 0x3f317217, v72
	v_fma_f32 v73, v72, s55, -v73
	v_fmac_f32_e32 v73, 0x3377d1cf, v72
	v_fmac_f32_e32 v73, 0x3f317217, v72
	v_cmp_lt_f32_e64 s[12:13], |v72|, s56
	s_nop 1
	v_cndmask_b32_e64 v72, v72, v73, s[12:13]
	v_cndmask_b32_e32 v73, 0, v76, vcc
	v_sub_f32_e32 v72, v72, v73
	s_waitcnt vmcnt(0)
	v_cmp_gt_f32_e32 vcc, s54, v2
	v_add_f32_e32 v93, v97, v72
	s_nop 0
	v_cndmask_b32_e64 v72, 0, 32, vcc
	v_ldexp_f32 v72, v2, v72
	v_log_f32_e32 v72, v72
	s_nop 0
	v_mul_f32_e32 v73, 0x3f317217, v72
	v_fma_f32 v73, v72, s55, -v73
	v_fmac_f32_e32 v73, 0x3377d1cf, v72
	v_fmac_f32_e32 v73, 0x3f317217, v72
	v_cmp_lt_f32_e64 s[12:13], |v72|, s56
	s_nop 1
	v_cndmask_b32_e64 v72, v72, v73, s[12:13]
	v_cndmask_b32_e32 v73, 0, v76, vcc
	v_cmp_gt_f32_e32 vcc, s54, v3
	v_sub_f32_e32 v72, v72, v73
	v_add_f32_e32 v72, v92, v72
	v_cndmask_b32_e64 v73, 0, 32, vcc
	v_ldexp_f32 v73, v3, v73
	v_log_f32_e32 v73, v73
	v_mul_f32_e32 v72, 0x3fb8aa3b, v72
	v_exp_f32_e32 v72, v72
	v_mul_f32_e32 v122, 0x3f317217, v73
	v_fma_f32 v122, v73, s55, -v122
	v_fmac_f32_e32 v122, 0x3377d1cf, v73
	v_fmac_f32_e32 v122, 0x3f317217, v73
	v_cmp_lt_f32_e64 s[12:13], |v73|, s56
	v_mul_f32_e32 v4, v4, v72
	s_nop 0
	v_cndmask_b32_e64 v73, v73, v122, s[12:13]
	v_cndmask_b32_e32 v122, 0, v76, vcc
	v_sub_f32_e32 v73, v73, v122
	s_or_b32 s12, s63, s62
	v_add_f32_e32 v73, v93, v73
	s_mul_hi_i32 s13, s12, 0x2400
	s_mulk_i32 s12, 0x2400
	s_add_u32 s12, s2, s12
	v_mul_f32_e32 v73, 0x3fb8aa3b, v73
	s_addc_u32 s13, s3, s13
	v_exp_f32_e32 v73, v73
	v_lshl_add_u64 v[122:123], s[12:13], 0, v[16:17]
	v_add_co_u32_e32 v122, vcc, s18, v122
	v_mul_f32_e32 v5, v5, v73
	s_nop 0
	v_addc_co_u32_e32 v123, vcc, 0, v123, vcc
	global_store_dwordx2 v[122:123], v[72:73], off offset:512
	v_bfe_u32 v122, v70, 16, 1
	v_add3_u32 v70, v70, v122, s57
	v_bfe_u32 v122, v71, 16, 1
	v_lshrrev_b32_e32 v70, 16, v70
	v_add3_u32 v71, v71, v122, s57
	v_and_or_b32 v70, v71, s58, v70
	v_mul_f32_e32 v71, 0x3fb8aa3b, v120
	v_exp_f32_e32 v71, v71
	v_mul_f32_e32 v120, 0x3fb8aa3b, v121
	v_exp_f32_e32 v120, v120
	v_mul_f32_e32 v68, v68, v71
	v_bfe_u32 v121, v68, 16, 1
	v_mul_f32_e32 v69, v69, v120
	v_add3_u32 v68, v68, v121, s57
	v_bfe_u32 v121, v69, 16, 1
	v_lshrrev_b32_e32 v68, 16, v68
	v_add3_u32 v69, v69, v121, s57
	v_and_or_b32 v68, v69, s58, v68
	ds_write2_b32 v74, v70, v68 offset1:68
	v_mov_b32_e32 v68, v64
	v_div_scale_f32 v64, s[62:63], v71, v71, 1.0
	v_mov_b32_e32 v69, v66
	v_rcp_f32_e32 v66, v64
	v_pk_add_f32 v[68:69], v[68:69], 1.0 op_sel_hi:[1,0] neg_lo:[1,0] neg_hi:[1,0]
	v_fma_f32 v70, -v64, v66, 1.0
	v_fmac_f32_e32 v66, v70, v66
	v_div_scale_f32 v70, vcc, 1.0, v71, 1.0
	v_mul_f32_e32 v121, v70, v66
	v_fma_f32 v122, -v64, v121, v70
	v_fmac_f32_e32 v121, v122, v66
	v_fma_f32 v64, -v64, v121, v70
	v_div_fmas_f32 v64, v64, v66, v121
	v_div_fixup_f32 v71, v64, v71, 1.0
	v_div_scale_f32 v64, s[62:63], v118, v118, 1.0
	v_rcp_f32_e32 v66, v64
	s_nop 0
	v_fma_f32 v70, -v64, v66, 1.0
	v_fmac_f32_e32 v66, v70, v66
	v_div_scale_f32 v70, vcc, 1.0, v118, 1.0
	v_mul_f32_e32 v121, v70, v66
	v_fma_f32 v122, -v64, v121, v70
	v_fmac_f32_e32 v121, v122, v66
; __device__ __forceinline__ void hgrn_pre_phase(KP p, char* smem, int wv, const int seg, const int gw, const int nw) {
;     ...
;     for (int i = 0; i < 16; ++i) {
;       const float e0 = __expf(lb0[i]), e1 = __expf(lb1[i]);
;       const float k0 = (1.f - fv[i].x) * __frcp_rn(e0), k1 = (1.f - fv[i].y) * __frcp_rn(e1);
;       const unsigned qt = (unsigned)f2bf(qv[i].x * e0) | ((unsigned)f2bf(qv[i].y * e1) << 16);
;       const unsigned kt = (unsigned)f2bf(k0) | ((unsigned)f2bf(k1) << 16);
;       *(unsigned*)(wl + i * 136 + lane * 2) = qt;
;       *(unsigned*)(wl + 2176 + i * 136 + lane * 2) = kt;
;       kh0[i] = f2bf(k0 * ec0);
;       kh1[i] = f2bf(k1 * ec1);
;     }
	v_fma_f32 v64, -v64, v121, v70
	v_div_fmas_f32 v64, v64, v66, v121
	v_div_fixup_f32 v70, v64, v118, 1.0
	v_pk_mul_f32 v[68:69], v[68:69], v[70:71]
	v_mov_b32_e32 v66, v65
	v_bfe_u32 v64, v68, 16, 1
	v_add3_u32 v64, v68, v64, s57
	v_lshrrev_b32_e32 v70, 16, v64
	v_bfe_u32 v64, v69, 16, 1
	v_add3_u32 v64, v69, v64, s57
	v_lshrrev_b32_e32 v71, 16, v64
	v_pk_add_f32 v[64:65], v[66:67], 1.0 op_sel_hi:[1,0] neg_lo:[1,0] neg_hi:[1,0]
	v_div_scale_f32 v66, s[62:63], v120, v120, 1.0
	v_rcp_f32_e32 v67, v66
	v_pk_mul_f32 v[68:69], v[68:69], v[72:73] op_sel_hi:[1,0]
	v_fma_f32 v118, -v66, v67, 1.0
	v_fmac_f32_e32 v67, v118, v67
	v_div_scale_f32 v118, vcc, 1.0, v120, 1.0
	v_mul_f32_e32 v121, v118, v67
	v_fma_f32 v122, -v66, v121, v118
	v_fmac_f32_e32 v121, v122, v67
	v_fma_f32 v66, -v66, v121, v118
	v_div_fmas_f32 v66, v66, v67, v121
	v_div_fixup_f32 v67, v66, v120, 1.0
	v_div_scale_f32 v66, s[62:63], v119, v119, 1.0
	v_rcp_f32_e32 v118, v66
	s_nop 0
	v_fma_f32 v120, -v66, v118, 1.0
	v_fmac_f32_e32 v118, v120, v118
	v_div_scale_f32 v120, vcc, 1.0, v119, 1.0
	v_mul_f32_e32 v121, v120, v118
	v_fma_f32 v122, -v66, v121, v120
	v_fmac_f32_e32 v121, v122, v118
	v_fma_f32 v66, -v66, v121, v120
	v_div_fmas_f32 v66, v66, v118, v121
	v_div_fixup_f32 v66, v66, v119, 1.0
	v_pk_mul_f32 v[64:65], v[64:65], v[66:67]
	s_nop 0
	v_bfe_u32 v66, v64, 16, 1
	v_bfe_u32 v67, v65, 16, 1
	v_add3_u32 v66, v64, v66, s57
	v_add3_u32 v67, v65, v67, s57
	v_and_or_b32 v66, v66, s58, v70
	v_and_or_b32 v67, v67, s58, v71
	ds_write2_b32 v81, v66, v67 offset0:64 offset1:132
	v_mov_b32_e32 v66, v73
	v_pk_mul_f32 v[64:65], v[64:65], v[66:67] op_sel_hi:[1,0]
	v_mul_f32_e32 v67, 0x3fb8aa3b, v114
	v_exp_f32_e32 v67, v67
	v_mul_f32_e32 v70, 0x3fb8aa3b, v115
	v_exp_f32_e32 v70, v70
	v_mul_f32_e32 v62, v62, v67
	v_bfe_u32 v71, v62, 16, 1
	v_mul_f32_e32 v63, v63, v70
	v_add3_u32 v62, v62, v71, s57
	v_bfe_u32 v71, v63, 16, 1
	v_lshrrev_b32_e32 v62, 16, v62
	v_add3_u32 v63, v63, v71, s57
	v_and_or_b32 v62, v63, s58, v62
	v_mul_f32_e32 v63, 0x3fb8aa3b, v116
	v_exp_f32_e32 v63, v63
	v_mul_f32_e32 v71, 0x3fb8aa3b, v117
	v_exp_f32_e32 v71, v71
	v_mul_f32_e32 v60, v60, v63
	v_bfe_u32 v114, v60, 16, 1
	v_mul_f32_e32 v61, v61, v71
	v_add3_u32 v60, v60, v114, s57
	v_bfe_u32 v114, v61, 16, 1
	v_lshrrev_b32_e32 v60, 16, v60
	v_add3_u32 v61, v61, v114, s57
	v_and_or_b32 v60, v61, s58, v60
	ds_write2_b32 v74, v62, v60 offset0:136 offset1:204
	v_mov_b32_e32 v60, v56
	v_div_scale_f32 v56, s[62:63], v67, v67, 1.0
	v_mov_b32_e32 v61, v58
	v_rcp_f32_e32 v58, v56
	v_pk_add_f32 v[60:61], v[60:61], 1.0 op_sel_hi:[1,0] neg_lo:[1,0] neg_hi:[1,0]
	v_fma_f32 v62, -v56, v58, 1.0
	v_fmac_f32_e32 v58, v62, v58
	v_div_scale_f32 v62, vcc, 1.0, v67, 1.0
	v_mul_f32_e32 v114, v62, v58
	v_fma_f32 v115, -v56, v114, v62
	v_fmac_f32_e32 v114, v115, v58
	v_fma_f32 v56, -v56, v114, v62
	v_div_fmas_f32 v56, v56, v58, v114
	v_div_fixup_f32 v62, v56, v67, 1.0
	v_div_scale_f32 v56, s[62:63], v63, v63, 1.0
	v_rcp_f32_e32 v58, v56
	s_nop 0
	v_fma_f32 v67, -v56, v58, 1.0
	v_fmac_f32_e32 v58, v67, v58
	v_div_scale_f32 v67, vcc, 1.0, v63, 1.0
	v_mul_f32_e32 v114, v67, v58
	v_fma_f32 v115, -v56, v114, v67
	v_fmac_f32_e32 v114, v115, v58
	v_fma_f32 v56, -v56, v114, v67
	v_div_fmas_f32 v56, v56, v58, v114
	v_div_fixup_f32 v63, v56, v63, 1.0
	v_pk_mul_f32 v[60:61], v[60:61], v[62:63]
	v_mov_b32_e32 v58, v57
	v_bfe_u32 v56, v60, 16, 1
	v_add3_u32 v56, v60, v56, s57
	v_lshrrev_b32_e32 v62, 16, v56
	v_bfe_u32 v56, v61, 16, 1
	v_add3_u32 v56, v61, v56, s57
	v_lshrrev_b32_e32 v63, 16, v56
	v_pk_add_f32 v[56:57], v[58:59], 1.0 op_sel_hi:[1,0] neg_lo:[1,0] neg_hi:[1,0]
	v_div_scale_f32 v58, s[62:63], v70, v70, 1.0
	v_rcp_f32_e32 v59, v58
	v_pk_mul_f32 v[60:61], v[60:61], v[72:73] op_sel_hi:[1,0]
	v_fma_f32 v67, -v58, v59, 1.0
	v_fmac_f32_e32 v59, v67, v59
	v_div_scale_f32 v67, vcc, 1.0, v70, 1.0
	v_mul_f32_e32 v114, v67, v59
	v_fma_f32 v115, -v58, v114, v67
	v_fmac_f32_e32 v114, v115, v59
	v_fma_f32 v58, -v58, v114, v67
	v_div_fmas_f32 v58, v58, v59, v114
	v_div_scale_f32 v59, s[62:63], v71, v71, 1.0
	v_rcp_f32_e32 v67, v59
	v_div_fixup_f32 v58, v58, v70, 1.0
	v_fma_f32 v70, -v59, v67, 1.0
	v_fmac_f32_e32 v67, v70, v67
	v_div_scale_f32 v70, vcc, 1.0, v71, 1.0
	v_mul_f32_e32 v114, v70, v67
	v_fma_f32 v115, -v59, v114, v70
	v_fmac_f32_e32 v114, v115, v67
	v_fma_f32 v59, -v59, v114, v70
	v_div_fmas_f32 v59, v59, v67, v114
	v_div_fixup_f32 v59, v59, v71, 1.0
	v_pk_mul_f32 v[56:57], v[56:57], v[58:59]
	s_nop 0
	v_bfe_u32 v58, v56, 16, 1
	v_bfe_u32 v59, v57, 16, 1
	v_add3_u32 v58, v56, v58, s57
	v_add3_u32 v59, v57, v59, s57
	v_and_or_b32 v58, v58, s58, v62
	v_and_or_b32 v59, v59, s58, v63
	ds_write2_b32 v82, v58, v59 offset0:72 offset1:140
	v_mul_f32_e32 v58, 0x3fb8aa3b, v110
	v_exp_f32_e32 v58, v58
	v_mul_f32_e32 v59, 0x3fb8aa3b, v111
	v_exp_f32_e32 v59, v59
	v_pk_mul_f32 v[56:57], v[56:57], v[66:67] op_sel_hi:[1,0]
	v_mul_f32_e32 v54, v54, v58
	v_bfe_u32 v62, v54, 16, 1
	v_mul_f32_e32 v55, v55, v59
	v_add3_u32 v54, v54, v62, s57
	v_bfe_u32 v62, v55, 16, 1
	v_lshrrev_b32_e32 v54, 16, v54
	v_add3_u32 v55, v55, v62, s57
	v_and_or_b32 v54, v55, s58, v54
	v_mul_f32_e32 v55, 0x3fb8aa3b, v112
	v_exp_f32_e32 v55, v55
	v_mul_f32_e32 v62, 0x3fb8aa3b, v113
	v_exp_f32_e32 v62, v62
	v_mul_f32_e32 v52, v52, v55
	v_bfe_u32 v63, v52, 16, 1
	v_mul_f32_e32 v53, v53, v62
	v_add3_u32 v52, v52, v63, s57
	v_bfe_u32 v63, v53, 16, 1
	v_lshrrev_b32_e32 v52, 16, v52
	v_add3_u32 v53, v53, v63, s57
	v_and_or_b32 v52, v53, s58, v52
	ds_write2_b32 v83, v54, v52 offset0:16 offset1:84
	v_mov_b32_e32 v52, v48
	v_div_scale_f32 v48, s[62:63], v58, v58, 1.0
	v_mov_b32_e32 v53, v50
; __device__ __forceinline__ void hgrn_pre_phase(KP p, char* smem, int wv, const int seg, const int gw, const int nw) {
;     ...
;     for (int i = 0; i < 16; ++i) {
;       const float e0 = __expf(lb0[i]), e1 = __expf(lb1[i]);
;       const float k0 = (1.f - fv[i].x) * __frcp_rn(e0), k1 = (1.f - fv[i].y) * __frcp_rn(e1);
;       const unsigned qt = (unsigned)f2bf(qv[i].x * e0) | ((unsigned)f2bf(qv[i].y * e1) << 16);
;       const unsigned kt = (unsigned)f2bf(k0) | ((unsigned)f2bf(k1) << 16);
;       *(unsigned*)(wl + i * 136 + lane * 2) = qt;
;       *(unsigned*)(wl + 2176 + i * 136 + lane * 2) = kt;
;       kh0[i] = f2bf(k0 * ec0);
;       kh1[i] = f2bf(k1 * ec1);
;     }
	v_rcp_f32_e32 v50, v48
	v_pk_add_f32 v[52:53], v[52:53], 1.0 op_sel_hi:[1,0] neg_lo:[1,0] neg_hi:[1,0]
	v_fma_f32 v54, -v48, v50, 1.0
	v_fmac_f32_e32 v50, v54, v50
	v_div_scale_f32 v54, vcc, 1.0, v58, 1.0
	v_mul_f32_e32 v63, v54, v50
	v_fma_f32 v67, -v48, v63, v54
	v_fmac_f32_e32 v63, v67, v50
	v_fma_f32 v48, -v48, v63, v54
	v_div_fmas_f32 v48, v48, v50, v63
	v_div_fixup_f32 v54, v48, v58, 1.0
	v_div_scale_f32 v48, s[62:63], v55, v55, 1.0
	v_rcp_f32_e32 v50, v48
	s_nop 0
	v_fma_f32 v58, -v48, v50, 1.0
	v_fmac_f32_e32 v50, v58, v50
	v_div_scale_f32 v58, vcc, 1.0, v55, 1.0
	v_mul_f32_e32 v63, v58, v50
	v_fma_f32 v67, -v48, v63, v58
	v_fmac_f32_e32 v63, v67, v50
	v_fma_f32 v48, -v48, v63, v58
	v_div_fmas_f32 v48, v48, v50, v63
	v_div_fixup_f32 v55, v48, v55, 1.0
	v_pk_mul_f32 v[52:53], v[52:53], v[54:55]
	v_mov_b32_e32 v50, v49
	v_bfe_u32 v48, v52, 16, 1
	v_add3_u32 v48, v52, v48, s57
	v_lshrrev_b32_e32 v54, 16, v48
	v_bfe_u32 v48, v53, 16, 1
	v_add3_u32 v48, v53, v48, s57
	v_lshrrev_b32_e32 v55, 16, v48
	v_pk_add_f32 v[48:49], v[50:51], 1.0 op_sel_hi:[1,0] neg_lo:[1,0] neg_hi:[1,0]
	v_div_scale_f32 v50, s[62:63], v59, v59, 1.0
	v_rcp_f32_e32 v51, v50
	v_pk_mul_f32 v[52:53], v[52:53], v[72:73] op_sel_hi:[1,0]
	v_fma_f32 v58, -v50, v51, 1.0
	v_fmac_f32_e32 v51, v58, v51
	v_div_scale_f32 v58, vcc, 1.0, v59, 1.0
	v_mul_f32_e32 v63, v58, v51
	v_fma_f32 v67, -v50, v63, v58
	v_fmac_f32_e32 v63, v67, v51
	v_fma_f32 v50, -v50, v63, v58
	v_div_fmas_f32 v50, v50, v51, v63
	v_div_scale_f32 v51, s[62:63], v62, v62, 1.0
	v_rcp_f32_e32 v58, v51
	v_div_fixup_f32 v50, v50, v59, 1.0
	v_fma_f32 v59, -v51, v58, 1.0
	v_fmac_f32_e32 v58, v59, v58
	v_div_scale_f32 v59, vcc, 1.0, v62, 1.0
	v_mul_f32_e32 v63, v59, v58
	v_fma_f32 v67, -v51, v63, v59
	v_fmac_f32_e32 v63, v67, v58
	v_fma_f32 v51, -v51, v63, v59
	v_div_fmas_f32 v51, v51, v58, v63
	v_div_fixup_f32 v51, v51, v62, 1.0
	v_pk_mul_f32 v[48:49], v[48:49], v[50:51]
	s_nop 0
	v_bfe_u32 v50, v48, 16, 1
	v_bfe_u32 v51, v49, 16, 1
	v_add3_u32 v50, v48, v50, s57
	v_add3_u32 v51, v49, v51, s57
	v_and_or_b32 v50, v50, s58, v54
	v_and_or_b32 v51, v51, s58, v55
	ds_write2_b32 v84, v50, v51 offset0:80 offset1:148
	v_mul_f32_e32 v50, 0x3fb8aa3b, v106
	v_exp_f32_e32 v50, v50
	v_mul_f32_e32 v51, 0x3fb8aa3b, v107
	v_exp_f32_e32 v51, v51
	v_pk_mul_f32 v[48:49], v[48:49], v[66:67] op_sel_hi:[1,0]
	v_mul_f32_e32 v46, v46, v50
	v_bfe_u32 v54, v46, 16, 1
	v_mul_f32_e32 v47, v47, v51
	v_add3_u32 v46, v46, v54, s57
	v_bfe_u32 v54, v47, 16, 1
	v_lshrrev_b32_e32 v46, 16, v46
	v_add3_u32 v47, v47, v54, s57
	v_and_or_b32 v46, v47, s58, v46
	v_mul_f32_e32 v47, 0x3fb8aa3b, v108
	v_exp_f32_e32 v47, v47
	v_mul_f32_e32 v54, 0x3fb8aa3b, v109
	v_exp_f32_e32 v54, v54
	v_mul_f32_e32 v44, v44, v47
	v_bfe_u32 v55, v44, 16, 1
	v_mul_f32_e32 v45, v45, v54
	v_add3_u32 v44, v44, v55, s57
	v_bfe_u32 v55, v45, 16, 1
	v_lshrrev_b32_e32 v44, 16, v44
	v_add3_u32 v45, v45, v55, s57
	v_and_or_b32 v44, v45, s58, v44
	ds_write2_b32 v83, v46, v44 offset0:152 offset1:220
	v_mov_b32_e32 v44, v40
	v_div_scale_f32 v40, s[62:63], v50, v50, 1.0
	v_mov_b32_e32 v45, v42
	v_rcp_f32_e32 v42, v40
	v_pk_add_f32 v[44:45], v[44:45], 1.0 op_sel_hi:[1,0] neg_lo:[1,0] neg_hi:[1,0]
	v_fma_f32 v46, -v40, v42, 1.0
	v_fmac_f32_e32 v42, v46, v42
	v_div_scale_f32 v46, vcc, 1.0, v50, 1.0
	v_mul_f32_e32 v55, v46, v42
	v_fma_f32 v58, -v40, v55, v46
	v_fmac_f32_e32 v55, v58, v42
	v_fma_f32 v40, -v40, v55, v46
	v_div_fmas_f32 v40, v40, v42, v55
	v_div_fixup_f32 v46, v40, v50, 1.0
	v_div_scale_f32 v40, s[62:63], v47, v47, 1.0
	v_rcp_f32_e32 v42, v40
	s_nop 0
	v_fma_f32 v50, -v40, v42, 1.0
	v_fmac_f32_e32 v42, v50, v42
	v_div_scale_f32 v50, vcc, 1.0, v47, 1.0
	v_mul_f32_e32 v55, v50, v42
	v_fma_f32 v58, -v40, v55, v50
	v_fmac_f32_e32 v55, v58, v42
	v_fma_f32 v40, -v40, v55, v50
	v_div_fmas_f32 v40, v40, v42, v55
	v_div_fixup_f32 v47, v40, v47, 1.0
	v_pk_mul_f32 v[44:45], v[44:45], v[46:47]
	v_mov_b32_e32 v42, v41
	v_bfe_u32 v40, v44, 16, 1
	v_add3_u32 v40, v44, v40, s57
	v_lshrrev_b32_e32 v46, 16, v40
	v_bfe_u32 v40, v45, 16, 1
	v_add3_u32 v40, v45, v40, s57
	v_lshrrev_b32_e32 v47, 16, v40
	v_pk_add_f32 v[40:41], v[42:43], 1.0 op_sel_hi:[1,0] neg_lo:[1,0] neg_hi:[1,0]
	v_div_scale_f32 v42, s[62:63], v51, v51, 1.0
	v_rcp_f32_e32 v43, v42
	v_pk_mul_f32 v[44:45], v[44:45], v[72:73] op_sel_hi:[1,0]
	v_fma_f32 v50, -v42, v43, 1.0
	v_fmac_f32_e32 v43, v50, v43
	v_div_scale_f32 v50, vcc, 1.0, v51, 1.0
	v_mul_f32_e32 v55, v50, v43
	v_fma_f32 v58, -v42, v55, v50
	v_fmac_f32_e32 v55, v58, v43
	v_fma_f32 v42, -v42, v55, v50
	v_div_fmas_f32 v42, v42, v43, v55
	v_div_scale_f32 v43, s[62:63], v54, v54, 1.0
	v_rcp_f32_e32 v50, v43
	v_div_fixup_f32 v42, v42, v51, 1.0
	v_fma_f32 v51, -v43, v50, 1.0
	v_fmac_f32_e32 v50, v51, v50
	v_div_scale_f32 v51, vcc, 1.0, v54, 1.0
	v_mul_f32_e32 v55, v51, v50
	v_fma_f32 v58, -v43, v55, v51
	v_fmac_f32_e32 v55, v58, v50
	v_fma_f32 v43, -v43, v55, v51
	v_div_fmas_f32 v43, v43, v50, v55
	v_div_fixup_f32 v43, v43, v54, 1.0
	v_pk_mul_f32 v[40:41], v[40:41], v[42:43]
	s_nop 0
	v_bfe_u32 v42, v40, 16, 1
	v_bfe_u32 v43, v41, 16, 1
	v_add3_u32 v42, v40, v42, s57
	v_add3_u32 v43, v41, v43, s57
	v_and_or_b32 v42, v42, s58, v46
	v_and_or_b32 v43, v43, s58, v47
	ds_write2_b32 v85, v42, v43 offset0:88 offset1:156
	v_mul_f32_e32 v42, 0x3fb8aa3b, v102
	v_exp_f32_e32 v42, v42
	v_mul_f32_e32 v43, 0x3fb8aa3b, v103
	v_exp_f32_e32 v43, v43
	v_pk_mul_f32 v[40:41], v[40:41], v[66:67] op_sel_hi:[1,0]
	v_mul_f32_e32 v38, v38, v42
	v_bfe_u32 v46, v38, 16, 1
	v_mul_f32_e32 v39, v39, v43
	v_add3_u32 v38, v38, v46, s57
	v_bfe_u32 v46, v39, 16, 1
	v_lshrrev_b32_e32 v38, 16, v38
; __device__ __forceinline__ void hgrn_pre_phase(KP p, char* smem, int wv, const int seg, const int gw, const int nw) {
;     ...
;     for (int i = 0; i < 16; ++i) {
;       const float e0 = __expf(lb0[i]), e1 = __expf(lb1[i]);
;       const float k0 = (1.f - fv[i].x) * __frcp_rn(e0), k1 = (1.f - fv[i].y) * __frcp_rn(e1);
;       const unsigned qt = (unsigned)f2bf(qv[i].x * e0) | ((unsigned)f2bf(qv[i].y * e1) << 16);
;       const unsigned kt = (unsigned)f2bf(k0) | ((unsigned)f2bf(k1) << 16);
;       *(unsigned*)(wl + i * 136 + lane * 2) = qt;
;       *(unsigned*)(wl + 2176 + i * 136 + lane * 2) = kt;
;       kh0[i] = f2bf(k0 * ec0);
;       kh1[i] = f2bf(k1 * ec1);
;     }
	v_add3_u32 v39, v39, v46, s57
	v_and_or_b32 v38, v39, s58, v38
	v_mul_f32_e32 v39, 0x3fb8aa3b, v104
	v_exp_f32_e32 v39, v39
	v_mul_f32_e32 v46, 0x3fb8aa3b, v105
	v_exp_f32_e32 v46, v46
	v_mul_f32_e32 v36, v36, v39
	v_bfe_u32 v47, v36, 16, 1
	v_mul_f32_e32 v37, v37, v46
	v_add3_u32 v36, v36, v47, s57
	v_bfe_u32 v47, v37, 16, 1
	v_lshrrev_b32_e32 v36, 16, v36
	v_add3_u32 v37, v37, v47, s57
	v_and_or_b32 v36, v37, s58, v36
	ds_write2_b32 v86, v38, v36 offset0:32 offset1:100
	v_mov_b32_e32 v36, v32
	v_div_scale_f32 v32, s[62:63], v42, v42, 1.0
	v_mov_b32_e32 v37, v34
	v_rcp_f32_e32 v34, v32
	v_pk_add_f32 v[36:37], v[36:37], 1.0 op_sel_hi:[1,0] neg_lo:[1,0] neg_hi:[1,0]
	v_fma_f32 v38, -v32, v34, 1.0
	v_fmac_f32_e32 v34, v38, v34
	v_div_scale_f32 v38, vcc, 1.0, v42, 1.0
	v_mul_f32_e32 v47, v38, v34
	v_fma_f32 v50, -v32, v47, v38
	v_fmac_f32_e32 v47, v50, v34
	v_fma_f32 v32, -v32, v47, v38
	v_div_fmas_f32 v32, v32, v34, v47
	v_div_fixup_f32 v38, v32, v42, 1.0
	v_div_scale_f32 v32, s[62:63], v39, v39, 1.0
	v_rcp_f32_e32 v34, v32
	s_nop 0
	v_fma_f32 v42, -v32, v34, 1.0
	v_fmac_f32_e32 v34, v42, v34
	v_div_scale_f32 v42, vcc, 1.0, v39, 1.0
	v_mul_f32_e32 v47, v42, v34
	v_fma_f32 v50, -v32, v47, v42
	v_fmac_f32_e32 v47, v50, v34
	v_fma_f32 v32, -v32, v47, v42
	v_div_fmas_f32 v32, v32, v34, v47
	v_div_fixup_f32 v39, v32, v39, 1.0
	v_pk_mul_f32 v[36:37], v[36:37], v[38:39]
	v_mov_b32_e32 v34, v33
	v_bfe_u32 v32, v36, 16, 1
	v_add3_u32 v32, v36, v32, s57
	v_lshrrev_b32_e32 v38, 16, v32
	v_bfe_u32 v32, v37, 16, 1
	v_add3_u32 v32, v37, v32, s57
	v_lshrrev_b32_e32 v39, 16, v32
	v_pk_add_f32 v[32:33], v[34:35], 1.0 op_sel_hi:[1,0] neg_lo:[1,0] neg_hi:[1,0]
	v_div_scale_f32 v34, s[62:63], v43, v43, 1.0
	v_rcp_f32_e32 v35, v34
	v_pk_mul_f32 v[36:37], v[36:37], v[72:73] op_sel_hi:[1,0]
	v_fma_f32 v42, -v34, v35, 1.0
	v_fmac_f32_e32 v35, v42, v35
	v_div_scale_f32 v42, vcc, 1.0, v43, 1.0
	v_mul_f32_e32 v47, v42, v35
	v_fma_f32 v50, -v34, v47, v42
	v_fmac_f32_e32 v47, v50, v35
	v_fma_f32 v34, -v34, v47, v42
	v_div_fmas_f32 v34, v34, v35, v47
	v_div_scale_f32 v35, s[62:63], v46, v46, 1.0
	v_rcp_f32_e32 v42, v35
	v_div_fixup_f32 v34, v34, v43, 1.0
	v_fma_f32 v43, -v35, v42, 1.0
	v_fmac_f32_e32 v42, v43, v42
	v_div_scale_f32 v43, vcc, 1.0, v46, 1.0
	v_mul_f32_e32 v47, v43, v42
	v_fma_f32 v50, -v35, v47, v43
	v_fmac_f32_e32 v47, v50, v42
	v_fma_f32 v35, -v35, v47, v43
	v_div_fmas_f32 v35, v35, v42, v47
	v_div_fixup_f32 v35, v35, v46, 1.0
	v_pk_mul_f32 v[32:33], v[32:33], v[34:35]
	s_nop 0
	v_bfe_u32 v34, v32, 16, 1
	v_bfe_u32 v35, v33, 16, 1
	v_add3_u32 v34, v32, v34, s57
	v_add3_u32 v35, v33, v35, s57
	v_and_or_b32 v34, v34, s58, v38
	v_and_or_b32 v35, v35, s58, v39
	ds_write2_b32 v87, v34, v35 offset0:96 offset1:164
	v_mul_f32_e32 v34, 0x3fb8aa3b, v98
	v_exp_f32_e32 v34, v34
	v_mul_f32_e32 v35, 0x3fb8aa3b, v99
	v_exp_f32_e32 v35, v35
	v_pk_mul_f32 v[32:33], v[32:33], v[66:67] op_sel_hi:[1,0]
	v_mul_f32_e32 v30, v30, v34
	v_bfe_u32 v38, v30, 16, 1
	v_mul_f32_e32 v31, v31, v35
	v_add3_u32 v30, v30, v38, s57
	v_bfe_u32 v38, v31, 16, 1
	v_lshrrev_b32_e32 v30, 16, v30
	v_add3_u32 v31, v31, v38, s57
	v_and_or_b32 v30, v31, s58, v30
	v_mul_f32_e32 v31, 0x3fb8aa3b, v100
	v_exp_f32_e32 v31, v31
	v_mul_f32_e32 v38, 0x3fb8aa3b, v101
	v_exp_f32_e32 v38, v38
	v_mul_f32_e32 v28, v28, v31
	v_bfe_u32 v39, v28, 16, 1
	v_mul_f32_e32 v29, v29, v38
	v_add3_u32 v28, v28, v39, s57
	v_bfe_u32 v39, v29, 16, 1
	v_lshrrev_b32_e32 v28, 16, v28
	v_add3_u32 v29, v29, v39, s57
	v_and_or_b32 v28, v29, s58, v28
	ds_write2_b32 v86, v30, v28 offset0:168 offset1:236
	v_mov_b32_e32 v28, v24
	v_div_scale_f32 v24, s[62:63], v34, v34, 1.0
	v_mov_b32_e32 v29, v26
	v_rcp_f32_e32 v26, v24
	v_pk_add_f32 v[28:29], v[28:29], 1.0 op_sel_hi:[1,0] neg_lo:[1,0] neg_hi:[1,0]
	v_fma_f32 v30, -v24, v26, 1.0
	v_fmac_f32_e32 v26, v30, v26
	v_div_scale_f32 v30, vcc, 1.0, v34, 1.0
	v_mul_f32_e32 v39, v30, v26
	v_fma_f32 v42, -v24, v39, v30
	v_fmac_f32_e32 v39, v42, v26
	v_fma_f32 v24, -v24, v39, v30
	v_div_fmas_f32 v24, v24, v26, v39
	v_div_fixup_f32 v30, v24, v34, 1.0
	v_div_scale_f32 v24, s[62:63], v31, v31, 1.0
	v_rcp_f32_e32 v26, v24
	s_nop 0
	v_fma_f32 v34, -v24, v26, 1.0
	v_fmac_f32_e32 v26, v34, v26
	v_div_scale_f32 v34, vcc, 1.0, v31, 1.0
	v_mul_f32_e32 v39, v34, v26
	v_fma_f32 v42, -v24, v39, v34
	v_fmac_f32_e32 v39, v42, v26
	v_fma_f32 v24, -v24, v39, v34
	v_div_fmas_f32 v24, v24, v26, v39
	v_div_fixup_f32 v31, v24, v31, 1.0
	v_pk_mul_f32 v[28:29], v[28:29], v[30:31]
	v_mov_b32_e32 v26, v25
	v_bfe_u32 v24, v28, 16, 1
	v_add3_u32 v24, v28, v24, s57
	v_lshrrev_b32_e32 v30, 16, v24
	v_bfe_u32 v24, v29, 16, 1
	v_add3_u32 v24, v29, v24, s57
	v_lshrrev_b32_e32 v31, 16, v24
	v_pk_add_f32 v[24:25], v[26:27], 1.0 op_sel_hi:[1,0] neg_lo:[1,0] neg_hi:[1,0]
	v_div_scale_f32 v26, s[62:63], v35, v35, 1.0
	v_rcp_f32_e32 v27, v26
	v_pk_mul_f32 v[28:29], v[28:29], v[72:73] op_sel_hi:[1,0]
	v_fma_f32 v34, -v26, v27, 1.0
	v_fmac_f32_e32 v27, v34, v27
	v_div_scale_f32 v34, vcc, 1.0, v35, 1.0
	v_mul_f32_e32 v39, v34, v27
	v_fma_f32 v42, -v26, v39, v34
	v_fmac_f32_e32 v39, v42, v27
	v_fma_f32 v26, -v26, v39, v34
	v_div_fmas_f32 v26, v26, v27, v39
	v_div_scale_f32 v27, s[62:63], v38, v38, 1.0
	v_rcp_f32_e32 v34, v27
	v_div_fixup_f32 v26, v26, v35, 1.0
	v_fma_f32 v35, -v27, v34, 1.0
	v_fmac_f32_e32 v34, v35, v34
	v_div_scale_f32 v35, vcc, 1.0, v38, 1.0
	v_mul_f32_e32 v39, v35, v34
	v_fma_f32 v42, -v27, v39, v35
	v_fmac_f32_e32 v39, v42, v34
	v_fma_f32 v27, -v27, v39, v35
	v_div_fmas_f32 v27, v27, v34, v39
	v_div_fixup_f32 v27, v27, v38, 1.0
	v_pk_mul_f32 v[24:25], v[24:25], v[26:27]
	s_nop 0
	v_bfe_u32 v26, v24, 16, 1
; __device__ __forceinline__ void hgrn_pre_phase(KP p, char* smem, int wv, const int seg, const int gw, const int nw) {
;     ...
;     for (int i = 0; i < 16; ++i) {
;       const float e0 = __expf(lb0[i]), e1 = __expf(lb1[i]);
;       const float k0 = (1.f - fv[i].x) * __frcp_rn(e0), k1 = (1.f - fv[i].y) * __frcp_rn(e1);
;       const unsigned qt = (unsigned)f2bf(qv[i].x * e0) | ((unsigned)f2bf(qv[i].y * e1) << 16);
;       const unsigned kt = (unsigned)f2bf(k0) | ((unsigned)f2bf(k1) << 16);
;       *(unsigned*)(wl + i * 136 + lane * 2) = qt;
;       *(unsigned*)(wl + 2176 + i * 136 + lane * 2) = kt;
;       kh0[i] = f2bf(k0 * ec0);
;       kh1[i] = f2bf(k1 * ec1);
;     }
	v_bfe_u32 v27, v25, 16, 1
	v_add3_u32 v26, v24, v26, s57
	v_add3_u32 v27, v25, v27, s57
	v_and_or_b32 v26, v26, s58, v30
	v_and_or_b32 v27, v27, s58, v31
	ds_write2_b32 v88, v26, v27 offset0:104 offset1:172
	v_mul_f32_e32 v26, 0x3fb8aa3b, v94
	v_exp_f32_e32 v26, v26
	v_mul_f32_e32 v27, 0x3fb8aa3b, v95
	v_exp_f32_e32 v27, v27
	v_pk_mul_f32 v[24:25], v[24:25], v[66:67] op_sel_hi:[1,0]
	v_mul_f32_e32 v14, v14, v26
	v_bfe_u32 v30, v14, 16, 1
	v_mul_f32_e32 v15, v15, v27
	v_add3_u32 v14, v14, v30, s57
	v_bfe_u32 v30, v15, 16, 1
	v_lshrrev_b32_e32 v14, 16, v14
	v_add3_u32 v15, v15, v30, s57
	v_and_or_b32 v14, v15, s58, v14
	v_mul_f32_e32 v15, 0x3fb8aa3b, v96
	v_exp_f32_e32 v15, v15
	v_mul_f32_e32 v30, 0x3fb8aa3b, v97
	v_exp_f32_e32 v30, v30
	v_mul_f32_e32 v12, v12, v15
	v_bfe_u32 v31, v12, 16, 1
	v_mul_f32_e32 v13, v13, v30
	v_add3_u32 v12, v12, v31, s57
	v_bfe_u32 v31, v13, 16, 1
	v_lshrrev_b32_e32 v12, 16, v12
	v_add3_u32 v13, v13, v31, s57
	v_and_or_b32 v12, v13, s58, v12
	ds_write2_b32 v89, v14, v12 offset0:48 offset1:116
	v_mov_b32_e32 v12, v8
	v_div_scale_f32 v8, s[62:63], v26, v26, 1.0
	v_mov_b32_e32 v13, v10
	v_rcp_f32_e32 v10, v8
	v_pk_add_f32 v[12:13], v[12:13], 1.0 op_sel_hi:[1,0] neg_lo:[1,0] neg_hi:[1,0]
	v_fma_f32 v14, -v8, v10, 1.0
	v_fmac_f32_e32 v10, v14, v10
	v_div_scale_f32 v14, vcc, 1.0, v26, 1.0
	v_mul_f32_e32 v31, v14, v10
	v_fma_f32 v34, -v8, v31, v14
	v_fmac_f32_e32 v31, v34, v10
	v_fma_f32 v8, -v8, v31, v14
	v_div_fmas_f32 v8, v8, v10, v31
	v_div_fixup_f32 v14, v8, v26, 1.0
	v_div_scale_f32 v8, s[62:63], v15, v15, 1.0
	v_rcp_f32_e32 v10, v8
	s_nop 0
	v_fma_f32 v26, -v8, v10, 1.0
	v_fmac_f32_e32 v10, v26, v10
	v_div_scale_f32 v26, vcc, 1.0, v15, 1.0
	v_mul_f32_e32 v31, v26, v10
	v_fma_f32 v34, -v8, v31, v26
	v_fmac_f32_e32 v31, v34, v10
	v_fma_f32 v8, -v8, v31, v26
	v_div_fmas_f32 v8, v8, v10, v31
	v_div_fixup_f32 v15, v8, v15, 1.0
	v_pk_mul_f32 v[12:13], v[12:13], v[14:15]
	v_mov_b32_e32 v10, v9
	v_bfe_u32 v8, v12, 16, 1
	v_add3_u32 v8, v12, v8, s57
	v_lshrrev_b32_e32 v14, 16, v8
	v_bfe_u32 v8, v13, 16, 1
	v_add3_u32 v8, v13, v8, s57
	v_lshrrev_b32_e32 v15, 16, v8
	v_pk_add_f32 v[8:9], v[10:11], 1.0 op_sel_hi:[1,0] neg_lo:[1,0] neg_hi:[1,0]
	v_div_scale_f32 v10, s[62:63], v27, v27, 1.0
	v_rcp_f32_e32 v11, v10
	v_pk_mul_f32 v[12:13], v[12:13], v[72:73] op_sel_hi:[1,0]
	v_fma_f32 v26, -v10, v11, 1.0
	v_fmac_f32_e32 v11, v26, v11
	v_div_scale_f32 v26, vcc, 1.0, v27, 1.0
	v_mul_f32_e32 v31, v26, v11
	v_fma_f32 v34, -v10, v31, v26
	v_fmac_f32_e32 v31, v34, v11
	v_fma_f32 v10, -v10, v31, v26
	v_div_fmas_f32 v10, v10, v11, v31
	v_div_scale_f32 v11, s[62:63], v30, v30, 1.0
	v_rcp_f32_e32 v26, v11
	v_div_fixup_f32 v10, v10, v27, 1.0
	v_fma_f32 v27, -v11, v26, 1.0
	v_fmac_f32_e32 v26, v27, v26
	v_div_scale_f32 v27, vcc, 1.0, v30, 1.0
	v_mul_f32_e32 v31, v27, v26
	v_fma_f32 v34, -v11, v31, v27
	v_fmac_f32_e32 v31, v34, v26
	v_fma_f32 v11, -v11, v31, v27
	v_div_fmas_f32 v11, v11, v26, v31
	v_div_fixup_f32 v11, v11, v30, 1.0
	v_pk_mul_f32 v[8:9], v[8:9], v[10:11]
	s_nop 0
	v_bfe_u32 v10, v8, 16, 1
	v_bfe_u32 v11, v9, 16, 1
	v_add3_u32 v10, v8, v10, s57
	v_add3_u32 v11, v9, v11, s57
	v_and_or_b32 v10, v10, s58, v14
	v_and_or_b32 v11, v11, s58, v15
	v_pk_mul_f32 v[14:15], v[8:9], v[66:67] op_sel_hi:[1,0]
	v_mul_f32_e32 v8, 0x3fb8aa3b, v92
	v_exp_f32_e32 v8, v8
	v_mul_f32_e32 v9, 0x3fb8aa3b, v93
	v_exp_f32_e32 v9, v9
	ds_write2_b32 v90, v10, v11 offset0:112 offset1:180
	v_mul_f32_e32 v6, v6, v8
	v_bfe_u32 v10, v6, 16, 1
	v_mul_f32_e32 v7, v7, v9
	v_add3_u32 v6, v6, v10, s57
	v_bfe_u32 v10, v7, 16, 1
	v_lshrrev_b32_e32 v6, 16, v6
	v_add3_u32 v7, v7, v10, s57
	v_and_or_b32 v6, v7, s58, v6
	v_bfe_u32 v7, v4, 16, 1
	v_add3_u32 v4, v4, v7, s57
	v_bfe_u32 v7, v5, 16, 1
	v_lshrrev_b32_e32 v4, 16, v4
	v_add3_u32 v5, v5, v7, s57
	v_and_or_b32 v4, v5, s58, v4
	ds_write2_b32 v89, v6, v4 offset0:184 offset1:252
	v_mov_b32_e32 v4, v0
	v_div_scale_f32 v0, s[62:63], v8, v8, 1.0
	v_mov_b32_e32 v5, v2
	v_rcp_f32_e32 v2, v0
	v_pk_add_f32 v[4:5], v[4:5], 1.0 op_sel_hi:[1,0] neg_lo:[1,0] neg_hi:[1,0]
	v_fma_f32 v6, -v0, v2, 1.0
	v_fmac_f32_e32 v2, v6, v2
	v_div_scale_f32 v6, vcc, 1.0, v8, 1.0
	v_mul_f32_e32 v7, v6, v2
	v_fma_f32 v10, -v0, v7, v6
	v_fmac_f32_e32 v7, v10, v2
	v_fma_f32 v0, -v0, v7, v6
	v_div_fmas_f32 v0, v0, v2, v7
	v_div_fixup_f32 v6, v0, v8, 1.0
	v_div_scale_f32 v0, s[62:63], v72, v72, 1.0
	v_rcp_f32_e32 v2, v0
	s_nop 0
	v_fma_f32 v7, -v0, v2, 1.0
	v_fmac_f32_e32 v2, v7, v2
	v_div_scale_f32 v7, vcc, 1.0, v72, 1.0
	v_mul_f32_e32 v8, v7, v2
	v_fma_f32 v10, -v0, v8, v7
	v_fmac_f32_e32 v8, v10, v2
	v_fma_f32 v0, -v0, v8, v7
	v_div_fmas_f32 v0, v0, v2, v8
	v_div_fixup_f32 v7, v0, v72, 1.0
	v_pk_mul_f32 v[4:5], v[4:5], v[6:7]
	v_mov_b32_e32 v2, v1
	v_bfe_u32 v0, v4, 16, 1
	v_add3_u32 v0, v4, v0, s57
	v_lshrrev_b32_e32 v6, 16, v0
	v_bfe_u32 v0, v5, 16, 1
	v_add3_u32 v0, v5, v0, s57
	v_lshrrev_b32_e32 v7, 16, v0
	v_pk_add_f32 v[0:1], v[2:3], 1.0 op_sel_hi:[1,0] neg_lo:[1,0] neg_hi:[1,0]
	v_div_scale_f32 v2, s[62:63], v9, v9, 1.0
	v_rcp_f32_e32 v3, v2
	v_pk_mul_f32 v[4:5], v[4:5], v[72:73] op_sel_hi:[1,0]
	v_fma_f32 v8, -v2, v3, 1.0
	v_fmac_f32_e32 v3, v8, v3
	v_div_scale_f32 v8, vcc, 1.0, v9, 1.0
	v_mul_f32_e32 v10, v8, v3
	v_fma_f32 v11, -v2, v10, v8
; __device__ __forceinline__ void hgrn_pre_phase(KP p, char* smem, int wv, const int seg, const int gw, const int nw) {
;     ...
;     {
;       const int ch0 = lane * 2, ch1 = ch0 + 1;
;       bf16x8 a, bq, cc, dd;
; #pragma unroll
;       for (int j = 0; j < 8; ++j) { a[j] = (short)kh0[j]; bq[j] = (short)kh0[8 + j]; cc[j] = (short)kh1[j]; dd[j] = (short)kh1[8 + j]; }
;       char* kb = tb + 4096;
;       *(bf16x8*)(kb + (((ch0 >> 4) * 32) + (ch0 & 15)) * 16) = a;
;       *(bf16x8*)(kb + (((ch0 >> 4) * 32) + 16 + (ch0 & 15)) * 16) = bq;
;       *(bf16x8*)(kb + (((ch1 >> 4) * 32) + (ch1 & 15)) * 16) = cc;
;       *(bf16x8*)(kb + (((ch1 >> 4) * 32) + 16 + (ch1 & 15)) * 16) = dd;
;     }
;     f32x4 acc = {0.f, 0.f, 0.f, 0.f};
; #pragma unroll
;     for (int sidx = 0; sidx < 4; ++sidx) {
;       const bf16x8 af = *(const bf16x8*)(wl + fr * 136 + sidx * 32 + fq * 8);
;       const bf16x8 bfm = *(const bf16x8*)(wl + 2176 + fr * 136 + sidx * 32 + fq * 8);
;       *(bf16x8*)(tb + (sidx * 64 + lane) * 16) = af;
;       acc = __builtin_amdgcn_mfma_f32_16x16x32_bf16(af, bfm, acc, 0, 0, 0);
;     }
;     unsigned short* at = (unsigned short*)(tb + 8192);
; #pragma unroll
;     for (int r = 0; r < 4; ++r) {
;       const int i = 4 * fq + r, j = fr;
;       at[((j >> 3) * 16 + i) * 8 + (j & 7)] = (j <= i) ? f2bf(acc[r]) : (unsigned short)0;
;     }
	v_fmac_f32_e32 v10, v11, v3
	v_fma_f32 v2, -v2, v10, v8
	v_div_fmas_f32 v2, v2, v3, v10
	v_div_scale_f32 v3, s[62:63], v73, v73, 1.0
	v_rcp_f32_e32 v8, v3
	v_div_fixup_f32 v2, v2, v9, 1.0
	v_bfe_u32 v30, v5, 16, 1
	v_bfe_u32 v31, v4, 16, 1
	v_fma_f32 v9, -v3, v8, 1.0
	v_fmac_f32_e32 v8, v9, v8
	v_div_scale_f32 v9, vcc, 1.0, v73, 1.0
	v_mul_f32_e32 v10, v9, v8
	v_fma_f32 v11, -v3, v10, v9
	v_fmac_f32_e32 v10, v11, v8
	v_fma_f32 v3, -v3, v10, v9
	v_div_fmas_f32 v3, v3, v8, v10
	v_div_fixup_f32 v3, v3, v73, 1.0
	v_pk_mul_f32 v[0:1], v[0:1], v[2:3]
	v_bfe_u32 v8, v69, 16, 1
	v_bfe_u32 v2, v0, 16, 1
	v_bfe_u32 v3, v1, 16, 1
	v_add3_u32 v2, v0, v2, s57
	v_add3_u32 v3, v1, v3, s57
	v_and_or_b32 v2, v2, s58, v6
	v_and_or_b32 v3, v3, s58, v7
	ds_write2_b32 v91, v2, v3 offset0:120 offset1:188
	v_pk_mul_f32 v[26:27], v[0:1], v[66:67] op_sel_hi:[1,0]
	v_bfe_u32 v0, v61, 16, 1
	v_bfe_u32 v1, v60, 16, 1
	v_bfe_u32 v2, v53, 16, 1
	v_bfe_u32 v3, v52, 16, 1
	v_bfe_u32 v6, v45, 16, 1
	v_bfe_u32 v7, v44, 16, 1
	v_bfe_u32 v9, v68, 16, 1
	v_add3_u32 v7, v44, v7, s57
	v_add3_u32 v6, v45, v6, s57
	v_add3_u32 v3, v52, v3, s57
	v_add3_u32 v2, v53, v2, s57
	v_add3_u32 v1, v60, v1, s57
	v_add3_u32 v0, v61, v0, s57
	v_add3_u32 v9, v68, v9, s57
	v_add3_u32 v8, v69, v8, s57
	v_perm_b32 v1, v0, v1, s59
	v_perm_b32 v2, v2, v3, s59
	v_perm_b32 v3, v6, v7, s59
	v_perm_b32 v0, v8, v9, s59
	v_bfe_u32 v6, v37, 16, 1
	v_bfe_u32 v7, v36, 16, 1
	v_bfe_u32 v8, v29, 16, 1
	v_bfe_u32 v9, v28, 16, 1
	v_bfe_u32 v10, v13, 16, 1
	v_bfe_u32 v11, v12, 16, 1
	v_add3_u32 v31, v4, v31, s57
	v_add3_u32 v30, v5, v30, s57
	v_add3_u32 v11, v12, v11, s57
	v_add3_u32 v10, v13, v10, s57
	v_add3_u32 v5, v28, v9, s57
	v_add3_u32 v8, v29, v8, s57
	v_add3_u32 v4, v36, v7, s57
	v_add3_u32 v6, v37, v6, s57
	v_perm_b32 v4, v6, v4, s59
	v_perm_b32 v5, v8, v5, s59
	v_perm_b32 v6, v10, v11, s59
	v_bfe_u32 v8, v57, 16, 1
	v_bfe_u32 v9, v56, 16, 1
	v_bfe_u32 v10, v49, 16, 1
	v_bfe_u32 v11, v48, 16, 1
	v_bfe_u32 v12, v41, 16, 1
	v_bfe_u32 v13, v40, 16, 1
	v_bfe_u32 v28, v65, 16, 1
	v_bfe_u32 v29, v64, 16, 1
	v_add3_u32 v13, v40, v13, s57
	v_add3_u32 v12, v41, v12, s57
	v_add3_u32 v11, v48, v11, s57
	v_add3_u32 v10, v49, v10, s57
	v_add3_u32 v9, v56, v9, s57
	v_add3_u32 v8, v57, v8, s57
	v_add3_u32 v29, v64, v29, s57
	v_add3_u32 v28, v65, v28, s57
	v_perm_b32 v9, v8, v9, s59
	v_perm_b32 v10, v10, v11, s59
	v_perm_b32 v11, v12, v13, s59
	v_perm_b32 v8, v28, v29, s59
	v_bfe_u32 v12, v33, 16, 1
	v_bfe_u32 v13, v32, 16, 1
	v_bfe_u32 v28, v25, 16, 1
	v_bfe_u32 v29, v24, 16, 1
	v_perm_b32 v7, v30, v31, s59
	v_bfe_u32 v30, v15, 16, 1
	v_bfe_u32 v31, v14, 16, 1
	v_bfe_u32 v34, v27, 16, 1
	v_bfe_u32 v35, v26, 16, 1
	v_add3_u32 v24, v24, v29, s57
	v_add3_u32 v25, v25, v28, s57
	v_add3_u32 v13, v32, v13, s57
	v_add3_u32 v12, v33, v12, s57
	v_add3_u32 v26, v26, v35, s57
	v_add3_u32 v27, v27, v34, s57
	v_add3_u32 v14, v14, v31, s57
	v_add3_u32 v15, v15, v30, s57
	v_perm_b32 v12, v12, v13, s59
	v_perm_b32 v13, v25, v24, s59
	v_lshl_add_u64 v[24:25], s[12:13], 0, v[18:19]
	v_perm_b32 v14, v15, v14, s59
	v_perm_b32 v15, v27, v26, s59
	v_lshl_add_u64 v[26:27], v[24:25], 0, s[16:17]
	v_add_co_u32_e32 v24, vcc, s60, v24
	s_nop 1
	v_addc_co_u32_e32 v25, vcc, 0, v25, vcc
	global_store_dwordx4 v[24:25], v[0:3], off
	global_store_dwordx4 v[26:27], v[4:7], off offset:256
	global_store_dwordx4 v[26:27], v[8:11], off offset:16
	global_store_dwordx4 v[26:27], v[12:15], off offset:272
	ds_read_b128 v[0:3], v75
	ds_read_b128 v[4:7], v75 offset:4352
	v_lshl_add_u64 v[12:13], s[12:13], 0, v[20:21]
	s_add_u32 s12, s12, 0x2000
	s_addc_u32 s13, s13, 0
	s_waitcnt lgkmcnt(1)
	global_store_dwordx4 v[12:13], v[0:3], off
	s_add_i32 s61, s61, s66
	s_cmpk_lt_i32 s61, 0x800
	s_waitcnt lgkmcnt(0)
	v_mfma_f32_16x16x32_bf16 v[0:3], v[0:3], v[4:7], 0
	ds_read_b128 v[4:7], v75 offset:64
	ds_read_b128 v[8:11], v75 offset:4416
	s_waitcnt lgkmcnt(1)
	global_store_dwordx4 v[12:13], v[4:7], off offset:1024
	s_waitcnt lgkmcnt(0)
	v_mfma_f32_16x16x32_bf16 v[0:3], v[4:7], v[8:11], v[0:3]
	ds_read_b128 v[4:7], v75 offset:128
	ds_read_b128 v[8:11], v75 offset:4480
	s_waitcnt lgkmcnt(1)
	global_store_dwordx4 v[12:13], v[4:7], off offset:2048
	s_waitcnt lgkmcnt(0)
	v_mfma_f32_16x16x32_bf16 v[0:3], v[4:7], v[8:11], v[0:3]
	ds_read_b128 v[4:7], v75 offset:192
	ds_read_b128 v[8:11], v75 offset:4544
	s_waitcnt lgkmcnt(1)
	global_store_dwordx4 v[12:13], v[4:7], off offset:3072
	s_waitcnt lgkmcnt(0)
	v_mfma_f32_16x16x32_bf16 v[0:3], v[4:7], v[8:11], v[0:3]
	s_nop 7
	v_bfe_u32 v4, v0, 16, 1
	v_add3_u32 v0, v0, v4, s57
	v_lshrrev_b32_e32 v0, 16, v0
	v_cndmask_b32_e64 v0, v0, 0, s[10:11]
	global_store_short v77, v0, s[12:13]
	v_bfe_u32 v0, v1, 16, 1
	v_add3_u32 v0, v1, v0, s57
	v_lshrrev_b32_e32 v0, 16, v0
	v_cndmask_b32_e64 v0, v0, 0, s[4:5]
	global_store_short v78, v0, s[12:13]
	v_bfe_u32 v0, v2, 16, 1
	v_add3_u32 v0, v2, v0, s57
	v_lshrrev_b32_e32 v0, 16, v0
	v_cndmask_b32_e64 v0, v0, 0, s[6:7]
	global_store_short v79, v0, s[12:13]
	v_bfe_u32 v0, v3, 16, 1
	v_add3_u32 v0, v3, v0, s57
	v_lshrrev_b32_e32 v0, 16, v0
	v_cndmask_b32_e64 v0, v0, 0, s[8:9]
	global_store_short v80, v0, s[12:13]
	s_cbranch_scc1 .LBB0_777
	v_readlane_b32 s36, v253, 14
	s_mov_b32 s37, s66

; __device__ __forceinline__ void side_load(const SideJob& jb, float4 (&v)[8], const int lane) {
;   const int r8 = lane >> 3, c4 = (lane & 7) * 4;
; #pragma unroll
;   for (int i = 0; i < 8; ++i) v[i] = *(const float4*)(jb.W + (long)(jb.k0 + i * 8 + r8) * jb.N + jb.n0 + c4);
; }
; __device__ __forceinline__ void side_transpose(KP p, char* smem, int bid, int nb, int wv, const int part) {
;     ...
;   SideJob cur = side_job(p, j);
;   float4 va[8], vb[8];
;   side_load(cur, va, lane);
;   for (;;) {
;     const int jn = j + stride;
;     const bool more = jn < tot;
;     SideJob nxt = cur;
;     if (more) { nxt = side_job(p, jn); side_load(nxt, vb, lane); }
.Ld1_BB0_890:
	s_load_dwordx2 s[10:11], s[10:11], 0x0
	v_bfe_u32 v68, v10, 3, 3
	v_lshlrev_b32_e32 v0, 2, v10
	v_or_b32_e32 v69, 8, v68
	v_or_b32_e32 v70, 16, v68
	v_and_b32_e32 v12, 28, v0
	v_add_u32_e32 v0, s4, v68
	v_add_u32_e32 v4, s4, v69
	v_add_u32_e32 v11, s4, v70
	v_or_b32_e32 v71, 24, v68
	v_mad_i64_i32 v[2:3], s[12:13], s8, v0, 0
	v_mad_i64_i32 v[4:5], s[16:17], s8, v4, 0
	v_mad_i64_i32 v[14:15], s[16:17], s8, v11, 0
	v_add_u32_e32 v11, s4, v71
	s_waitcnt lgkmcnt(0)
	v_lshl_add_u64 v[2:3], v[2:3], 2, s[10:11]
	s_lshl_b64 s[12:13], s[42:43], 2
	v_lshl_add_u64 v[4:5], v[4:5], 2, s[10:11]
	v_lshl_add_u64 v[14:15], v[14:15], 2, s[10:11]
	v_mad_i64_i32 v[16:17], s[16:17], s8, v11, 0
	v_lshl_add_u64 v[2:3], v[2:3], 0, s[12:13]
	v_lshlrev_b32_e32 v0, 2, v12
	v_lshl_add_u64 v[4:5], v[4:5], 0, s[12:13]
	v_lshl_add_u64 v[14:15], v[14:15], 0, s[12:13]
	v_lshl_add_u64 v[16:17], v[16:17], 2, s[10:11]
	v_or_b32_e32 v72, 32, v68
	v_lshl_add_u64 v[2:3], v[2:3], 0, v[0:1]
	v_lshl_add_u64 v[6:7], v[4:5], 0, v[0:1]
	v_lshl_add_u64 v[14:15], v[14:15], 0, v[0:1]
	v_lshl_add_u64 v[16:17], v[16:17], 0, s[12:13]
	v_add_u32_e32 v11, s4, v72
	v_or_b32_e32 v73, 40, v68
	global_load_dwordx4 v[2:5], v[2:3], off nt
	s_nop 0
	global_load_dwordx4 v[6:9], v[6:7], off nt
	v_lshl_add_u64 v[16:17], v[16:17], 0, v[0:1]
	global_load_dwordx4 v[18:21], v[14:15], off nt
	global_load_dwordx4 v[22:25], v[16:17], off nt
	v_mad_i64_i32 v[14:15], s[16:17], s8, v11, 0
	v_add_u32_e32 v11, s4, v73
	v_lshl_add_u64 v[14:15], v[14:15], 2, s[10:11]
	v_mad_i64_i32 v[16:17], s[16:17], s8, v11, 0
	v_lshl_add_u64 v[14:15], v[14:15], 0, s[12:13]
	v_lshl_add_u64 v[16:17], v[16:17], 2, s[10:11]
	v_or_b32_e32 v74, 48, v68
	v_lshl_add_u64 v[14:15], v[14:15], 0, v[0:1]
	v_lshl_add_u64 v[16:17], v[16:17], 0, s[12:13]
	v_add_u32_e32 v11, s4, v74
	v_or_b32_e32 v75, 56, v68
	v_lshl_add_u64 v[16:17], v[16:17], 0, v[0:1]
	global_load_dwordx4 v[26:29], v[14:15], off nt
	global_load_dwordx4 v[34:37], v[16:17], off nt
	v_mad_i64_i32 v[14:15], s[16:17], s8, v11, 0
	v_add_u32_e32 v11, s4, v75
	v_lshl_add_u64 v[14:15], v[14:15], 2, s[10:11]
	v_mad_i64_i32 v[16:17], s[8:9], s8, v11, 0
	v_lshl_add_u64 v[14:15], v[14:15], 0, s[12:13]
	v_lshl_add_u64 v[16:17], v[16:17], 2, s[10:11]
	v_lshl_add_u64 v[14:15], v[14:15], 0, v[0:1]
	v_lshl_add_u64 v[16:17], v[16:17], 0, s[12:13]
	v_lshl_add_u64 v[16:17], v[16:17], 0, v[0:1]
	global_load_dwordx4 v[42:45], v[14:15], off nt
	global_load_dwordx4 v[46:49], v[16:17], off nt
	s_add_u32 s8, s14, 0x58
	s_addc_u32 s9, s15, 0
	s_load_dwordx2 s[6:7], s[6:7], 0x0
	s_add_u32 s10, s14, 0x98
	s_addc_u32 s11, s15, 0
	s_add_u32 s12, s14, 0x48
	v_and_b32_e32 v0, 7, v10
	v_readlane_b32 s5, v253, 13
	s_addc_u32 s13, s15, 0
	v_mul_u32_u24_e32 v13, 0x84, v68
	v_lshl_add_u32 v11, v0, 4, s5
	v_lshlrev_b32_e32 v10, 3, v0
	v_mul_u32_u24_e32 v0, 0x420, v0
	v_lshlrev_b32_e32 v14, 2, v68
	s_add_u32 s14, s14, 0x90
	v_add3_u32 v76, s5, v0, v14
	s_addc_u32 s15, s15, 0
	v_lshlrev_b32_e32 v0, 2, v12
	v_add_u32_e32 v77, v11, v13
	v_lshlrev_b32_e32 v66, 1, v10
	v_readlane_b32 s28, v253, 29
	s_mov_b32 s29, s42
	s_waitcnt lgkmcnt(0)
	s_mov_b64 s[18:19], s[6:7]
	s_branch .Ld1_BB0_893
.Ld1_BB0_891:
	s_load_dwordx2 s[22:23], s[22:23], 0x0
	v_add_u32_e32 v10, s30, v68
	v_add_u32_e32 v12, s30, v69
	v_add_u32_e32 v30, s30, v70
	v_add_u32_e32 v32, s30, v71
	v_add_u32_e32 v50, s30, v72
	v_add_u32_e32 v52, s30, v73
	v_add_u32_e32 v58, s30, v74
	v_add_u32_e32 v60, s30, v75
	v_mad_i64_i32 v[10:11], s[36:37], s20, v10, 0
	v_mad_i64_i32 v[12:13], s[36:37], s20, v12, 0
	v_mad_i64_i32 v[30:31], s[36:37], s20, v30, 0
	v_mad_i64_i32 v[32:33], s[36:37], s20, v32, 0
	v_mad_i64_i32 v[50:51], s[36:37], s20, v50, 0
	v_mad_i64_i32 v[52:53], s[36:37], s20, v52, 0
	v_mad_i64_i32 v[58:59], s[36:37], s20, v58, 0
	v_mad_i64_i32 v[60:61], s[20:21], s20, v60, 0
	s_lshl_b64 s[24:25], s[42:43], 2
	s_waitcnt lgkmcnt(0)
	v_lshl_add_u64 v[10:11], v[10:11], 2, s[22:23]
	v_lshl_add_u64 v[12:13], v[12:13], 2, s[22:23]
	v_lshl_add_u64 v[30:31], v[30:31], 2, s[22:23]
	v_lshl_add_u64 v[32:33], v[32:33], 2, s[22:23]
	v_lshl_add_u64 v[50:51], v[50:51], 2, s[22:23]
	v_lshl_add_u64 v[52:53], v[52:53], 2, s[22:23]
	v_lshl_add_u64 v[58:59], v[58:59], 2, s[22:23]
	v_lshl_add_u64 v[60:61], v[60:61], 2, s[22:23]
	v_lshl_add_u64 v[10:11], v[10:11], 0, s[24:25]
	v_lshl_add_u64 v[12:13], v[12:13], 0, s[24:25]
	v_lshl_add_u64 v[30:31], v[30:31], 0, s[24:25]
	v_lshl_add_u64 v[32:33], v[32:33], 0, s[24:25]
	v_lshl_add_u64 v[50:51], v[50:51], 0, s[24:25]
	v_lshl_add_u64 v[52:53], v[52:53], 0, s[24:25]
	v_lshl_add_u64 v[58:59], v[58:59], 0, s[24:25]
	v_lshl_add_u64 v[60:61], v[60:61], 0, s[24:25]
	v_lshl_add_u64 v[10:11], v[10:11], 0, v[0:1]
	v_lshl_add_u64 v[14:15], v[12:13], 0, v[0:1]
	v_lshl_add_u64 v[30:31], v[30:31], 0, v[0:1]
	v_lshl_add_u64 v[38:39], v[32:33], 0, v[0:1]
	v_lshl_add_u64 v[50:51], v[50:51], 0, v[0:1]
	v_lshl_add_u64 v[54:55], v[52:53], 0, v[0:1]
	v_lshl_add_u64 v[58:59], v[58:59], 0, v[0:1]
	v_lshl_add_u64 v[62:63], v[60:61], 0, v[0:1]
	global_load_dwordx4 v[10:13], v[10:11], off nt
	s_nop 0
	global_load_dwordx4 v[14:17], v[14:15], off nt
	s_nop 0
	global_load_dwordx4 v[30:33], v[30:31], off nt
	s_nop 0
	global_load_dwordx4 v[38:41], v[38:39], off nt
	s_nop 0
	global_load_dwordx4 v[50:53], v[50:51], off nt
	s_nop 0
	global_load_dwordx4 v[54:57], v[54:55], off nt
	s_nop 0
	global_load_dwordx4 v[58:61], v[58:59], off nt
	s_nop 0
	global_load_dwordx4 v[62:65], v[62:63], off nt
	s_load_dwordx2 s[18:19], s[18:19], 0x0
	v_readlane_b32 s36, v253, 14
	v_readlane_b32 s37, v253, 15
	s_waitcnt vmcnt(8)
	s_branch .Ld1_st_body_a

; __device__ __forceinline__ void side_store(const SideJob& jb, const float4 (&v)[8], float* tile, const int lane) {
;   const int r8 = lane >> 3, c4 = (lane & 7) * 4;
; #pragma unroll
;   for (int i = 0; i < 8; ++i) {
;     float* d = tile + (i * 8 + r8) * 33 + c4;
;     d[0] = v[i].x; d[1] = v[i].y; d[2] = v[i].z; d[3] = v[i].w;
;   }
;   const int kk = lane & 7, nl = lane >> 3;
; #pragma unroll
;   for (int i = 0; i < 4; ++i) {
;     const int n = i * 8 + nl;
;     bf16x8 o;
; #pragma unroll
;     for (int j = 0; j < 8; ++j) o[j] = (short)f2bf(tile[(kk * 8 + j) * 33 + n]);
;     *(bf16x8*)(jb.Wt + (long)(jb.n0 + n) * jb.K + jb.k0 + kk * 8) = o;
;   }
; }
; __device__ __forceinline__ void side_transpose(KP p, char* smem, int bid, int nb, int wv, const int part) {
;     ...
;     side_store(cur, va, tile, lane);
;     if (!more) break;
; #pragma unroll
;     for (int i = 0; i < 8; ++i) va[i] = vb[i];
;     cur = nxt; j = jn;
;   }
.Ld1_st_body_a:
	ds_write2_b32 v77, v2, v3 offset1:1
	ds_write2_b32 v77, v4, v5 offset0:2 offset1:3
	v_add_u32_e32 v2, 0x420, v77
	ds_write2_b32 v2, v6, v7 offset1:1
	v_add_u32_e32 v2, 0x428, v77
	ds_write2_b32 v2, v8, v9 offset1:1
	v_add_u32_e32 v2, 0x840, v77
	ds_write2_b32 v2, v18, v19 offset1:1
	v_add_u32_e32 v2, 0x848, v77
	ds_write2_b32 v2, v20, v21 offset1:1
	v_add_u32_e32 v2, 0xc60, v77
	ds_write2_b32 v2, v22, v23 offset1:1
	v_add_u32_e32 v2, 0xc68, v77
	ds_write2_b32 v2, v24, v25 offset1:1
	v_add_u32_e32 v2, 0x1080, v77
	ds_write2_b32 v2, v26, v27 offset1:1
	v_add_u32_e32 v2, 0x1088, v77
	ds_write2_b32 v2, v28, v29 offset1:1
	v_add_u32_e32 v2, 0x14a0, v77
	ds_write2_b32 v2, v34, v35 offset1:1
	v_add_u32_e32 v2, 0x14a8, v77
	ds_write2_b32 v2, v36, v37 offset1:1
	v_add_u32_e32 v2, 0x18c0, v77
	ds_write2_b32 v2, v42, v43 offset1:1
	v_add_u32_e32 v2, 0x18c8, v77
	ds_write2_b32 v2, v44, v45 offset1:1
	v_add_u32_e32 v2, 0x1ce0, v77
	ds_write2_b32 v2, v46, v47 offset1:1
	v_add_u32_e32 v2, 0x1ce8, v77
	ds_write2_b32 v2, v48, v49 offset1:1
	ds_read2_b32 v[6:7], v76 offset0:33 offset1:41
	ds_read2_b32 v[8:9], v76 offset0:66 offset1:74
	ds_read2_b32 v[18:19], v76 offset0:231 offset1:239
	ds_read2_b32 v[20:21], v76 offset0:198 offset1:206
	ds_read2_b32 v[22:23], v76 offset0:165 offset1:173
	ds_read2_b32 v[24:25], v76 offset0:99 offset1:107
	ds_read2_b32 v[26:27], v76 offset0:132 offset1:140
	ds_read2_b32 v[28:29], v76 offset1:8
	s_waitcnt lgkmcnt(0)
	v_bfe_u32 v35, v8, 16, 1
	v_add3_u32 v8, v8, v35, s97
	v_bfe_u32 v34, v24, 16, 1
	v_add3_u32 v24, v24, v34, s97
	v_add_u32_e32 v34, s29, v68
	v_mov_b32_e32 v35, v1
	v_lshlrev_b64 v[34:35], 13, v[34:35]
	s_ashr_i32 s5, s4, 31
	v_bfe_u32 v2, v18, 16, 1
	v_bfe_u32 v3, v20, 16, 1
	v_bfe_u32 v4, v22, 16, 1
	v_bfe_u32 v5, v26, 16, 1
	v_bfe_u32 v36, v6, 16, 1
	v_bfe_u32 v37, v28, 16, 1
	v_lshl_add_u64 v[34:35], s[6:7], 0, v[34:35]
	s_lshl_b64 s[4:5], s[4:5], 1
	v_add3_u32 v28, v28, v37, s97
	v_add3_u32 v6, v6, v36, s97
	v_add3_u32 v26, v26, v5, s97
	v_add3_u32 v4, v22, v4, s97
	v_add3_u32 v3, v20, v3, s97
	v_add3_u32 v2, v18, v2, s97
	v_lshl_add_u64 v[34:35], v[34:35], 0, s[4:5]
	v_mov_b32_e32 v67, v1
	v_perm_b32 v5, v2, v3, s49
	v_perm_b32 v4, v4, v26, s49
	v_perm_b32 v3, v24, v8, s49
	v_perm_b32 v2, v6, v28, s49
	v_lshl_add_u64 v[34:35], v[34:35], 0, v[66:67]
	global_store_dwordx4 v[34:35], v[2:5], off nt
	v_bfe_u32 v6, v25, 16, 1
	v_bfe_u32 v8, v9, 16, 1
	v_bfe_u32 v2, v19, 16, 1
	v_bfe_u32 v3, v21, 16, 1
	v_bfe_u32 v18, v7, 16, 1
	v_bfe_u32 v20, v29, 16, 1
	v_bfe_u32 v5, v27, 16, 1
	v_add3_u32 v20, v29, v20, s97
	v_add3_u32 v7, v7, v18, s97
	v_add3_u32 v8, v9, v8, s97
	v_add3_u32 v6, v25, v6, s97
	v_add3_u32 v3, v21, v3, s97
	v_add3_u32 v2, v19, v2, s97
	v_add3_u32 v9, v27, v5, s97
	v_perm_b32 v5, v2, v3, s49
	v_perm_b32 v3, v6, v8, s49
	v_perm_b32 v2, v7, v20, s49
	v_add_u32_e32 v6, s29, v69
	v_mov_b32_e32 v7, v1
	v_lshlrev_b64 v[6:7], 13, v[6:7]
	v_bfe_u32 v4, v23, 16, 1
	v_lshl_add_u64 v[6:7], s[6:7], 0, v[6:7]
	v_add3_u32 v4, v23, v4, s97
	v_lshl_add_u64 v[6:7], v[6:7], 0, s[4:5]
	v_perm_b32 v4, v4, v9, s49
	v_lshl_add_u64 v[6:7], v[6:7], 0, v[66:67]
	global_store_dwordx4 v[6:7], v[2:5], off nt
	ds_read2_b32 v[6:7], v76 offset0:16 offset1:24
	ds_read2_b32 v[8:9], v76 offset0:49 offset1:57
	ds_read2_b32 v[18:19], v76 offset0:82 offset1:90
	ds_read2_b32 v[20:21], v76 offset0:247 offset1:255
	ds_read2_b32 v[22:23], v76 offset0:214 offset1:222
	ds_read2_b32 v[24:25], v76 offset0:181 offset1:189
	ds_read2_b32 v[26:27], v76 offset0:148 offset1:156
	ds_read2_b32 v[28:29], v76 offset0:115 offset1:123
	s_waitcnt lgkmcnt(5)
	v_bfe_u32 v35, v18, 16, 1
	v_add3_u32 v18, v18, v35, s97
	v_mov_b32_e32 v35, v1
	s_waitcnt lgkmcnt(4)
	v_bfe_u32 v2, v20, 16, 1
	s_waitcnt lgkmcnt(0)
	v_bfe_u32 v34, v28, 16, 1
	v_add3_u32 v28, v28, v34, s97
	v_add_u32_e32 v34, s29, v70
	v_lshlrev_b64 v[34:35], 13, v[34:35]
	v_bfe_u32 v3, v22, 16, 1
	v_bfe_u32 v4, v24, 16, 1
	v_bfe_u32 v5, v26, 16, 1
	v_bfe_u32 v36, v8, 16, 1
	v_bfe_u32 v37, v6, 16, 1
	v_lshl_add_u64 v[34:35], s[6:7], 0, v[34:35]
	v_add3_u32 v6, v6, v37, s97
	v_add3_u32 v8, v8, v36, s97
	v_add3_u32 v26, v26, v5, s97
	v_add3_u32 v4, v24, v4, s97
	v_add3_u32 v3, v22, v3, s97
	v_add3_u32 v2, v20, v2, s97
	v_lshl_add_u64 v[34:35], v[34:35], 0, s[4:5]
	v_perm_b32 v5, v2, v3, s49
	v_perm_b32 v4, v4, v26, s49
	v_perm_b32 v3, v28, v18, s49
	v_perm_b32 v2, v8, v6, s49
	v_lshl_add_u64 v[34:35], v[34:35], 0, v[66:67]
	global_store_dwordx4 v[34:35], v[2:5], off nt
	v_bfe_u32 v6, v29, 16, 1
	v_bfe_u32 v8, v19, 16, 1
	v_bfe_u32 v2, v21, 16, 1
	v_bfe_u32 v3, v23, 16, 1
	v_bfe_u32 v18, v9, 16, 1
	v_bfe_u32 v20, v7, 16, 1
	v_bfe_u32 v5, v27, 16, 1
	v_add3_u32 v7, v7, v20, s97
	v_add3_u32 v9, v9, v18, s97
	v_add3_u32 v8, v19, v8, s97
	v_add3_u32 v6, v29, v6, s97
	v_add3_u32 v3, v23, v3, s97
	v_add3_u32 v2, v21, v2, s97
	v_add3_u32 v18, v27, v5, s97
	v_perm_b32 v5, v2, v3, s49
	v_perm_b32 v3, v6, v8, s49
	v_perm_b32 v2, v9, v7, s49
	v_add_u32_e32 v6, s29, v71
	v_mov_b32_e32 v7, v1
	v_lshlrev_b64 v[6:7], 13, v[6:7]
	v_bfe_u32 v4, v25, 16, 1
	v_lshl_add_u64 v[6:7], s[6:7], 0, v[6:7]
	v_add3_u32 v4, v25, v4, s97
	v_lshl_add_u64 v[6:7], v[6:7], 0, s[4:5]
	v_perm_b32 v4, v4, v18, s49
	v_lshl_add_u64 v[6:7], v[6:7], 0, v[66:67]
	v_readlane_b32 s4, v253, 30
	global_store_dwordx4 v[6:7], v[2:5], off nt
	s_add_i32 s28, s28, s4
	s_andn2_b64 vcc, exec, s[16:17]
	s_mov_b32 s29, s42
	s_mov_b32 s4, s30
	s_mov_b64 s[6:7], s[18:19]
	s_waitcnt vmcnt(4)
	v_mov_b64_e32 v[2:3], v[10:11]
	v_mov_b64_e32 v[4:5], v[12:13]
	v_mov_b64_e32 v[6:7], v[14:15]
	v_mov_b64_e32 v[8:9], v[16:17]
	v_mov_b64_e32 v[18:19], v[30:31]
	v_mov_b64_e32 v[20:21], v[32:33]
	v_mov_b64_e32 v[22:23], v[38:39]
	v_mov_b64_e32 v[24:25], v[40:41]
	v_mov_b64_e32 v[26:27], v[50:51]
	v_mov_b64_e32 v[28:29], v[52:53]
	v_mov_b64_e32 v[34:35], v[54:55]
	v_mov_b64_e32 v[36:37], v[56:57]
	v_mov_b64_e32 v[42:43], v[58:59]
	v_mov_b64_e32 v[44:45], v[60:61]
	v_mov_b64_e32 v[46:47], v[62:63]
	v_mov_b64_e32 v[48:49], v[64:65]
	s_cbranch_vccz .Ld1_done

; __device__ __forceinline__ void hgrn_pre_phase(KP p, char* smem, int wv, const int seg, const int gw, const int nw) {
;     ...
;   for (int idx = gw; idx < 2048; idx += nw) {
;     const int bh = idx >> 6, c = seg * 64 + (idx & 63), task = bh * 256 + c, b = bh >> 4, h = bh & 15;
;     const long r0 = (long)b * SEQ + c * 16;
;     const float* qsrc = p->proj + r0 * PW + h * 128 + lane * 2;
;     float2 qv[16], fv[16];
; #pragma unroll
;     for (int i = 0; i < 16; ++i) { qv[i] = *(const float2*)(qsrc + (long)i * PW); fv[i] = *(const float2*)(qsrc + 2048 + (long)i * PW); }
.LBB0_850:
	s_and_b32 s12, s20, 63
	s_or_b32 s21, s12, s19
	s_ashr_i32 s12, s20, 10
	s_ashr_i32 s23, s20, 6
	s_ashr_i32 s13, s12, 31
	s_lshl_b32 s22, s23, 8
	s_lshl_b64 s[12:13], s[12:13], 12
	s_lshl_b32 s24, s21, 4
	s_add_u32 s12, s12, s24
	s_addc_u32 s13, s13, 0
	s_mul_i32 s13, s13, 0xe080
	s_mul_hi_u32 s24, s12, 0xe080
	s_add_i32 s24, s24, s13
	s_mul_i32 s12, s12, 0xe080
	s_waitcnt lgkmcnt(0)
	s_add_u32 s12, s16, s12
	s_addc_u32 s13, s17, s24
	s_lshl_b32 s23, s23, 9
	s_and_b32 s23, s23, 0x1e00
	s_add_u32 s12, s12, s23
	s_addc_u32 s13, s13, 0
	v_lshl_add_u64 v[4:5], s[12:13], 0, v[22:23]
	v_add_co_u32_e32 v2, vcc, s54, v4
	global_load_dwordx2 v[70:71], v22, s[12:13]
	s_nop 0
	v_addc_co_u32_e32 v3, vcc, 0, v5, vcc
	global_load_dwordx2 v[64:65], v[2:3], off nt
	v_add_co_u32_e32 v2, vcc, s55, v4
	s_nop 1
	v_addc_co_u32_e32 v3, vcc, 0, v5, vcc
	global_load_dwordx2 v[68:69], v[2:3], off offset:128 nt
	v_add_co_u32_e32 v2, vcc, s1, v4
	s_nop 1
	v_addc_co_u32_e32 v3, vcc, 0, v5, vcc
	global_load_dwordx2 v[66:67], v[2:3], off offset:128 nt
	v_add_co_u32_e32 v2, vcc, s2, v4
	s_nop 1
	v_addc_co_u32_e32 v3, vcc, 0, v5, vcc
	global_load_dwordx2 v[62:63], v[2:3], off offset:256 nt
	v_add_co_u32_e32 v2, vcc, s3, v4
	s_nop 1
	v_addc_co_u32_e32 v3, vcc, 0, v5, vcc
	global_load_dwordx2 v[56:57], v[2:3], off offset:256 nt
	v_add_co_u32_e32 v2, vcc, s34, v4
	s_nop 1
	v_addc_co_u32_e32 v3, vcc, 0, v5, vcc
	global_load_dwordx2 v[60:61], v[2:3], off offset:384 nt
	v_add_co_u32_e32 v2, vcc, s35, v4
	s_nop 1
	v_addc_co_u32_e32 v3, vcc, 0, v5, vcc
	global_load_dwordx2 v[58:59], v[2:3], off offset:384 nt
	v_add_co_u32_e32 v2, vcc, s29, v4
	s_nop 1
	v_addc_co_u32_e32 v3, vcc, 0, v5, vcc
	global_load_dwordx2 v[54:55], v[2:3], off offset:512 nt
	v_add_co_u32_e32 v2, vcc, s40, v4
	s_nop 1
	v_addc_co_u32_e32 v3, vcc, 0, v5, vcc
	global_load_dwordx2 v[48:49], v[2:3], off offset:512 nt
	v_add_co_u32_e32 v2, vcc, s42, v4
	s_nop 1
	v_addc_co_u32_e32 v3, vcc, 0, v5, vcc
	global_load_dwordx2 v[52:53], v[2:3], off offset:640 nt
	v_add_co_u32_e32 v2, vcc, s44, v4
	s_nop 1
	v_addc_co_u32_e32 v3, vcc, 0, v5, vcc
	global_load_dwordx2 v[50:51], v[2:3], off offset:640 nt
	v_add_co_u32_e32 v2, vcc, s45, v4
	s_nop 1
	v_addc_co_u32_e32 v3, vcc, 0, v5, vcc
	global_load_dwordx2 v[46:47], v[2:3], off offset:768 nt
	v_add_co_u32_e32 v2, vcc, s50, v4
	s_nop 1
	v_addc_co_u32_e32 v3, vcc, 0, v5, vcc
	global_load_dwordx2 v[40:41], v[2:3], off offset:768 nt
	v_add_co_u32_e32 v2, vcc, s51, v4
	s_nop 1
	v_addc_co_u32_e32 v3, vcc, 0, v5, vcc
	global_load_dwordx2 v[44:45], v[2:3], off offset:896 nt
	v_add_co_u32_e32 v2, vcc, s52, v4
	s_nop 1
	v_addc_co_u32_e32 v3, vcc, 0, v5, vcc
	global_load_dwordx2 v[42:43], v[2:3], off offset:896 nt
	v_add_co_u32_e32 v2, vcc, s82, v4
	s_nop 1
	v_addc_co_u32_e32 v3, vcc, 0, v5, vcc
	global_load_dwordx2 v[38:39], v[2:3], off offset:1024 nt
	v_add_co_u32_e32 v2, vcc, s83, v4
	s_nop 1
	v_addc_co_u32_e32 v3, vcc, 0, v5, vcc
	global_load_dwordx2 v[32:33], v[2:3], off offset:1024 nt
	v_add_co_u32_e32 v2, vcc, s88, v4
	s_nop 1
	v_addc_co_u32_e32 v3, vcc, 0, v5, vcc
	global_load_dwordx2 v[36:37], v[2:3], off offset:1152 nt
	v_add_co_u32_e32 v2, vcc, s89, v4
	s_nop 1
	v_addc_co_u32_e32 v3, vcc, 0, v5, vcc
	global_load_dwordx2 v[34:35], v[2:3], off offset:1152 nt
	v_add_co_u32_e32 v2, vcc, s90, v4
	s_nop 1
	v_addc_co_u32_e32 v3, vcc, 0, v5, vcc
	global_load_dwordx2 v[30:31], v[2:3], off offset:1280 nt
	v_add_co_u32_e32 v2, vcc, s91, v4
	s_nop 1
	v_addc_co_u32_e32 v3, vcc, 0, v5, vcc
	global_load_dwordx2 v[24:25], v[2:3], off offset:1280 nt
	v_add_co_u32_e32 v2, vcc, s92, v4
	s_nop 1
	v_addc_co_u32_e32 v3, vcc, 0, v5, vcc
	global_load_dwordx2 v[28:29], v[2:3], off offset:1408 nt
	v_add_co_u32_e32 v2, vcc, s93, v4
	s_nop 1
	v_addc_co_u32_e32 v3, vcc, 0, v5, vcc
	global_load_dwordx2 v[26:27], v[2:3], off offset:1408 nt
	v_add_co_u32_e32 v2, vcc, s94, v4
	s_nop 1
	v_addc_co_u32_e32 v3, vcc, 0, v5, vcc
	global_load_dwordx2 v[16:17], v[2:3], off offset:1536 nt
	v_add_co_u32_e32 v2, vcc, s95, v4
	s_nop 1
	v_addc_co_u32_e32 v3, vcc, 0, v5, vcc
	global_load_dwordx2 v[10:11], v[2:3], off offset:1536 nt
	v_add_co_u32_e32 v2, vcc, s18, v4
	s_nop 1
	v_addc_co_u32_e32 v3, vcc, 0, v5, vcc
	global_load_dwordx2 v[14:15], v[2:3], off offset:1664 nt
	v_add_co_u32_e32 v2, vcc, s86, v4
	s_nop 1
	v_addc_co_u32_e32 v3, vcc, 0, v5, vcc
	global_load_dwordx2 v[12:13], v[2:3], off offset:1664 nt
	v_add_co_u32_e32 v2, vcc, s87, v4
	s_nop 1
	v_addc_co_u32_e32 v3, vcc, 0, v5, vcc
	global_load_dwordx2 v[8:9], v[2:3], off offset:1792 nt
	v_add_co_u32_e32 v2, vcc, s25, v4
	s_nop 1
	v_addc_co_u32_e32 v3, vcc, 0, v5, vcc
	v_add_co_u32_e32 v6, vcc, s26, v4
	global_load_dwordx2 v[2:3], v[2:3], off offset:1792 nt
	s_nop 0
	v_addc_co_u32_e32 v7, vcc, 0, v5, vcc
	v_add_co_u32_e32 v4, vcc, s27, v4
	global_load_dwordx2 v[6:7], v[6:7], off offset:1920 nt
	s_nop 0
	v_addc_co_u32_e32 v5, vcc, 0, v5, vcc
	s_waitcnt vmcnt(0)
; __device__ __forceinline__ void hgrn_pre_phase(KP p, char* smem, int wv, const int seg, const int gw, const int nw) {
;     ...
;     for (int i = 0; i < 16; ++i) { qv[i] = *(const float2*)(qsrc + (long)i * PW); fv[i] = *(const float2*)(qsrc + 2048 + (long)i * PW); }
;     float lb0[16], lb1[16];
;     float c0 = 0.f, c1 = 0.f;
; #pragma unroll
;     for (int i = 0; i < 16; ++i) { c0 += __logf(fv[i].x); c1 += __logf(fv[i].y); lb0[i] = c0; lb1[i] = c1; }
	v_cmp_gt_f32_e32 vcc, s38, v64
	global_load_dwordx2 v[4:5], v[4:5], off offset:1920 nt
	s_nop 0
	v_cndmask_b32_e64 v72, 0, 32, vcc
	v_ldexp_f32 v72, v64, v72
	v_log_f32_e32 v72, v72
	s_nop 0
	v_mul_f32_e32 v73, 0x3f317217, v72
	v_fma_f32 v73, v72, s39, -v73
	v_fmac_f32_e32 v73, 0x3377d1cf, v72
	v_fmac_f32_e32 v73, 0x3f317217, v72
	v_cmp_lt_f32_e64 s[12:13], |v72|, s96
	s_nop 1
	v_cndmask_b32_e64 v72, v72, v73, s[12:13]
	v_cndmask_b32_e32 v73, 0, v99, vcc
	v_sub_f32_e32 v72, v72, v73
	v_cmp_gt_f32_e32 vcc, s38, v65
	v_add_f32_e32 v125, 0, v72
	s_nop 0
	v_cndmask_b32_e64 v72, 0, 32, vcc
	v_ldexp_f32 v72, v65, v72
	v_log_f32_e32 v72, v72
	s_nop 0
	v_mul_f32_e32 v73, 0x3f317217, v72
	v_fma_f32 v73, v72, s39, -v73
	v_fmac_f32_e32 v73, 0x3377d1cf, v72
	v_fmac_f32_e32 v73, 0x3f317217, v72
	v_cmp_lt_f32_e64 s[12:13], |v72|, s96
	s_nop 1
	v_cndmask_b32_e64 v72, v72, v73, s[12:13]
	v_cndmask_b32_e32 v73, 0, v99, vcc
	v_sub_f32_e32 v72, v72, v73
	v_cmp_gt_f32_e32 vcc, s38, v66
	v_add_f32_e32 v126, 0, v72
	s_nop 0
	v_cndmask_b32_e64 v72, 0, 32, vcc
	v_ldexp_f32 v72, v66, v72
	v_log_f32_e32 v72, v72
	s_nop 0
	v_mul_f32_e32 v73, 0x3f317217, v72
	v_fma_f32 v73, v72, s39, -v73
	v_fmac_f32_e32 v73, 0x3377d1cf, v72
	v_fmac_f32_e32 v73, 0x3f317217, v72
	v_cmp_lt_f32_e64 s[12:13], |v72|, s96
	s_nop 1
	v_cndmask_b32_e64 v72, v72, v73, s[12:13]
	v_cndmask_b32_e32 v73, 0, v99, vcc
	v_sub_f32_e32 v72, v72, v73
	v_cmp_gt_f32_e32 vcc, s38, v67
	v_add_f32_e32 v127, v125, v72
	v_mul_f32_e32 v125, 0x3fb8aa3b, v125
	v_cndmask_b32_e64 v72, 0, 32, vcc
	v_ldexp_f32 v72, v67, v72
	v_log_f32_e32 v72, v72
	v_exp_f32_e32 v125, v125
	v_mul_f32_e32 v73, 0x3f317217, v72
	v_fma_f32 v73, v72, s39, -v73
	v_fmac_f32_e32 v73, 0x3377d1cf, v72
	v_fmac_f32_e32 v73, 0x3f317217, v72
	v_cmp_lt_f32_e64 s[12:13], |v72|, s96
	v_mul_f32_e32 v70, v70, v125
	s_nop 0
	v_cndmask_b32_e64 v72, v72, v73, s[12:13]
	v_cndmask_b32_e32 v73, 0, v99, vcc
	v_sub_f32_e32 v72, v72, v73
	v_cmp_gt_f32_e32 vcc, s38, v56
	v_add_f32_e32 v128, v126, v72
	v_mul_f32_e32 v126, 0x3fb8aa3b, v126
	v_cndmask_b32_e64 v72, 0, 32, vcc
	v_ldexp_f32 v72, v56, v72
	v_log_f32_e32 v72, v72
	v_exp_f32_e32 v126, v126
	v_mul_f32_e32 v73, 0x3f317217, v72
	v_fma_f32 v73, v72, s39, -v73
	v_fmac_f32_e32 v73, 0x3377d1cf, v72
	v_fmac_f32_e32 v73, 0x3f317217, v72
	v_cmp_lt_f32_e64 s[12:13], |v72|, s96
	v_mul_f32_e32 v71, v71, v126
	s_nop 0
	v_cndmask_b32_e64 v72, v72, v73, s[12:13]
	v_cndmask_b32_e32 v73, 0, v99, vcc
	v_sub_f32_e32 v72, v72, v73
	v_cmp_gt_f32_e32 vcc, s38, v57
	v_add_f32_e32 v121, v127, v72
	s_nop 0
	v_cndmask_b32_e64 v72, 0, 32, vcc
	v_ldexp_f32 v72, v57, v72
	v_log_f32_e32 v72, v72
	s_nop 0
	v_mul_f32_e32 v73, 0x3f317217, v72
	v_fma_f32 v73, v72, s39, -v73
	v_fmac_f32_e32 v73, 0x3377d1cf, v72
	v_fmac_f32_e32 v73, 0x3f317217, v72
	v_cmp_lt_f32_e64 s[12:13], |v72|, s96
	s_nop 1
	v_cndmask_b32_e64 v72, v72, v73, s[12:13]
	v_cndmask_b32_e32 v73, 0, v99, vcc
	v_sub_f32_e32 v72, v72, v73
	v_cmp_gt_f32_e32 vcc, s38, v58
	v_add_f32_e32 v122, v128, v72
	s_nop 0
	v_cndmask_b32_e64 v72, 0, 32, vcc
	v_ldexp_f32 v72, v58, v72
	v_log_f32_e32 v72, v72
	s_nop 0
	v_mul_f32_e32 v73, 0x3f317217, v72
	v_fma_f32 v73, v72, s39, -v73
	v_fmac_f32_e32 v73, 0x3377d1cf, v72
	v_fmac_f32_e32 v73, 0x3f317217, v72
	v_cmp_lt_f32_e64 s[12:13], |v72|, s96
	s_nop 1
	v_cndmask_b32_e64 v72, v72, v73, s[12:13]
	v_cndmask_b32_e32 v73, 0, v99, vcc
	v_sub_f32_e32 v72, v72, v73
	v_cmp_gt_f32_e32 vcc, s38, v59
	v_add_f32_e32 v123, v121, v72
	s_nop 0
	v_cndmask_b32_e64 v72, 0, 32, vcc
	v_ldexp_f32 v72, v59, v72
	v_log_f32_e32 v72, v72
	s_nop 0
	v_mul_f32_e32 v73, 0x3f317217, v72
	v_fma_f32 v73, v72, s39, -v73
	v_fmac_f32_e32 v73, 0x3377d1cf, v72
	v_fmac_f32_e32 v73, 0x3f317217, v72
	v_cmp_lt_f32_e64 s[12:13], |v72|, s96
	s_nop 1
	v_cndmask_b32_e64 v72, v72, v73, s[12:13]
	v_cndmask_b32_e32 v73, 0, v99, vcc
	v_sub_f32_e32 v72, v72, v73
	v_cmp_gt_f32_e32 vcc, s38, v48
	v_add_f32_e32 v124, v122, v72
	s_nop 0
	v_cndmask_b32_e64 v72, 0, 32, vcc
	v_ldexp_f32 v72, v48, v72
	v_log_f32_e32 v72, v72
	s_nop 0
	v_mul_f32_e32 v73, 0x3f317217, v72
	v_fma_f32 v73, v72, s39, -v73
	v_fmac_f32_e32 v73, 0x3377d1cf, v72
	v_fmac_f32_e32 v73, 0x3f317217, v72
	v_cmp_lt_f32_e64 s[12:13], |v72|, s96
	s_nop 1
	v_cndmask_b32_e64 v72, v72, v73, s[12:13]
	v_cndmask_b32_e32 v73, 0, v99, vcc
	v_sub_f32_e32 v72, v72, v73
	v_cmp_gt_f32_e32 vcc, s38, v49
	v_add_f32_e32 v117, v123, v72
	s_nop 0
	v_cndmask_b32_e64 v72, 0, 32, vcc
	v_ldexp_f32 v72, v49, v72
	v_log_f32_e32 v72, v72
	s_nop 0
	v_mul_f32_e32 v73, 0x3f317217, v72
	v_fma_f32 v73, v72, s39, -v73
	v_fmac_f32_e32 v73, 0x3377d1cf, v72
	v_fmac_f32_e32 v73, 0x3f317217, v72
	v_cmp_lt_f32_e64 s[12:13], |v72|, s96
	s_nop 1
	v_cndmask_b32_e64 v72, v72, v73, s[12:13]
	v_cndmask_b32_e32 v73, 0, v99, vcc
	v_sub_f32_e32 v72, v72, v73
	v_cmp_gt_f32_e32 vcc, s38, v50
	v_add_f32_e32 v118, v124, v72
	s_nop 0
	v_cndmask_b32_e64 v72, 0, 32, vcc
	v_ldexp_f32 v72, v50, v72
	v_log_f32_e32 v72, v72
	s_nop 0
	v_mul_f32_e32 v73, 0x3f317217, v72
	v_fma_f32 v73, v72, s39, -v73
	v_fmac_f32_e32 v73, 0x3377d1cf, v72
	v_fmac_f32_e32 v73, 0x3f317217, v72
	v_cmp_lt_f32_e64 s[12:13], |v72|, s96
	s_nop 1
	v_cndmask_b32_e64 v72, v72, v73, s[12:13]
	v_cndmask_b32_e32 v73, 0, v99, vcc
	v_sub_f32_e32 v72, v72, v73
	v_cmp_gt_f32_e32 vcc, s38, v51
	v_add_f32_e32 v119, v117, v72
	s_nop 0
	v_cndmask_b32_e64 v72, 0, 32, vcc
	v_ldexp_f32 v72, v51, v72
	v_log_f32_e32 v72, v72
	s_nop 0
	v_mul_f32_e32 v73, 0x3f317217, v72
	v_fma_f32 v73, v72, s39, -v73
	v_fmac_f32_e32 v73, 0x3377d1cf, v72
	v_fmac_f32_e32 v73, 0x3f317217, v72
	v_cmp_lt_f32_e64 s[12:13], |v72|, s96
	s_nop 1
; __device__ __forceinline__ void hgrn_pre_phase(KP p, char* smem, int wv, const int seg, const int gw, const int nw) {
;     ...
;     for (int i = 0; i < 16; ++i) { c0 += __logf(fv[i].x); c1 += __logf(fv[i].y); lb0[i] = c0; lb1[i] = c1; }
	v_cndmask_b32_e64 v72, v72, v73, s[12:13]
	v_cndmask_b32_e32 v73, 0, v99, vcc
	v_sub_f32_e32 v72, v72, v73
	v_cmp_gt_f32_e32 vcc, s38, v40
	v_add_f32_e32 v120, v118, v72
	s_nop 0
	v_cndmask_b32_e64 v72, 0, 32, vcc
	v_ldexp_f32 v72, v40, v72
	v_log_f32_e32 v72, v72
	s_nop 0
	v_mul_f32_e32 v73, 0x3f317217, v72
	v_fma_f32 v73, v72, s39, -v73
	v_fmac_f32_e32 v73, 0x3377d1cf, v72
	v_fmac_f32_e32 v73, 0x3f317217, v72
	v_cmp_lt_f32_e64 s[12:13], |v72|, s96
	s_nop 1
	v_cndmask_b32_e64 v72, v72, v73, s[12:13]
	v_cndmask_b32_e32 v73, 0, v99, vcc
	v_sub_f32_e32 v72, v72, v73
	v_cmp_gt_f32_e32 vcc, s38, v41
	v_add_f32_e32 v113, v119, v72
	s_nop 0
	v_cndmask_b32_e64 v72, 0, 32, vcc
	v_ldexp_f32 v72, v41, v72
	v_log_f32_e32 v72, v72
	s_nop 0
	v_mul_f32_e32 v73, 0x3f317217, v72
	v_fma_f32 v73, v72, s39, -v73
	v_fmac_f32_e32 v73, 0x3377d1cf, v72
	v_fmac_f32_e32 v73, 0x3f317217, v72
	v_cmp_lt_f32_e64 s[12:13], |v72|, s96
	s_nop 1
	v_cndmask_b32_e64 v72, v72, v73, s[12:13]
	v_cndmask_b32_e32 v73, 0, v99, vcc
	v_sub_f32_e32 v72, v72, v73
	v_cmp_gt_f32_e32 vcc, s38, v42
	v_add_f32_e32 v114, v120, v72
	s_nop 0
	v_cndmask_b32_e64 v72, 0, 32, vcc
	v_ldexp_f32 v72, v42, v72
	v_log_f32_e32 v72, v72
	s_nop 0
	v_mul_f32_e32 v73, 0x3f317217, v72
	v_fma_f32 v73, v72, s39, -v73
	v_fmac_f32_e32 v73, 0x3377d1cf, v72
	v_fmac_f32_e32 v73, 0x3f317217, v72
	v_cmp_lt_f32_e64 s[12:13], |v72|, s96
	s_nop 1
	v_cndmask_b32_e64 v72, v72, v73, s[12:13]
	v_cndmask_b32_e32 v73, 0, v99, vcc
	v_sub_f32_e32 v72, v72, v73
	v_cmp_gt_f32_e32 vcc, s38, v43
	v_add_f32_e32 v115, v113, v72
	s_nop 0
	v_cndmask_b32_e64 v72, 0, 32, vcc
	v_ldexp_f32 v72, v43, v72
	v_log_f32_e32 v72, v72
	s_nop 0
	v_mul_f32_e32 v73, 0x3f317217, v72
	v_fma_f32 v73, v72, s39, -v73
	v_fmac_f32_e32 v73, 0x3377d1cf, v72
	v_fmac_f32_e32 v73, 0x3f317217, v72
	v_cmp_lt_f32_e64 s[12:13], |v72|, s96
	s_nop 1
	v_cndmask_b32_e64 v72, v72, v73, s[12:13]
	v_cndmask_b32_e32 v73, 0, v99, vcc
	v_sub_f32_e32 v72, v72, v73
	v_cmp_gt_f32_e32 vcc, s38, v32
	v_add_f32_e32 v116, v114, v72
	s_nop 0
	v_cndmask_b32_e64 v72, 0, 32, vcc
	v_ldexp_f32 v72, v32, v72
	v_log_f32_e32 v72, v72
	s_nop 0
	v_mul_f32_e32 v73, 0x3f317217, v72
	v_fma_f32 v73, v72, s39, -v73
	v_fmac_f32_e32 v73, 0x3377d1cf, v72
	v_fmac_f32_e32 v73, 0x3f317217, v72
	v_cmp_lt_f32_e64 s[12:13], |v72|, s96
	s_nop 1
	v_cndmask_b32_e64 v72, v72, v73, s[12:13]
	v_cndmask_b32_e32 v73, 0, v99, vcc
	v_sub_f32_e32 v72, v72, v73
	v_cmp_gt_f32_e32 vcc, s38, v33
	v_add_f32_e32 v104, v115, v72
	s_nop 0
	v_cndmask_b32_e64 v72, 0, 32, vcc
	v_ldexp_f32 v72, v33, v72
	v_log_f32_e32 v72, v72
	s_nop 0
	v_mul_f32_e32 v73, 0x3f317217, v72
	v_fma_f32 v73, v72, s39, -v73
	v_fmac_f32_e32 v73, 0x3377d1cf, v72
	v_fmac_f32_e32 v73, 0x3f317217, v72
	v_cmp_lt_f32_e64 s[12:13], |v72|, s96
	s_nop 1
	v_cndmask_b32_e64 v72, v72, v73, s[12:13]
	v_cndmask_b32_e32 v73, 0, v99, vcc
	v_sub_f32_e32 v72, v72, v73
	v_cmp_gt_f32_e32 vcc, s38, v34
	v_add_f32_e32 v106, v116, v72
	s_nop 0
	v_cndmask_b32_e64 v72, 0, 32, vcc
	v_ldexp_f32 v72, v34, v72
	v_log_f32_e32 v72, v72
	s_nop 0
	v_mul_f32_e32 v73, 0x3f317217, v72
	v_fma_f32 v73, v72, s39, -v73
	v_fmac_f32_e32 v73, 0x3377d1cf, v72
	v_fmac_f32_e32 v73, 0x3f317217, v72
	v_cmp_lt_f32_e64 s[12:13], |v72|, s96
	s_nop 1
	v_cndmask_b32_e64 v72, v72, v73, s[12:13]
	v_cndmask_b32_e32 v73, 0, v99, vcc
	v_sub_f32_e32 v72, v72, v73
	v_cmp_gt_f32_e32 vcc, s38, v35
	v_add_f32_e32 v107, v104, v72
	s_nop 0
	v_cndmask_b32_e64 v72, 0, 32, vcc
	v_ldexp_f32 v72, v35, v72
	v_log_f32_e32 v72, v72
	s_nop 0
	v_mul_f32_e32 v73, 0x3f317217, v72
	v_fma_f32 v73, v72, s39, -v73
	v_fmac_f32_e32 v73, 0x3377d1cf, v72
	v_fmac_f32_e32 v73, 0x3f317217, v72
	v_cmp_lt_f32_e64 s[12:13], |v72|, s96
	s_nop 1
	v_cndmask_b32_e64 v72, v72, v73, s[12:13]
	v_cndmask_b32_e32 v73, 0, v99, vcc
	v_sub_f32_e32 v72, v72, v73
	v_cmp_gt_f32_e32 vcc, s38, v24
	v_add_f32_e32 v112, v106, v72
	s_nop 0
	v_cndmask_b32_e64 v72, 0, 32, vcc
	v_ldexp_f32 v72, v24, v72
	v_log_f32_e32 v72, v72
	s_nop 0
	v_mul_f32_e32 v73, 0x3f317217, v72
	v_fma_f32 v73, v72, s39, -v73
	v_fmac_f32_e32 v73, 0x3377d1cf, v72
	v_fmac_f32_e32 v73, 0x3f317217, v72
	v_cmp_lt_f32_e64 s[12:13], |v72|, s96
	s_nop 1
	v_cndmask_b32_e64 v72, v72, v73, s[12:13]
	v_cndmask_b32_e32 v73, 0, v99, vcc
	v_sub_f32_e32 v72, v72, v73
	v_cmp_gt_f32_e32 vcc, s38, v25
	v_add_f32_e32 v97, v107, v72
	s_nop 0
	v_cndmask_b32_e64 v72, 0, 32, vcc
	v_ldexp_f32 v72, v25, v72
	v_log_f32_e32 v72, v72
	s_nop 0
	v_mul_f32_e32 v73, 0x3f317217, v72
	v_fma_f32 v73, v72, s39, -v73
	v_fmac_f32_e32 v73, 0x3377d1cf, v72
	v_fmac_f32_e32 v73, 0x3f317217, v72
	v_cmp_lt_f32_e64 s[12:13], |v72|, s96
	s_nop 1
	v_cndmask_b32_e64 v72, v72, v73, s[12:13]
	v_cndmask_b32_e32 v73, 0, v99, vcc
	v_sub_f32_e32 v72, v72, v73
	v_cmp_gt_f32_e32 vcc, s38, v26
	v_add_f32_e32 v98, v112, v72
	s_nop 0
	v_cndmask_b32_e64 v72, 0, 32, vcc
	v_ldexp_f32 v72, v26, v72
	v_log_f32_e32 v72, v72
	s_nop 0
	v_mul_f32_e32 v73, 0x3f317217, v72
	v_fma_f32 v73, v72, s39, -v73
	v_fmac_f32_e32 v73, 0x3377d1cf, v72
	v_fmac_f32_e32 v73, 0x3f317217, v72
	v_cmp_lt_f32_e64 s[12:13], |v72|, s96
	s_nop 1
	v_cndmask_b32_e64 v72, v72, v73, s[12:13]
	v_cndmask_b32_e32 v73, 0, v99, vcc
	v_sub_f32_e32 v72, v72, v73
	v_cmp_gt_f32_e32 vcc, s38, v27
	v_add_f32_e32 v100, v97, v72
	s_nop 0
	v_cndmask_b32_e64 v72, 0, 32, vcc
	v_ldexp_f32 v72, v27, v72
	v_log_f32_e32 v72, v72
	s_nop 0
	v_mul_f32_e32 v73, 0x3f317217, v72
	v_fma_f32 v73, v72, s39, -v73
	v_fmac_f32_e32 v73, 0x3377d1cf, v72
	v_fmac_f32_e32 v73, 0x3f317217, v72
	v_cmp_lt_f32_e64 s[12:13], |v72|, s96
	s_nop 1
	v_cndmask_b32_e64 v72, v72, v73, s[12:13]
	v_cndmask_b32_e32 v73, 0, v99, vcc
; __device__ __forceinline__ void hgrn_pre_phase(KP p, char* smem, int wv, const int seg, const int gw, const int nw) {
;     ...
;     for (int i = 0; i < 16; ++i) { c0 += __logf(fv[i].x); c1 += __logf(fv[i].y); lb0[i] = c0; lb1[i] = c1; }
;     char* tb = scr + (long)task * HG_TASK_B;
;     *(float2*)(tb + 8704 + lane * 8) = make_float2(__expf(c0), __expf(c1));
;     unsigned short kh0[16], kh1[16];
;     const float ec0 = __expf(c0), ec1 = __expf(c1);
; #pragma unroll
;     for (int i = 0; i < 16; ++i) {
;       const float e0 = __expf(lb0[i]), e1 = __expf(lb1[i]);
;       const float k0 = (1.f - fv[i].x) * __frcp_rn(e0), k1 = (1.f - fv[i].y) * __frcp_rn(e1);
;       const unsigned qt = (unsigned)f2bf(qv[i].x * e0) | ((unsigned)f2bf(qv[i].y * e1) << 16);
;       const unsigned kt = (unsigned)f2bf(k0) | ((unsigned)f2bf(k1) << 16);
;       *(unsigned*)(wl + i * 136 + lane * 2) = qt;
;       *(unsigned*)(wl + 2176 + i * 136 + lane * 2) = kt;
;       kh0[i] = f2bf(k0 * ec0);
;       kh1[i] = f2bf(k1 * ec1);
	v_sub_f32_e32 v72, v72, v73
	v_cmp_gt_f32_e32 vcc, s38, v10
	v_add_f32_e32 v102, v98, v72
	s_nop 0
	v_cndmask_b32_e64 v72, 0, 32, vcc
	v_ldexp_f32 v72, v10, v72
	v_log_f32_e32 v72, v72
	s_nop 0
	v_mul_f32_e32 v73, 0x3f317217, v72
	v_fma_f32 v73, v72, s39, -v73
	v_fmac_f32_e32 v73, 0x3377d1cf, v72
	v_fmac_f32_e32 v73, 0x3f317217, v72
	v_cmp_lt_f32_e64 s[12:13], |v72|, s96
	s_nop 1
	v_cndmask_b32_e64 v72, v72, v73, s[12:13]
	v_cndmask_b32_e32 v73, 0, v99, vcc
	v_sub_f32_e32 v72, v72, v73
	v_cmp_gt_f32_e32 vcc, s38, v11
	v_add_f32_e32 v93, v100, v72
	s_nop 0
	v_cndmask_b32_e64 v72, 0, 32, vcc
	v_ldexp_f32 v72, v11, v72
	v_log_f32_e32 v72, v72
	s_nop 0
	v_mul_f32_e32 v73, 0x3f317217, v72
	v_fma_f32 v73, v72, s39, -v73
	v_fmac_f32_e32 v73, 0x3377d1cf, v72
	v_fmac_f32_e32 v73, 0x3f317217, v72
	v_cmp_lt_f32_e64 s[12:13], |v72|, s96
	s_nop 1
	v_cndmask_b32_e64 v72, v72, v73, s[12:13]
	v_cndmask_b32_e32 v73, 0, v99, vcc
	v_sub_f32_e32 v72, v72, v73
	v_cmp_gt_f32_e32 vcc, s38, v12
	v_add_f32_e32 v94, v102, v72
	s_nop 0
	v_cndmask_b32_e64 v72, 0, 32, vcc
	v_ldexp_f32 v72, v12, v72
	v_log_f32_e32 v72, v72
	s_nop 0
	v_mul_f32_e32 v73, 0x3f317217, v72
	v_fma_f32 v73, v72, s39, -v73
	v_fmac_f32_e32 v73, 0x3377d1cf, v72
	v_fmac_f32_e32 v73, 0x3f317217, v72
	v_cmp_lt_f32_e64 s[12:13], |v72|, s96
	s_nop 1
	v_cndmask_b32_e64 v72, v72, v73, s[12:13]
	v_cndmask_b32_e32 v73, 0, v99, vcc
	v_sub_f32_e32 v72, v72, v73
	v_cmp_gt_f32_e32 vcc, s38, v13
	v_add_f32_e32 v95, v93, v72
	s_nop 0
	v_cndmask_b32_e64 v72, 0, 32, vcc
	v_ldexp_f32 v72, v13, v72
	v_log_f32_e32 v72, v72
	s_nop 0
	v_mul_f32_e32 v73, 0x3f317217, v72
	v_fma_f32 v73, v72, s39, -v73
	v_fmac_f32_e32 v73, 0x3377d1cf, v72
	v_fmac_f32_e32 v73, 0x3f317217, v72
	v_cmp_lt_f32_e64 s[12:13], |v72|, s96
	s_nop 1
	v_cndmask_b32_e64 v72, v72, v73, s[12:13]
	v_cndmask_b32_e32 v73, 0, v99, vcc
	v_sub_f32_e32 v72, v72, v73
	v_cmp_gt_f32_e32 vcc, s38, v2
	v_add_f32_e32 v96, v94, v72
	s_nop 0
	v_cndmask_b32_e64 v72, 0, 32, vcc
	v_ldexp_f32 v72, v2, v72
	v_log_f32_e32 v72, v72
	s_nop 0
	v_mul_f32_e32 v73, 0x3f317217, v72
	v_fma_f32 v73, v72, s39, -v73
	v_fmac_f32_e32 v73, 0x3377d1cf, v72
	v_fmac_f32_e32 v73, 0x3f317217, v72
	v_cmp_lt_f32_e64 s[12:13], |v72|, s96
	s_nop 1
	v_cndmask_b32_e64 v72, v72, v73, s[12:13]
	v_cndmask_b32_e32 v73, 0, v99, vcc
	v_sub_f32_e32 v72, v72, v73
	v_cmp_gt_f32_e32 vcc, s38, v3
	v_add_f32_e32 v91, v95, v72
	s_nop 0
	v_cndmask_b32_e64 v72, 0, 32, vcc
	v_ldexp_f32 v72, v3, v72
	v_log_f32_e32 v72, v72
	s_nop 0
	v_mul_f32_e32 v73, 0x3f317217, v72
	v_fma_f32 v73, v72, s39, -v73
	v_fmac_f32_e32 v73, 0x3377d1cf, v72
	v_fmac_f32_e32 v73, 0x3f317217, v72
	v_cmp_lt_f32_e64 s[12:13], |v72|, s96
	s_nop 1
	v_cndmask_b32_e64 v72, v72, v73, s[12:13]
	v_cndmask_b32_e32 v73, 0, v99, vcc
	v_sub_f32_e32 v72, v72, v73
	s_waitcnt vmcnt(0)
	v_cmp_gt_f32_e32 vcc, s38, v4
	v_add_f32_e32 v92, v96, v72
	s_nop 0
	v_cndmask_b32_e64 v72, 0, 32, vcc
	v_ldexp_f32 v72, v4, v72
	v_log_f32_e32 v72, v72
	s_nop 0
	v_mul_f32_e32 v73, 0x3f317217, v72
	v_fma_f32 v73, v72, s39, -v73
	v_fmac_f32_e32 v73, 0x3377d1cf, v72
	v_fmac_f32_e32 v73, 0x3f317217, v72
	v_cmp_lt_f32_e64 s[12:13], |v72|, s96
	s_nop 1
	v_cndmask_b32_e64 v72, v72, v73, s[12:13]
	v_cndmask_b32_e32 v73, 0, v99, vcc
	v_cmp_gt_f32_e32 vcc, s38, v5
	v_sub_f32_e32 v72, v72, v73
	v_add_f32_e32 v72, v91, v72
	v_cndmask_b32_e64 v73, 0, 32, vcc
	v_ldexp_f32 v73, v5, v73
	v_log_f32_e32 v73, v73
	v_mul_f32_e32 v72, 0x3fb8aa3b, v72
	v_exp_f32_e32 v72, v72
	v_mul_f32_e32 v129, 0x3f317217, v73
	v_fma_f32 v129, v73, s39, -v129
	v_fmac_f32_e32 v129, 0x3377d1cf, v73
	v_fmac_f32_e32 v129, 0x3f317217, v73
	v_cmp_lt_f32_e64 s[12:13], |v73|, s96
	v_mul_f32_e32 v6, v6, v72
	s_nop 0
	v_cndmask_b32_e64 v73, v73, v129, s[12:13]
	v_cndmask_b32_e32 v129, 0, v99, vcc
	v_sub_f32_e32 v73, v73, v129
	v_bfe_u32 v129, v70, 16, 1
	v_add3_u32 v70, v70, v129, s97
	v_bfe_u32 v129, v71, 16, 1
	v_lshrrev_b32_e32 v70, 16, v70
	v_add3_u32 v71, v71, v129, s97
	v_and_or_b32 v70, v71, s48, v70
	v_mul_f32_e32 v71, 0x3fb8aa3b, v127
	v_exp_f32_e32 v71, v71
	v_mul_f32_e32 v127, 0x3fb8aa3b, v128
	v_exp_f32_e32 v127, v127
	s_add_i32 s12, s22, s21
	v_mul_f32_e32 v68, v68, v71
	v_bfe_u32 v128, v68, 16, 1
	v_mul_f32_e32 v69, v69, v127
	v_add3_u32 v68, v68, v128, s97
	v_bfe_u32 v128, v69, 16, 1
	v_lshrrev_b32_e32 v68, 16, v68
	v_add3_u32 v69, v69, v128, s97
	v_and_or_b32 v68, v69, s48, v68
	s_mul_hi_i32 s13, s12, 0x2400
	s_mulk_i32 s12, 0x2400
	ds_write2_b32 v74, v70, v68 offset1:68
	v_mov_b32_e32 v68, v64
	v_div_scale_f32 v64, s[22:23], v71, v71, 1.0
	s_add_u32 s12, s14, s12
	v_mov_b32_e32 v69, v66
	v_rcp_f32_e32 v66, v64
	s_addc_u32 s13, s15, s13
	v_lshl_add_u64 v[130:131], s[12:13], 0, v[0:1]
	v_add_co_u32_e32 v130, vcc, s54, v130
	v_fma_f32 v70, -v64, v66, 1.0
	s_nop 0
	v_addc_co_u32_e32 v131, vcc, 0, v131, vcc
	v_fmac_f32_e32 v66, v70, v66
	v_div_scale_f32 v70, vcc, 1.0, v71, 1.0
	v_mul_f32_e32 v128, v70, v66
	v_fma_f32 v129, -v64, v128, v70
	v_fmac_f32_e32 v128, v129, v66
	v_fma_f32 v64, -v64, v128, v70
	v_div_fmas_f32 v64, v64, v66, v128
	v_div_fixup_f32 v71, v64, v71, 1.0
	v_div_scale_f32 v64, s[22:23], v125, v125, 1.0
	v_rcp_f32_e32 v66, v64
	v_pk_add_f32 v[68:69], v[68:69], 1.0 op_sel_hi:[1,0] neg_lo:[1,0] neg_hi:[1,0]
	v_add_f32_e32 v73, v92, v73
	v_mul_f32_e32 v73, 0x3fb8aa3b, v73
	v_fma_f32 v70, -v64, v66, 1.0
	v_fmac_f32_e32 v66, v70, v66
	v_div_scale_f32 v70, vcc, 1.0, v125, 1.0
	v_mul_f32_e32 v128, v70, v66
	v_fma_f32 v129, -v64, v128, v70
	v_fmac_f32_e32 v128, v129, v66
	v_fma_f32 v64, -v64, v128, v70
	v_div_fmas_f32 v64, v64, v66, v128
	v_div_fixup_f32 v70, v64, v125, 1.0
; __device__ __forceinline__ void hgrn_pre_phase(KP p, char* smem, int wv, const int seg, const int gw, const int nw) {
;     ...
;     for (int i = 0; i < 16; ++i) {
;       const float e0 = __expf(lb0[i]), e1 = __expf(lb1[i]);
;       const float k0 = (1.f - fv[i].x) * __frcp_rn(e0), k1 = (1.f - fv[i].y) * __frcp_rn(e1);
;       const unsigned qt = (unsigned)f2bf(qv[i].x * e0) | ((unsigned)f2bf(qv[i].y * e1) << 16);
;       const unsigned kt = (unsigned)f2bf(k0) | ((unsigned)f2bf(k1) << 16);
;       *(unsigned*)(wl + i * 136 + lane * 2) = qt;
;       *(unsigned*)(wl + 2176 + i * 136 + lane * 2) = kt;
;       kh0[i] = f2bf(k0 * ec0);
;       kh1[i] = f2bf(k1 * ec1);
;     }
	v_pk_mul_f32 v[68:69], v[68:69], v[70:71]
	v_mov_b32_e32 v66, v65
	v_bfe_u32 v64, v68, 16, 1
	v_add3_u32 v64, v68, v64, s97
	v_lshrrev_b32_e32 v70, 16, v64
	v_bfe_u32 v64, v69, 16, 1
	v_add3_u32 v64, v69, v64, s97
	v_lshrrev_b32_e32 v71, 16, v64
	v_pk_add_f32 v[64:65], v[66:67], 1.0 op_sel_hi:[1,0] neg_lo:[1,0] neg_hi:[1,0]
	v_div_scale_f32 v66, s[22:23], v127, v127, 1.0
	v_rcp_f32_e32 v67, v66
	v_exp_f32_e32 v73, v73
	v_fma_f32 v125, -v66, v67, 1.0
	v_fmac_f32_e32 v67, v125, v67
	v_div_scale_f32 v125, vcc, 1.0, v127, 1.0
	v_mul_f32_e32 v128, v125, v67
	v_fma_f32 v129, -v66, v128, v125
	v_fmac_f32_e32 v128, v129, v67
	v_fma_f32 v66, -v66, v128, v125
	v_div_fmas_f32 v66, v66, v67, v128
	v_div_fixup_f32 v67, v66, v127, 1.0
	v_div_scale_f32 v66, s[22:23], v126, v126, 1.0
	v_rcp_f32_e32 v125, v66
	v_mul_f32_e32 v7, v7, v73
	v_pk_mul_f32 v[68:69], v[68:69], v[72:73] op_sel_hi:[1,0]
	global_store_dwordx2 v[130:131], v[72:73], off offset:512
	v_fma_f32 v127, -v66, v125, 1.0
	v_fmac_f32_e32 v125, v127, v125
	v_div_scale_f32 v127, vcc, 1.0, v126, 1.0
	v_mul_f32_e32 v128, v127, v125
	v_fma_f32 v129, -v66, v128, v127
	v_fmac_f32_e32 v128, v129, v125
	v_fma_f32 v66, -v66, v128, v127
	v_div_fmas_f32 v66, v66, v125, v128
	v_div_fixup_f32 v66, v66, v126, 1.0
	v_pk_mul_f32 v[64:65], v[64:65], v[66:67]
	s_nop 0
	v_bfe_u32 v66, v64, 16, 1
	v_bfe_u32 v67, v65, 16, 1
	v_add3_u32 v66, v64, v66, s97
	v_add3_u32 v67, v65, v67, s97
	v_and_or_b32 v66, v66, s48, v70
	v_and_or_b32 v67, v67, s48, v71
	ds_write2_b32 v80, v66, v67 offset0:64 offset1:132
	v_mov_b32_e32 v66, v73
	v_pk_mul_f32 v[64:65], v[64:65], v[66:67] op_sel_hi:[1,0]
	v_mul_f32_e32 v67, 0x3fb8aa3b, v121
	v_exp_f32_e32 v67, v67
	v_mul_f32_e32 v70, 0x3fb8aa3b, v122
	v_exp_f32_e32 v70, v70
	v_mul_f32_e32 v62, v62, v67
	v_bfe_u32 v71, v62, 16, 1
	v_mul_f32_e32 v63, v63, v70
	v_add3_u32 v62, v62, v71, s97
	v_bfe_u32 v71, v63, 16, 1
	v_lshrrev_b32_e32 v62, 16, v62
	v_add3_u32 v63, v63, v71, s97
	v_and_or_b32 v62, v63, s48, v62
	v_mul_f32_e32 v63, 0x3fb8aa3b, v123
	v_exp_f32_e32 v63, v63
	v_mul_f32_e32 v71, 0x3fb8aa3b, v124
	v_exp_f32_e32 v71, v71
	v_mul_f32_e32 v60, v60, v63
	v_bfe_u32 v121, v60, 16, 1
	v_mul_f32_e32 v61, v61, v71
	v_add3_u32 v60, v60, v121, s97
	v_bfe_u32 v121, v61, 16, 1
	v_lshrrev_b32_e32 v60, 16, v60
	v_add3_u32 v61, v61, v121, s97
	v_and_or_b32 v60, v61, s48, v60
	ds_write2_b32 v74, v62, v60 offset0:136 offset1:204
	v_mov_b32_e32 v60, v56
	v_div_scale_f32 v56, s[22:23], v67, v67, 1.0
	v_mov_b32_e32 v61, v58
	v_rcp_f32_e32 v58, v56
	v_pk_add_f32 v[60:61], v[60:61], 1.0 op_sel_hi:[1,0] neg_lo:[1,0] neg_hi:[1,0]
	v_fma_f32 v62, -v56, v58, 1.0
	v_fmac_f32_e32 v58, v62, v58
	v_div_scale_f32 v62, vcc, 1.0, v67, 1.0
	v_mul_f32_e32 v121, v62, v58
	v_fma_f32 v122, -v56, v121, v62
	v_fmac_f32_e32 v121, v122, v58
	v_fma_f32 v56, -v56, v121, v62
	v_div_fmas_f32 v56, v56, v58, v121
	v_div_fixup_f32 v62, v56, v67, 1.0
	v_div_scale_f32 v56, s[22:23], v63, v63, 1.0
	v_rcp_f32_e32 v58, v56
	s_nop 0
	v_fma_f32 v67, -v56, v58, 1.0
	v_fmac_f32_e32 v58, v67, v58
	v_div_scale_f32 v67, vcc, 1.0, v63, 1.0
	v_mul_f32_e32 v121, v67, v58
	v_fma_f32 v122, -v56, v121, v67
	v_fmac_f32_e32 v121, v122, v58
	v_fma_f32 v56, -v56, v121, v67
	v_div_fmas_f32 v56, v56, v58, v121
	v_div_fixup_f32 v63, v56, v63, 1.0
	v_pk_mul_f32 v[60:61], v[60:61], v[62:63]
	v_mov_b32_e32 v58, v57
	v_bfe_u32 v56, v60, 16, 1
	v_add3_u32 v56, v60, v56, s97
	v_lshrrev_b32_e32 v62, 16, v56
	v_bfe_u32 v56, v61, 16, 1
	v_add3_u32 v56, v61, v56, s97
	v_lshrrev_b32_e32 v63, 16, v56
	v_pk_add_f32 v[56:57], v[58:59], 1.0 op_sel_hi:[1,0] neg_lo:[1,0] neg_hi:[1,0]
	v_div_scale_f32 v58, s[22:23], v70, v70, 1.0
	v_rcp_f32_e32 v59, v58
	v_pk_mul_f32 v[60:61], v[60:61], v[72:73] op_sel_hi:[1,0]
	v_fma_f32 v67, -v58, v59, 1.0
	v_fmac_f32_e32 v59, v67, v59
	v_div_scale_f32 v67, vcc, 1.0, v70, 1.0
	v_mul_f32_e32 v121, v67, v59
	v_fma_f32 v122, -v58, v121, v67
	v_fmac_f32_e32 v121, v122, v59
	v_fma_f32 v58, -v58, v121, v67
	v_div_fmas_f32 v58, v58, v59, v121
	v_div_scale_f32 v59, s[22:23], v71, v71, 1.0
	v_rcp_f32_e32 v67, v59
	v_div_fixup_f32 v58, v58, v70, 1.0
	v_fma_f32 v70, -v59, v67, 1.0
	v_fmac_f32_e32 v67, v70, v67
	v_div_scale_f32 v70, vcc, 1.0, v71, 1.0
	v_mul_f32_e32 v121, v70, v67
	v_fma_f32 v122, -v59, v121, v70
	v_fmac_f32_e32 v121, v122, v67
	v_fma_f32 v59, -v59, v121, v70
	v_div_fmas_f32 v59, v59, v67, v121
	v_div_fixup_f32 v59, v59, v71, 1.0
	v_pk_mul_f32 v[56:57], v[56:57], v[58:59]
	s_nop 0
	v_bfe_u32 v58, v56, 16, 1
	v_bfe_u32 v59, v57, 16, 1
	v_add3_u32 v58, v56, v58, s97
	v_add3_u32 v59, v57, v59, s97
	v_and_or_b32 v58, v58, s48, v62
	v_and_or_b32 v59, v59, s48, v63
	ds_write2_b32 v81, v58, v59 offset0:72 offset1:140
	v_mul_f32_e32 v58, 0x3fb8aa3b, v117
	v_exp_f32_e32 v58, v58
	v_mul_f32_e32 v59, 0x3fb8aa3b, v118
	v_exp_f32_e32 v59, v59
	v_pk_mul_f32 v[56:57], v[56:57], v[66:67] op_sel_hi:[1,0]
	v_mul_f32_e32 v54, v54, v58
	v_bfe_u32 v62, v54, 16, 1
	v_mul_f32_e32 v55, v55, v59
	v_add3_u32 v54, v54, v62, s97
	v_bfe_u32 v62, v55, 16, 1
	v_lshrrev_b32_e32 v54, 16, v54
	v_add3_u32 v55, v55, v62, s97
	v_and_or_b32 v54, v55, s48, v54
	v_mul_f32_e32 v55, 0x3fb8aa3b, v119
	v_exp_f32_e32 v55, v55
	v_mul_f32_e32 v62, 0x3fb8aa3b, v120
	v_exp_f32_e32 v62, v62
	v_mul_f32_e32 v52, v52, v55
	v_bfe_u32 v63, v52, 16, 1
	v_mul_f32_e32 v53, v53, v62
	v_add3_u32 v52, v52, v63, s97
	v_bfe_u32 v63, v53, 16, 1
	v_lshrrev_b32_e32 v52, 16, v52
	v_add3_u32 v53, v53, v63, s97
	v_and_or_b32 v52, v53, s48, v52
	ds_write2_b32 v82, v54, v52 offset0:16 offset1:84
	v_mov_b32_e32 v52, v48
	v_div_scale_f32 v48, s[22:23], v58, v58, 1.0
	v_mov_b32_e32 v53, v50
; __device__ __forceinline__ void hgrn_pre_phase(KP p, char* smem, int wv, const int seg, const int gw, const int nw) {
;     ...
;     for (int i = 0; i < 16; ++i) {
;       const float e0 = __expf(lb0[i]), e1 = __expf(lb1[i]);
;       const float k0 = (1.f - fv[i].x) * __frcp_rn(e0), k1 = (1.f - fv[i].y) * __frcp_rn(e1);
;       const unsigned qt = (unsigned)f2bf(qv[i].x * e0) | ((unsigned)f2bf(qv[i].y * e1) << 16);
;       const unsigned kt = (unsigned)f2bf(k0) | ((unsigned)f2bf(k1) << 16);
;       *(unsigned*)(wl + i * 136 + lane * 2) = qt;
;       *(unsigned*)(wl + 2176 + i * 136 + lane * 2) = kt;
;       kh0[i] = f2bf(k0 * ec0);
;       kh1[i] = f2bf(k1 * ec1);
;     }
	v_rcp_f32_e32 v50, v48
	v_pk_add_f32 v[52:53], v[52:53], 1.0 op_sel_hi:[1,0] neg_lo:[1,0] neg_hi:[1,0]
	v_fma_f32 v54, -v48, v50, 1.0
	v_fmac_f32_e32 v50, v54, v50
	v_div_scale_f32 v54, vcc, 1.0, v58, 1.0
	v_mul_f32_e32 v63, v54, v50
	v_fma_f32 v67, -v48, v63, v54
	v_fmac_f32_e32 v63, v67, v50
	v_fma_f32 v48, -v48, v63, v54
	v_div_fmas_f32 v48, v48, v50, v63
	v_div_fixup_f32 v54, v48, v58, 1.0
	v_div_scale_f32 v48, s[22:23], v55, v55, 1.0
	v_rcp_f32_e32 v50, v48
	s_nop 0
	v_fma_f32 v58, -v48, v50, 1.0
	v_fmac_f32_e32 v50, v58, v50
	v_div_scale_f32 v58, vcc, 1.0, v55, 1.0
	v_mul_f32_e32 v63, v58, v50
	v_fma_f32 v67, -v48, v63, v58
	v_fmac_f32_e32 v63, v67, v50
	v_fma_f32 v48, -v48, v63, v58
	v_div_fmas_f32 v48, v48, v50, v63
	v_div_fixup_f32 v55, v48, v55, 1.0
	v_pk_mul_f32 v[52:53], v[52:53], v[54:55]
	v_mov_b32_e32 v50, v49
	v_bfe_u32 v48, v52, 16, 1
	v_add3_u32 v48, v52, v48, s97
	v_lshrrev_b32_e32 v54, 16, v48
	v_bfe_u32 v48, v53, 16, 1
	v_add3_u32 v48, v53, v48, s97
	v_lshrrev_b32_e32 v55, 16, v48
	v_pk_add_f32 v[48:49], v[50:51], 1.0 op_sel_hi:[1,0] neg_lo:[1,0] neg_hi:[1,0]
	v_div_scale_f32 v50, s[22:23], v59, v59, 1.0
	v_rcp_f32_e32 v51, v50
	v_pk_mul_f32 v[52:53], v[52:53], v[72:73] op_sel_hi:[1,0]
	v_fma_f32 v58, -v50, v51, 1.0
	v_fmac_f32_e32 v51, v58, v51
	v_div_scale_f32 v58, vcc, 1.0, v59, 1.0
	v_mul_f32_e32 v63, v58, v51
	v_fma_f32 v67, -v50, v63, v58
	v_fmac_f32_e32 v63, v67, v51
	v_fma_f32 v50, -v50, v63, v58
	v_div_fmas_f32 v50, v50, v51, v63
	v_div_scale_f32 v51, s[22:23], v62, v62, 1.0
	v_rcp_f32_e32 v58, v51
	v_div_fixup_f32 v50, v50, v59, 1.0
	v_fma_f32 v59, -v51, v58, 1.0
	v_fmac_f32_e32 v58, v59, v58
	v_div_scale_f32 v59, vcc, 1.0, v62, 1.0
	v_mul_f32_e32 v63, v59, v58
	v_fma_f32 v67, -v51, v63, v59
	v_fmac_f32_e32 v63, v67, v58
	v_fma_f32 v51, -v51, v63, v59
	v_div_fmas_f32 v51, v51, v58, v63
	v_div_fixup_f32 v51, v51, v62, 1.0
	v_pk_mul_f32 v[48:49], v[48:49], v[50:51]
	s_nop 0
	v_bfe_u32 v50, v48, 16, 1
	v_bfe_u32 v51, v49, 16, 1
	v_add3_u32 v50, v48, v50, s97
	v_add3_u32 v51, v49, v51, s97
	v_and_or_b32 v50, v50, s48, v54
	v_and_or_b32 v51, v51, s48, v55
	ds_write2_b32 v83, v50, v51 offset0:80 offset1:148
	v_mul_f32_e32 v50, 0x3fb8aa3b, v113
	v_exp_f32_e32 v50, v50
	v_mul_f32_e32 v51, 0x3fb8aa3b, v114
	v_exp_f32_e32 v51, v51
	v_pk_mul_f32 v[48:49], v[48:49], v[66:67] op_sel_hi:[1,0]
	v_mul_f32_e32 v46, v46, v50
	v_bfe_u32 v54, v46, 16, 1
	v_mul_f32_e32 v47, v47, v51
	v_add3_u32 v46, v46, v54, s97
	v_bfe_u32 v54, v47, 16, 1
	v_lshrrev_b32_e32 v46, 16, v46
	v_add3_u32 v47, v47, v54, s97
	v_and_or_b32 v46, v47, s48, v46
	v_mul_f32_e32 v47, 0x3fb8aa3b, v115
	v_exp_f32_e32 v47, v47
	v_mul_f32_e32 v54, 0x3fb8aa3b, v116
	v_exp_f32_e32 v54, v54
	v_mul_f32_e32 v44, v44, v47
	v_bfe_u32 v55, v44, 16, 1
	v_mul_f32_e32 v45, v45, v54
	v_add3_u32 v44, v44, v55, s97
	v_bfe_u32 v55, v45, 16, 1
	v_lshrrev_b32_e32 v44, 16, v44
	v_add3_u32 v45, v45, v55, s97
	v_and_or_b32 v44, v45, s48, v44
	ds_write2_b32 v82, v46, v44 offset0:152 offset1:220
	v_mov_b32_e32 v44, v40
	v_div_scale_f32 v40, s[22:23], v50, v50, 1.0
	v_mov_b32_e32 v45, v42
	v_rcp_f32_e32 v42, v40
	v_pk_add_f32 v[44:45], v[44:45], 1.0 op_sel_hi:[1,0] neg_lo:[1,0] neg_hi:[1,0]
	v_fma_f32 v46, -v40, v42, 1.0
	v_fmac_f32_e32 v42, v46, v42
	v_div_scale_f32 v46, vcc, 1.0, v50, 1.0
	v_mul_f32_e32 v55, v46, v42
	v_fma_f32 v58, -v40, v55, v46
	v_fmac_f32_e32 v55, v58, v42
	v_fma_f32 v40, -v40, v55, v46
	v_div_fmas_f32 v40, v40, v42, v55
	v_div_fixup_f32 v46, v40, v50, 1.0
	v_div_scale_f32 v40, s[22:23], v47, v47, 1.0
	v_rcp_f32_e32 v42, v40
	s_nop 0
	v_fma_f32 v50, -v40, v42, 1.0
	v_fmac_f32_e32 v42, v50, v42
	v_div_scale_f32 v50, vcc, 1.0, v47, 1.0
	v_mul_f32_e32 v55, v50, v42
	v_fma_f32 v58, -v40, v55, v50
	v_fmac_f32_e32 v55, v58, v42
	v_fma_f32 v40, -v40, v55, v50
	v_div_fmas_f32 v40, v40, v42, v55
	v_div_fixup_f32 v47, v40, v47, 1.0
	v_pk_mul_f32 v[44:45], v[44:45], v[46:47]
	v_mov_b32_e32 v42, v41
	v_bfe_u32 v40, v44, 16, 1
	v_add3_u32 v40, v44, v40, s97
	v_lshrrev_b32_e32 v46, 16, v40
	v_bfe_u32 v40, v45, 16, 1
	v_add3_u32 v40, v45, v40, s97
	v_lshrrev_b32_e32 v47, 16, v40
	v_pk_add_f32 v[40:41], v[42:43], 1.0 op_sel_hi:[1,0] neg_lo:[1,0] neg_hi:[1,0]
	v_div_scale_f32 v42, s[22:23], v51, v51, 1.0
	v_rcp_f32_e32 v43, v42
	v_pk_mul_f32 v[44:45], v[44:45], v[72:73] op_sel_hi:[1,0]
	v_fma_f32 v50, -v42, v43, 1.0
	v_fmac_f32_e32 v43, v50, v43
	v_div_scale_f32 v50, vcc, 1.0, v51, 1.0
	v_mul_f32_e32 v55, v50, v43
	v_fma_f32 v58, -v42, v55, v50
	v_fmac_f32_e32 v55, v58, v43
	v_fma_f32 v42, -v42, v55, v50
	v_div_fmas_f32 v42, v42, v43, v55
	v_div_scale_f32 v43, s[22:23], v54, v54, 1.0
	v_rcp_f32_e32 v50, v43
	v_div_fixup_f32 v42, v42, v51, 1.0
	v_fma_f32 v51, -v43, v50, 1.0
	v_fmac_f32_e32 v50, v51, v50
	v_div_scale_f32 v51, vcc, 1.0, v54, 1.0
	v_mul_f32_e32 v55, v51, v50
	v_fma_f32 v58, -v43, v55, v51
	v_fmac_f32_e32 v55, v58, v50
	v_fma_f32 v43, -v43, v55, v51
	v_div_fmas_f32 v43, v43, v50, v55
	v_div_fixup_f32 v43, v43, v54, 1.0
	v_pk_mul_f32 v[40:41], v[40:41], v[42:43]
	s_nop 0
	v_bfe_u32 v42, v40, 16, 1
	v_bfe_u32 v43, v41, 16, 1
	v_add3_u32 v42, v40, v42, s97
	v_add3_u32 v43, v41, v43, s97
	v_and_or_b32 v42, v42, s48, v46
	v_and_or_b32 v43, v43, s48, v47
	ds_write2_b32 v84, v42, v43 offset0:88 offset1:156
	v_mul_f32_e32 v42, 0x3fb8aa3b, v104
	v_exp_f32_e32 v42, v42
	v_mul_f32_e32 v43, 0x3fb8aa3b, v106
	v_exp_f32_e32 v43, v43
	v_pk_mul_f32 v[40:41], v[40:41], v[66:67] op_sel_hi:[1,0]
	v_mul_f32_e32 v38, v38, v42
	v_bfe_u32 v46, v38, 16, 1
	v_mul_f32_e32 v39, v39, v43
	v_add3_u32 v38, v38, v46, s97
	v_bfe_u32 v46, v39, 16, 1
	v_lshrrev_b32_e32 v38, 16, v38
; __device__ __forceinline__ void hgrn_pre_phase(KP p, char* smem, int wv, const int seg, const int gw, const int nw) {
;     ...
;     for (int i = 0; i < 16; ++i) {
;       const float e0 = __expf(lb0[i]), e1 = __expf(lb1[i]);
;       const float k0 = (1.f - fv[i].x) * __frcp_rn(e0), k1 = (1.f - fv[i].y) * __frcp_rn(e1);
;       const unsigned qt = (unsigned)f2bf(qv[i].x * e0) | ((unsigned)f2bf(qv[i].y * e1) << 16);
;       const unsigned kt = (unsigned)f2bf(k0) | ((unsigned)f2bf(k1) << 16);
;       *(unsigned*)(wl + i * 136 + lane * 2) = qt;
;       *(unsigned*)(wl + 2176 + i * 136 + lane * 2) = kt;
;       kh0[i] = f2bf(k0 * ec0);
;       kh1[i] = f2bf(k1 * ec1);
;     }
	v_add3_u32 v39, v39, v46, s97
	v_and_or_b32 v38, v39, s48, v38
	v_mul_f32_e32 v39, 0x3fb8aa3b, v107
	v_exp_f32_e32 v39, v39
	v_mul_f32_e32 v46, 0x3fb8aa3b, v112
	v_exp_f32_e32 v46, v46
	v_mul_f32_e32 v36, v36, v39
	v_bfe_u32 v47, v36, 16, 1
	v_mul_f32_e32 v37, v37, v46
	v_add3_u32 v36, v36, v47, s97
	v_bfe_u32 v47, v37, 16, 1
	v_lshrrev_b32_e32 v36, 16, v36
	v_add3_u32 v37, v37, v47, s97
	v_and_or_b32 v36, v37, s48, v36
	ds_write2_b32 v85, v38, v36 offset0:32 offset1:100
	v_mov_b32_e32 v36, v32
	v_div_scale_f32 v32, s[22:23], v42, v42, 1.0
	v_mov_b32_e32 v37, v34
	v_rcp_f32_e32 v34, v32
	v_pk_add_f32 v[36:37], v[36:37], 1.0 op_sel_hi:[1,0] neg_lo:[1,0] neg_hi:[1,0]
	v_fma_f32 v38, -v32, v34, 1.0
	v_fmac_f32_e32 v34, v38, v34
	v_div_scale_f32 v38, vcc, 1.0, v42, 1.0
	v_mul_f32_e32 v47, v38, v34
	v_fma_f32 v50, -v32, v47, v38
	v_fmac_f32_e32 v47, v50, v34
	v_fma_f32 v32, -v32, v47, v38
	v_div_fmas_f32 v32, v32, v34, v47
	v_div_fixup_f32 v38, v32, v42, 1.0
	v_div_scale_f32 v32, s[22:23], v39, v39, 1.0
	v_rcp_f32_e32 v34, v32
	s_nop 0
	v_fma_f32 v42, -v32, v34, 1.0
	v_fmac_f32_e32 v34, v42, v34
	v_div_scale_f32 v42, vcc, 1.0, v39, 1.0
	v_mul_f32_e32 v47, v42, v34
	v_fma_f32 v50, -v32, v47, v42
	v_fmac_f32_e32 v47, v50, v34
	v_fma_f32 v32, -v32, v47, v42
	v_div_fmas_f32 v32, v32, v34, v47
	v_div_fixup_f32 v39, v32, v39, 1.0
	v_pk_mul_f32 v[36:37], v[36:37], v[38:39]
	v_mov_b32_e32 v34, v33
	v_bfe_u32 v32, v36, 16, 1
	v_add3_u32 v32, v36, v32, s97
	v_lshrrev_b32_e32 v38, 16, v32
	v_bfe_u32 v32, v37, 16, 1
	v_add3_u32 v32, v37, v32, s97
	v_lshrrev_b32_e32 v39, 16, v32
	v_pk_add_f32 v[32:33], v[34:35], 1.0 op_sel_hi:[1,0] neg_lo:[1,0] neg_hi:[1,0]
	v_div_scale_f32 v34, s[22:23], v43, v43, 1.0
	v_rcp_f32_e32 v35, v34
	v_pk_mul_f32 v[36:37], v[36:37], v[72:73] op_sel_hi:[1,0]
	v_fma_f32 v42, -v34, v35, 1.0
	v_fmac_f32_e32 v35, v42, v35
	v_div_scale_f32 v42, vcc, 1.0, v43, 1.0
	v_mul_f32_e32 v47, v42, v35
	v_fma_f32 v50, -v34, v47, v42
	v_fmac_f32_e32 v47, v50, v35
	v_fma_f32 v34, -v34, v47, v42
	v_div_fmas_f32 v34, v34, v35, v47
	v_div_scale_f32 v35, s[22:23], v46, v46, 1.0
	v_rcp_f32_e32 v42, v35
	v_div_fixup_f32 v34, v34, v43, 1.0
	v_fma_f32 v43, -v35, v42, 1.0
	v_fmac_f32_e32 v42, v43, v42
	v_div_scale_f32 v43, vcc, 1.0, v46, 1.0
	v_mul_f32_e32 v47, v43, v42
	v_fma_f32 v50, -v35, v47, v43
	v_fmac_f32_e32 v47, v50, v42
	v_fma_f32 v35, -v35, v47, v43
	v_div_fmas_f32 v35, v35, v42, v47
	v_div_fixup_f32 v35, v35, v46, 1.0
	v_pk_mul_f32 v[32:33], v[32:33], v[34:35]
	s_nop 0
	v_bfe_u32 v34, v32, 16, 1
	v_bfe_u32 v35, v33, 16, 1
	v_add3_u32 v34, v32, v34, s97
	v_add3_u32 v35, v33, v35, s97
	v_and_or_b32 v34, v34, s48, v38
	v_and_or_b32 v35, v35, s48, v39
	ds_write2_b32 v86, v34, v35 offset0:96 offset1:164
	v_mul_f32_e32 v34, 0x3fb8aa3b, v97
	v_exp_f32_e32 v34, v34
	v_mul_f32_e32 v35, 0x3fb8aa3b, v98
	v_exp_f32_e32 v35, v35
	v_pk_mul_f32 v[32:33], v[32:33], v[66:67] op_sel_hi:[1,0]
	v_mul_f32_e32 v30, v30, v34
	v_bfe_u32 v38, v30, 16, 1
	v_mul_f32_e32 v31, v31, v35
	v_add3_u32 v30, v30, v38, s97
	v_bfe_u32 v38, v31, 16, 1
	v_lshrrev_b32_e32 v30, 16, v30
	v_add3_u32 v31, v31, v38, s97
	v_and_or_b32 v30, v31, s48, v30
	v_mul_f32_e32 v31, 0x3fb8aa3b, v100
	v_exp_f32_e32 v31, v31
	v_mul_f32_e32 v38, 0x3fb8aa3b, v102
	v_exp_f32_e32 v38, v38
	v_mul_f32_e32 v28, v28, v31
	v_bfe_u32 v39, v28, 16, 1
	v_mul_f32_e32 v29, v29, v38
	v_add3_u32 v28, v28, v39, s97
	v_bfe_u32 v39, v29, 16, 1
	v_lshrrev_b32_e32 v28, 16, v28
	v_add3_u32 v29, v29, v39, s97
	v_and_or_b32 v28, v29, s48, v28
	ds_write2_b32 v85, v30, v28 offset0:168 offset1:236
	v_mov_b32_e32 v28, v24
	v_div_scale_f32 v24, s[22:23], v34, v34, 1.0
	v_mov_b32_e32 v29, v26
	v_rcp_f32_e32 v26, v24
	v_pk_add_f32 v[28:29], v[28:29], 1.0 op_sel_hi:[1,0] neg_lo:[1,0] neg_hi:[1,0]
	v_fma_f32 v30, -v24, v26, 1.0
	v_fmac_f32_e32 v26, v30, v26
	v_div_scale_f32 v30, vcc, 1.0, v34, 1.0
	v_mul_f32_e32 v39, v30, v26
	v_fma_f32 v42, -v24, v39, v30
	v_fmac_f32_e32 v39, v42, v26
	v_fma_f32 v24, -v24, v39, v30
	v_div_fmas_f32 v24, v24, v26, v39
	v_div_fixup_f32 v30, v24, v34, 1.0
	v_div_scale_f32 v24, s[22:23], v31, v31, 1.0
	v_rcp_f32_e32 v26, v24
	s_nop 0
	v_fma_f32 v34, -v24, v26, 1.0
	v_fmac_f32_e32 v26, v34, v26
	v_div_scale_f32 v34, vcc, 1.0, v31, 1.0
	v_mul_f32_e32 v39, v34, v26
	v_fma_f32 v42, -v24, v39, v34
	v_fmac_f32_e32 v39, v42, v26
	v_fma_f32 v24, -v24, v39, v34
	v_div_fmas_f32 v24, v24, v26, v39
	v_div_fixup_f32 v31, v24, v31, 1.0
	v_pk_mul_f32 v[28:29], v[28:29], v[30:31]
	v_mov_b32_e32 v26, v25
	v_bfe_u32 v24, v28, 16, 1
	v_add3_u32 v24, v28, v24, s97
	v_lshrrev_b32_e32 v30, 16, v24
	v_bfe_u32 v24, v29, 16, 1
	v_add3_u32 v24, v29, v24, s97
	v_lshrrev_b32_e32 v31, 16, v24
	v_pk_add_f32 v[24:25], v[26:27], 1.0 op_sel_hi:[1,0] neg_lo:[1,0] neg_hi:[1,0]
	v_div_scale_f32 v26, s[22:23], v35, v35, 1.0
	v_rcp_f32_e32 v27, v26
	v_pk_mul_f32 v[28:29], v[28:29], v[72:73] op_sel_hi:[1,0]
	v_fma_f32 v34, -v26, v27, 1.0
	v_fmac_f32_e32 v27, v34, v27
	v_div_scale_f32 v34, vcc, 1.0, v35, 1.0
	v_mul_f32_e32 v39, v34, v27
	v_fma_f32 v42, -v26, v39, v34
	v_fmac_f32_e32 v39, v42, v27
	v_fma_f32 v26, -v26, v39, v34
	v_div_fmas_f32 v26, v26, v27, v39
	v_div_scale_f32 v27, s[22:23], v38, v38, 1.0
	v_rcp_f32_e32 v34, v27
	v_div_fixup_f32 v26, v26, v35, 1.0
	v_fma_f32 v35, -v27, v34, 1.0
	v_fmac_f32_e32 v34, v35, v34
	v_div_scale_f32 v35, vcc, 1.0, v38, 1.0
	v_mul_f32_e32 v39, v35, v34
	v_fma_f32 v42, -v27, v39, v35
	v_fmac_f32_e32 v39, v42, v34
	v_fma_f32 v27, -v27, v39, v35
	v_div_fmas_f32 v27, v27, v34, v39
	v_div_fixup_f32 v27, v27, v38, 1.0
	v_pk_mul_f32 v[24:25], v[24:25], v[26:27]
	s_nop 0
	v_bfe_u32 v26, v24, 16, 1
; __device__ __forceinline__ void hgrn_pre_phase(KP p, char* smem, int wv, const int seg, const int gw, const int nw) {
;     ...
;     for (int i = 0; i < 16; ++i) {
;       const float e0 = __expf(lb0[i]), e1 = __expf(lb1[i]);
;       const float k0 = (1.f - fv[i].x) * __frcp_rn(e0), k1 = (1.f - fv[i].y) * __frcp_rn(e1);
;       const unsigned qt = (unsigned)f2bf(qv[i].x * e0) | ((unsigned)f2bf(qv[i].y * e1) << 16);
;       const unsigned kt = (unsigned)f2bf(k0) | ((unsigned)f2bf(k1) << 16);
;       *(unsigned*)(wl + i * 136 + lane * 2) = qt;
;       *(unsigned*)(wl + 2176 + i * 136 + lane * 2) = kt;
;       kh0[i] = f2bf(k0 * ec0);
;       kh1[i] = f2bf(k1 * ec1);
;     }
	v_bfe_u32 v27, v25, 16, 1
	v_add3_u32 v26, v24, v26, s97
	v_add3_u32 v27, v25, v27, s97
	v_and_or_b32 v26, v26, s48, v30
	v_and_or_b32 v27, v27, s48, v31
	ds_write2_b32 v87, v26, v27 offset0:104 offset1:172
	v_mul_f32_e32 v26, 0x3fb8aa3b, v93
	v_exp_f32_e32 v26, v26
	v_mul_f32_e32 v27, 0x3fb8aa3b, v94
	v_exp_f32_e32 v27, v27
	v_pk_mul_f32 v[24:25], v[24:25], v[66:67] op_sel_hi:[1,0]
	v_mul_f32_e32 v16, v16, v26
	v_bfe_u32 v30, v16, 16, 1
	v_mul_f32_e32 v17, v17, v27
	v_add3_u32 v16, v16, v30, s97
	v_bfe_u32 v30, v17, 16, 1
	v_lshrrev_b32_e32 v16, 16, v16
	v_add3_u32 v17, v17, v30, s97
	v_and_or_b32 v16, v17, s48, v16
	v_mul_f32_e32 v17, 0x3fb8aa3b, v95
	v_exp_f32_e32 v17, v17
	v_mul_f32_e32 v30, 0x3fb8aa3b, v96
	v_exp_f32_e32 v30, v30
	v_mul_f32_e32 v14, v14, v17
	v_bfe_u32 v31, v14, 16, 1
	v_mul_f32_e32 v15, v15, v30
	v_add3_u32 v14, v14, v31, s97
	v_bfe_u32 v31, v15, 16, 1
	v_lshrrev_b32_e32 v14, 16, v14
	v_add3_u32 v15, v15, v31, s97
	v_and_or_b32 v14, v15, s48, v14
	ds_write2_b32 v88, v16, v14 offset0:48 offset1:116
	v_mov_b32_e32 v14, v10
	v_div_scale_f32 v10, s[22:23], v26, v26, 1.0
	v_mov_b32_e32 v15, v12
	v_rcp_f32_e32 v12, v10
	v_pk_add_f32 v[14:15], v[14:15], 1.0 op_sel_hi:[1,0] neg_lo:[1,0] neg_hi:[1,0]
	v_fma_f32 v16, -v10, v12, 1.0
	v_fmac_f32_e32 v12, v16, v12
	v_div_scale_f32 v16, vcc, 1.0, v26, 1.0
	v_mul_f32_e32 v31, v16, v12
	v_fma_f32 v34, -v10, v31, v16
	v_fmac_f32_e32 v31, v34, v12
	v_fma_f32 v10, -v10, v31, v16
	v_div_fmas_f32 v10, v10, v12, v31
	v_div_fixup_f32 v16, v10, v26, 1.0
	v_div_scale_f32 v10, s[22:23], v17, v17, 1.0
	v_rcp_f32_e32 v12, v10
	s_nop 0
	v_fma_f32 v26, -v10, v12, 1.0
	v_fmac_f32_e32 v12, v26, v12
	v_div_scale_f32 v26, vcc, 1.0, v17, 1.0
	v_mul_f32_e32 v31, v26, v12
	v_fma_f32 v34, -v10, v31, v26
	v_fmac_f32_e32 v31, v34, v12
	v_fma_f32 v10, -v10, v31, v26
	v_div_fmas_f32 v10, v10, v12, v31
	v_div_fixup_f32 v17, v10, v17, 1.0
	v_pk_mul_f32 v[14:15], v[14:15], v[16:17]
	v_mov_b32_e32 v12, v11
	v_bfe_u32 v10, v14, 16, 1
	v_add3_u32 v10, v14, v10, s97
	v_lshrrev_b32_e32 v16, 16, v10
	v_bfe_u32 v10, v15, 16, 1
	v_add3_u32 v10, v15, v10, s97
	v_lshrrev_b32_e32 v17, 16, v10
	v_pk_add_f32 v[10:11], v[12:13], 1.0 op_sel_hi:[1,0] neg_lo:[1,0] neg_hi:[1,0]
	v_div_scale_f32 v12, s[22:23], v27, v27, 1.0
	v_rcp_f32_e32 v13, v12
	v_pk_mul_f32 v[14:15], v[14:15], v[72:73] op_sel_hi:[1,0]
	v_fma_f32 v26, -v12, v13, 1.0
	v_fmac_f32_e32 v13, v26, v13
	v_div_scale_f32 v26, vcc, 1.0, v27, 1.0
	v_mul_f32_e32 v31, v26, v13
	v_fma_f32 v34, -v12, v31, v26
	v_fmac_f32_e32 v31, v34, v13
	v_fma_f32 v12, -v12, v31, v26
	v_div_fmas_f32 v12, v12, v13, v31
	v_div_scale_f32 v13, s[22:23], v30, v30, 1.0
	v_rcp_f32_e32 v26, v13
	v_div_fixup_f32 v12, v12, v27, 1.0
	v_fma_f32 v27, -v13, v26, 1.0
	v_fmac_f32_e32 v26, v27, v26
	v_div_scale_f32 v27, vcc, 1.0, v30, 1.0
	v_mul_f32_e32 v31, v27, v26
	v_fma_f32 v34, -v13, v31, v27
	v_fmac_f32_e32 v31, v34, v26
	v_fma_f32 v13, -v13, v31, v27
	v_div_fmas_f32 v13, v13, v26, v31
	v_div_fixup_f32 v13, v13, v30, 1.0
	v_pk_mul_f32 v[10:11], v[10:11], v[12:13]
	s_nop 0
	v_bfe_u32 v12, v10, 16, 1
	v_bfe_u32 v13, v11, 16, 1
	v_add3_u32 v12, v10, v12, s97
	v_add3_u32 v13, v11, v13, s97
	v_and_or_b32 v12, v12, s48, v16
	v_and_or_b32 v13, v13, s48, v17
	v_pk_mul_f32 v[16:17], v[10:11], v[66:67] op_sel_hi:[1,0]
	v_mul_f32_e32 v10, 0x3fb8aa3b, v91
	v_exp_f32_e32 v10, v10
	v_mul_f32_e32 v11, 0x3fb8aa3b, v92
	v_exp_f32_e32 v11, v11
	ds_write2_b32 v89, v12, v13 offset0:112 offset1:180
	v_mul_f32_e32 v8, v8, v10
	v_bfe_u32 v12, v8, 16, 1
	v_mul_f32_e32 v9, v9, v11
	v_add3_u32 v8, v8, v12, s97
	v_bfe_u32 v12, v9, 16, 1
	v_lshrrev_b32_e32 v8, 16, v8
	v_add3_u32 v9, v9, v12, s97
	v_and_or_b32 v8, v9, s48, v8
	v_bfe_u32 v9, v6, 16, 1
	v_add3_u32 v6, v6, v9, s97
	v_bfe_u32 v9, v7, 16, 1
	v_lshrrev_b32_e32 v6, 16, v6
	v_add3_u32 v7, v7, v9, s97
	v_and_or_b32 v6, v7, s48, v6
	ds_write2_b32 v88, v8, v6 offset0:184 offset1:252
	v_mov_b32_e32 v6, v2
	v_div_scale_f32 v2, s[22:23], v10, v10, 1.0
	v_mov_b32_e32 v7, v4
	v_rcp_f32_e32 v4, v2
	v_pk_add_f32 v[6:7], v[6:7], 1.0 op_sel_hi:[1,0] neg_lo:[1,0] neg_hi:[1,0]
	v_fma_f32 v8, -v2, v4, 1.0
	v_fmac_f32_e32 v4, v8, v4
	v_div_scale_f32 v8, vcc, 1.0, v10, 1.0
	v_mul_f32_e32 v9, v8, v4
	v_fma_f32 v12, -v2, v9, v8
	v_fmac_f32_e32 v9, v12, v4
	v_fma_f32 v2, -v2, v9, v8
	v_div_fmas_f32 v2, v2, v4, v9
	v_div_fixup_f32 v8, v2, v10, 1.0
	v_div_scale_f32 v2, s[22:23], v72, v72, 1.0
	v_rcp_f32_e32 v4, v2
	s_nop 0
	v_fma_f32 v9, -v2, v4, 1.0
	v_fmac_f32_e32 v4, v9, v4
	v_div_scale_f32 v9, vcc, 1.0, v72, 1.0
	v_mul_f32_e32 v10, v9, v4
	v_fma_f32 v12, -v2, v10, v9
	v_fmac_f32_e32 v10, v12, v4
	v_fma_f32 v2, -v2, v10, v9
	v_div_fmas_f32 v2, v2, v4, v10
	v_div_fixup_f32 v9, v2, v72, 1.0
	v_pk_mul_f32 v[6:7], v[6:7], v[8:9]
	v_mov_b32_e32 v4, v3
	v_bfe_u32 v2, v6, 16, 1
	v_add3_u32 v2, v6, v2, s97
	v_lshrrev_b32_e32 v8, 16, v2
	v_bfe_u32 v2, v7, 16, 1
	v_add3_u32 v2, v7, v2, s97
	v_lshrrev_b32_e32 v9, 16, v2
	v_pk_add_f32 v[2:3], v[4:5], 1.0 op_sel_hi:[1,0] neg_lo:[1,0] neg_hi:[1,0]
	v_div_scale_f32 v4, s[22:23], v11, v11, 1.0
	v_rcp_f32_e32 v5, v4
	v_pk_mul_f32 v[6:7], v[6:7], v[72:73] op_sel_hi:[1,0]
	v_fma_f32 v10, -v4, v5, 1.0
	v_fmac_f32_e32 v5, v10, v5
	v_div_scale_f32 v10, vcc, 1.0, v11, 1.0
; __device__ __forceinline__ void hgrn_pre_phase(KP p, char* smem, int wv, const int seg, const int gw, const int nw) {
;     ...
;     {
;       const int ch0 = lane * 2, ch1 = ch0 + 1;
;       bf16x8 a, bq, cc, dd;
; #pragma unroll
;       for (int j = 0; j < 8; ++j) { a[j] = (short)kh0[j]; bq[j] = (short)kh0[8 + j]; cc[j] = (short)kh1[j]; dd[j] = (short)kh1[8 + j]; }
;       char* kb = tb + 4096;
;       *(bf16x8*)(kb + (((ch0 >> 4) * 32) + (ch0 & 15)) * 16) = a;
;       *(bf16x8*)(kb + (((ch0 >> 4) * 32) + 16 + (ch0 & 15)) * 16) = bq;
;       *(bf16x8*)(kb + (((ch1 >> 4) * 32) + (ch1 & 15)) * 16) = cc;
;       *(bf16x8*)(kb + (((ch1 >> 4) * 32) + 16 + (ch1 & 15)) * 16) = dd;
;     }
;     f32x4 acc = {0.f, 0.f, 0.f, 0.f};
; #pragma unroll
;     for (int sidx = 0; sidx < 4; ++sidx) {
;       const bf16x8 af = *(const bf16x8*)(wl + fr * 136 + sidx * 32 + fq * 8);
;       const bf16x8 bfm = *(const bf16x8*)(wl + 2176 + fr * 136 + sidx * 32 + fq * 8);
;       *(bf16x8*)(tb + (sidx * 64 + lane) * 16) = af;
;       acc = __builtin_amdgcn_mfma_f32_16x16x32_bf16(af, bfm, acc, 0, 0, 0);
;     }
;     unsigned short* at = (unsigned short*)(tb + 8192);
; #pragma unroll
;     for (int r = 0; r < 4; ++r) {
;       const int i = 4 * fq + r, j = fr;
;       at[((j >> 3) * 16 + i) * 8 + (j & 7)] = (j <= i) ? f2bf(acc[r]) : (unsigned short)0;
;     }
	v_mul_f32_e32 v12, v10, v5
	v_fma_f32 v13, -v4, v12, v10
	v_fmac_f32_e32 v12, v13, v5
	v_fma_f32 v4, -v4, v12, v10
	v_div_fmas_f32 v4, v4, v5, v12
	v_div_scale_f32 v5, s[22:23], v73, v73, 1.0
	v_rcp_f32_e32 v10, v5
	v_div_fixup_f32 v4, v4, v11, 1.0
	v_bfe_u32 v30, v7, 16, 1
	v_bfe_u32 v31, v6, 16, 1
	v_fma_f32 v11, -v5, v10, 1.0
	v_fmac_f32_e32 v10, v11, v10
	v_div_scale_f32 v11, vcc, 1.0, v73, 1.0
	v_mul_f32_e32 v12, v11, v10
	v_fma_f32 v13, -v5, v12, v11
	v_fmac_f32_e32 v12, v13, v10
	v_fma_f32 v5, -v5, v12, v11
	v_div_fmas_f32 v5, v5, v10, v12
	v_div_fixup_f32 v5, v5, v73, 1.0
	v_pk_mul_f32 v[2:3], v[2:3], v[4:5]
	v_bfe_u32 v10, v69, 16, 1
	v_bfe_u32 v4, v2, 16, 1
	v_bfe_u32 v5, v3, 16, 1
	v_add3_u32 v4, v2, v4, s97
	v_add3_u32 v5, v3, v5, s97
	v_and_or_b32 v4, v4, s48, v8
	v_and_or_b32 v5, v5, s48, v9
	ds_write2_b32 v90, v4, v5 offset0:120 offset1:188
	v_pk_mul_f32 v[26:27], v[2:3], v[66:67] op_sel_hi:[1,0]
	v_bfe_u32 v2, v61, 16, 1
	v_bfe_u32 v3, v60, 16, 1
	v_bfe_u32 v4, v53, 16, 1
	v_bfe_u32 v5, v52, 16, 1
	v_bfe_u32 v8, v45, 16, 1
	v_bfe_u32 v9, v44, 16, 1
	v_bfe_u32 v11, v68, 16, 1
	v_add3_u32 v9, v44, v9, s97
	v_add3_u32 v8, v45, v8, s97
	v_add3_u32 v5, v52, v5, s97
	v_add3_u32 v4, v53, v4, s97
	v_add3_u32 v3, v60, v3, s97
	v_add3_u32 v2, v61, v2, s97
	v_add3_u32 v11, v68, v11, s97
	v_add3_u32 v10, v69, v10, s97
	v_perm_b32 v3, v2, v3, s49
	v_perm_b32 v4, v4, v5, s49
	v_perm_b32 v5, v8, v9, s49
	v_perm_b32 v2, v10, v11, s49
	v_bfe_u32 v8, v37, 16, 1
	v_bfe_u32 v9, v36, 16, 1
	v_bfe_u32 v10, v29, 16, 1
	v_bfe_u32 v11, v28, 16, 1
	v_bfe_u32 v12, v15, 16, 1
	v_bfe_u32 v13, v14, 16, 1
	v_add3_u32 v31, v6, v31, s97
	v_add3_u32 v30, v7, v30, s97
	v_add3_u32 v13, v14, v13, s97
	v_add3_u32 v12, v15, v12, s97
	v_add3_u32 v7, v28, v11, s97
	v_add3_u32 v10, v29, v10, s97
	v_add3_u32 v6, v36, v9, s97
	v_add3_u32 v8, v37, v8, s97
	v_perm_b32 v6, v8, v6, s49
	v_perm_b32 v7, v10, v7, s49
	v_perm_b32 v8, v12, v13, s49
	v_bfe_u32 v10, v57, 16, 1
	v_bfe_u32 v11, v56, 16, 1
	v_bfe_u32 v12, v49, 16, 1
	v_bfe_u32 v13, v48, 16, 1
	v_bfe_u32 v14, v41, 16, 1
	v_bfe_u32 v15, v40, 16, 1
	v_bfe_u32 v28, v65, 16, 1
	v_bfe_u32 v29, v64, 16, 1
	v_add3_u32 v15, v40, v15, s97
	v_add3_u32 v14, v41, v14, s97
	v_add3_u32 v13, v48, v13, s97
	v_add3_u32 v12, v49, v12, s97
	v_add3_u32 v11, v56, v11, s97
	v_add3_u32 v10, v57, v10, s97
	v_add3_u32 v29, v64, v29, s97
	v_add3_u32 v28, v65, v28, s97
	v_perm_b32 v11, v10, v11, s49
	v_perm_b32 v12, v12, v13, s49
	v_perm_b32 v13, v14, v15, s49
	v_perm_b32 v10, v28, v29, s49
	v_bfe_u32 v14, v33, 16, 1
	v_bfe_u32 v15, v32, 16, 1
	v_bfe_u32 v28, v25, 16, 1
	v_bfe_u32 v29, v24, 16, 1
	v_perm_b32 v9, v30, v31, s49
	v_bfe_u32 v30, v17, 16, 1
	v_bfe_u32 v31, v16, 16, 1
	v_bfe_u32 v34, v27, 16, 1
	v_bfe_u32 v35, v26, 16, 1
	v_add3_u32 v24, v24, v29, s97
	v_add3_u32 v25, v25, v28, s97
	v_add3_u32 v15, v32, v15, s97
	v_add3_u32 v14, v33, v14, s97
	v_add3_u32 v26, v26, v35, s97
	v_add3_u32 v27, v27, v34, s97
	v_add3_u32 v16, v16, v31, s97
	v_add3_u32 v17, v17, v30, s97
	v_perm_b32 v14, v14, v15, s49
	v_perm_b32 v15, v25, v24, s49
	v_lshl_add_u64 v[24:25], s[12:13], 0, v[18:19]
	v_perm_b32 v16, v17, v16, s49
	v_perm_b32 v17, v27, v26, s49
	v_lshl_add_u64 v[26:27], v[24:25], 0, s[30:31]
	v_add_co_u32_e32 v24, vcc, s28, v24
	s_nop 1
	v_addc_co_u32_e32 v25, vcc, 0, v25, vcc
	global_store_dwordx4 v[24:25], v[2:5], off
	global_store_dwordx4 v[26:27], v[6:9], off offset:256
	global_store_dwordx4 v[26:27], v[10:13], off offset:16
	global_store_dwordx4 v[26:27], v[14:17], off offset:272
	ds_read_b128 v[2:5], v75
	ds_read_b128 v[6:9], v75 offset:4352
	v_lshl_add_u64 v[14:15], s[12:13], 0, v[20:21]
	s_add_u32 s12, s12, 0x2000
	s_addc_u32 s13, s13, 0
	s_waitcnt lgkmcnt(1)
	global_store_dwordx4 v[14:15], v[2:5], off
	s_add_i32 s20, s20, s53
	s_cmpk_lt_i32 s20, 0x800
	s_waitcnt lgkmcnt(0)
	v_mfma_f32_16x16x32_bf16 v[2:5], v[2:5], v[6:9], 0
	ds_read_b128 v[6:9], v75 offset:64
	ds_read_b128 v[10:13], v75 offset:4416
	s_waitcnt lgkmcnt(1)
	global_store_dwordx4 v[14:15], v[6:9], off offset:1024
	s_waitcnt lgkmcnt(0)
	v_mfma_f32_16x16x32_bf16 v[2:5], v[6:9], v[10:13], v[2:5]
	ds_read_b128 v[6:9], v75 offset:128
	ds_read_b128 v[10:13], v75 offset:4480
	s_waitcnt lgkmcnt(1)
	global_store_dwordx4 v[14:15], v[6:9], off offset:2048
	s_waitcnt lgkmcnt(0)
	v_mfma_f32_16x16x32_bf16 v[2:5], v[6:9], v[10:13], v[2:5]
	ds_read_b128 v[6:9], v75 offset:192
	ds_read_b128 v[10:13], v75 offset:4544
	s_waitcnt lgkmcnt(1)
	global_store_dwordx4 v[14:15], v[6:9], off offset:3072
	s_waitcnt lgkmcnt(0)
	v_mfma_f32_16x16x32_bf16 v[2:5], v[6:9], v[10:13], v[2:5]
	s_nop 7
	v_bfe_u32 v6, v2, 16, 1
	v_add3_u32 v2, v2, v6, s97
	v_lshrrev_b32_e32 v2, 16, v2
	v_cndmask_b32_e64 v2, v2, 0, s[4:5]
	global_store_short v76, v2, s[12:13]
	v_bfe_u32 v2, v3, 16, 1
	v_add3_u32 v2, v3, v2, s97
	v_lshrrev_b32_e32 v2, 16, v2
	v_cndmask_b32_e64 v2, v2, 0, s[6:7]
	global_store_short v77, v2, s[12:13]
	v_bfe_u32 v2, v4, 16, 1
	v_add3_u32 v2, v4, v2, s97
	v_lshrrev_b32_e32 v2, 16, v2
	v_cndmask_b32_e64 v2, v2, 0, s[8:9]
	global_store_short v78, v2, s[12:13]
	v_bfe_u32 v2, v5, 16, 1
	v_add3_u32 v2, v5, v2, s97
	v_lshrrev_b32_e32 v2, 16, v2
	v_cndmask_b32_e64 v2, v2, 0, s[10:11]
	global_store_short v79, v2, s[12:13]
	s_cbranch_scc1 .LBB0_850

; #define tidx() tidx_(wv)
; __device__ __forceinline__ void headnorm_phase(KP p, int wv, const int seg, const int gw, const int nw) {
;   const int lane = tidx() & 63;
;   const int items = 2048 * 16;
;   for (int it = gw; it < items; it += nw) {
;     const int tl = it >> 4, grp = it & 15;
;     const int tok = (tl >> 10) * SEQ + seg * 1024 + (tl & 1023);
;     const int c = grp * 256 + lane * 4;
;     const float4 o = *(const float4*)(p->oraw + (long)tok * 4096 + c);
;     float ss = o.x * o.x + o.y * o.y + o.z * o.z + o.w * o.w;
;     ss = halfsum32(ss, lane);
;     const float rs = rsqrtf(ss * (1.f / 128.f) + 1e-6f);
;     const float4 w = *(const float4*)((grp < 8 ? p->hgrn_nw : p->gdn_nw) + (lane & 31) * 4);
;     const float4 g = (grp < 8) ? *(const float4*)(p->proj + (long)tok * PW + 6144 + c)
;                                : *(const float4*)(p->proj + (long)tok * PW + 12288 + (c - 2048));
;     u16x4 r;
;     r[0] = f2bf(o.x * rs * w.x * g.x); r[1] = f2bf(o.y * rs * w.y * g.y);
;     r[2] = f2bf(o.z * rs * w.z * g.z); r[3] = f2bf(o.w * rs * w.w * g.w);
;     *(u16x4*)(p->h + (long)tok * D + c) = r;
.Lhn_a_top:
	s_mul_i32 s20, s53, 6
	s_add_i32 s20, s20, s15
	s_cmp_lt_i32 s20, 0x8000
	s_cbranch_scc0 .Lhn_a_rem
	s_mov_b32 s19, s15
	s_ashr_i32 s12, s19, 2
	s_and_b32 s12, s12, 0xfffff000
	s_bfe_u32 s13, s19, 0xa0004
	s_add_i32 s12, s12, s14
	s_or_b32 s12, s12, s13
	s_ashr_i32 s13, s12, 31
	s_and_b32 s18, s19, 15
	v_lshl_or_b32 v159, s18, 8, v2
	v_lshlrev_b32_e32 v158, 2, v159
	s_lshl_b64 s[16:17], s[12:13], 14
	s_add_u32 s16, s10, s16
	s_addc_u32 s17, s11, s17
	global_load_dwordx4 v[148:151], v158, s[16:17]
	s_cmp_lt_u32 s18, 8
	s_cselect_b32 s18, s46, s2
	s_mul_i32 s16, s12, 0xe080
	s_mul_hi_i32 s17, s12, 0xe080
	s_add_u32 s16, s8, s16
	s_addc_u32 s17, s9, s17
	s_add_u32 s16, s16, s18
	s_addc_u32 s17, s17, 0
	global_load_dwordx4 v[152:155], v158, s[16:17] nt
	s_lshl_b64 s[12:13], s[12:13], 13
	s_add_u32 s12, s6, s12
	s_addc_u32 s13, s7, s13
	v_lshlrev_b32_e32 v156, 1, v159
	v_mov_b32_e32 v157, 0
	v_lshl_add_u64 v[156:157], s[12:13], 0, v[156:157]
	s_add_i32 s19, s19, s53
	s_ashr_i32 s12, s19, 2
	s_and_b32 s12, s12, 0xfffff000
	s_bfe_u32 s13, s19, 0xa0004
	s_add_i32 s12, s12, s14
	s_or_b32 s12, s12, s13
	s_ashr_i32 s13, s12, 31
	s_and_b32 s18, s19, 15
	v_lshl_or_b32 v171, s18, 8, v2
	v_lshlrev_b32_e32 v170, 2, v171
	s_lshl_b64 s[16:17], s[12:13], 14
	s_add_u32 s16, s10, s16
	s_addc_u32 s17, s11, s17
	global_load_dwordx4 v[160:163], v170, s[16:17]
	s_cmp_lt_u32 s18, 8
	s_cselect_b32 s18, s46, s2
	s_mul_i32 s16, s12, 0xe080
	s_mul_hi_i32 s17, s12, 0xe080
	s_add_u32 s16, s8, s16
	s_addc_u32 s17, s9, s17
	s_add_u32 s16, s16, s18
	s_addc_u32 s17, s17, 0
	global_load_dwordx4 v[164:167], v170, s[16:17] nt
	s_lshl_b64 s[12:13], s[12:13], 13
	s_add_u32 s12, s6, s12
	s_addc_u32 s13, s7, s13
	v_lshlrev_b32_e32 v168, 1, v171
	v_mov_b32_e32 v169, 0
	v_lshl_add_u64 v[168:169], s[12:13], 0, v[168:169]
	s_add_i32 s19, s19, s53
	s_ashr_i32 s12, s19, 2
	s_and_b32 s12, s12, 0xfffff000
	s_bfe_u32 s13, s19, 0xa0004
	s_add_i32 s12, s12, s14
	s_or_b32 s12, s12, s13
	s_ashr_i32 s13, s12, 31
	s_and_b32 s18, s19, 15
	v_lshl_or_b32 v183, s18, 8, v2
	v_lshlrev_b32_e32 v182, 2, v183
	s_lshl_b64 s[16:17], s[12:13], 14
	s_add_u32 s16, s10, s16
	s_addc_u32 s17, s11, s17
	global_load_dwordx4 v[172:175], v182, s[16:17]
	s_cmp_lt_u32 s18, 8
	s_cselect_b32 s18, s46, s2
	s_mul_i32 s16, s12, 0xe080
	s_mul_hi_i32 s17, s12, 0xe080
	s_add_u32 s16, s8, s16
	s_addc_u32 s17, s9, s17
	s_add_u32 s16, s16, s18
	s_addc_u32 s17, s17, 0
	global_load_dwordx4 v[176:179], v182, s[16:17] nt
	s_lshl_b64 s[12:13], s[12:13], 13
	s_add_u32 s12, s6, s12
	s_addc_u32 s13, s7, s13
	v_lshlrev_b32_e32 v180, 1, v183
	v_mov_b32_e32 v181, 0
	v_lshl_add_u64 v[180:181], s[12:13], 0, v[180:181]
	s_add_i32 s19, s19, s53
	s_ashr_i32 s12, s19, 2
	s_and_b32 s12, s12, 0xfffff000
	s_bfe_u32 s13, s19, 0xa0004
	s_add_i32 s12, s12, s14
	s_or_b32 s12, s12, s13
	s_ashr_i32 s13, s12, 31
	s_and_b32 s18, s19, 15
	v_lshl_or_b32 v195, s18, 8, v2
	v_lshlrev_b32_e32 v194, 2, v195
	s_lshl_b64 s[16:17], s[12:13], 14
	s_add_u32 s16, s10, s16
	s_addc_u32 s17, s11, s17
	global_load_dwordx4 v[184:187], v194, s[16:17]
	s_cmp_lt_u32 s18, 8
	s_cselect_b32 s18, s46, s2
	s_mul_i32 s16, s12, 0xe080
	s_mul_hi_i32 s17, s12, 0xe080
	s_add_u32 s16, s8, s16
	s_addc_u32 s17, s9, s17
	s_add_u32 s16, s16, s18
	s_addc_u32 s17, s17, 0
	global_load_dwordx4 v[188:191], v194, s[16:17] nt
	s_lshl_b64 s[12:13], s[12:13], 13
	s_add_u32 s12, s6, s12
	s_addc_u32 s13, s7, s13
	v_lshlrev_b32_e32 v192, 1, v195
	v_mov_b32_e32 v193, 0
	v_lshl_add_u64 v[192:193], s[12:13], 0, v[192:193]
	s_add_i32 s19, s19, s53
	s_ashr_i32 s12, s19, 2
	s_and_b32 s12, s12, 0xfffff000
	s_bfe_u32 s13, s19, 0xa0004
	s_add_i32 s12, s12, s14
	s_or_b32 s12, s12, s13
	s_ashr_i32 s13, s12, 31
	s_and_b32 s18, s19, 15
	v_lshl_or_b32 v207, s18, 8, v2
	v_lshlrev_b32_e32 v206, 2, v207
	s_lshl_b64 s[16:17], s[12:13], 14
	s_add_u32 s16, s10, s16
	s_addc_u32 s17, s11, s17
	global_load_dwordx4 v[196:199], v206, s[16:17]
	s_cmp_lt_u32 s18, 8
	s_cselect_b32 s18, s46, s2
	s_mul_i32 s16, s12, 0xe080
	s_mul_hi_i32 s17, s12, 0xe080
	s_add_u32 s16, s8, s16
	s_addc_u32 s17, s9, s17
	s_add_u32 s16, s16, s18
	s_addc_u32 s17, s17, 0
	global_load_dwordx4 v[200:203], v206, s[16:17] nt
	s_lshl_b64 s[12:13], s[12:13], 13
	s_add_u32 s12, s6, s12
	s_addc_u32 s13, s7, s13
	v_lshlrev_b32_e32 v204, 1, v207
	v_mov_b32_e32 v205, 0
	v_lshl_add_u64 v[204:205], s[12:13], 0, v[204:205]
	s_add_i32 s19, s19, s53
	s_ashr_i32 s12, s19, 2
	s_and_b32 s12, s12, 0xfffff000
	s_bfe_u32 s13, s19, 0xa0004
	s_add_i32 s12, s12, s14
	s_or_b32 s12, s12, s13
	s_ashr_i32 s13, s12, 31
	s_and_b32 s18, s19, 15
	v_lshl_or_b32 v219, s18, 8, v2
	v_lshlrev_b32_e32 v218, 2, v219
	s_lshl_b64 s[16:17], s[12:13], 14
	s_add_u32 s16, s10, s16
	s_addc_u32 s17, s11, s17
	global_load_dwordx4 v[208:211], v218, s[16:17]
	s_cmp_lt_u32 s18, 8
	s_cselect_b32 s18, s46, s2
	s_mul_i32 s16, s12, 0xe080
	s_mul_hi_i32 s17, s12, 0xe080
	s_add_u32 s16, s8, s16
	s_addc_u32 s17, s9, s17
	s_add_u32 s16, s16, s18
	s_addc_u32 s17, s17, 0
	global_load_dwordx4 v[212:215], v218, s[16:17] nt
	s_lshl_b64 s[12:13], s[12:13], 13
	s_add_u32 s12, s6, s12
	s_addc_u32 s13, s7, s13
	v_lshlrev_b32_e32 v216, 1, v219
	v_mov_b32_e32 v217, 0
	v_lshl_add_u64 v[216:217], s[12:13], 0, v[216:217]
	s_add_i32 s19, s19, s53
	s_ashr_i32 s12, s19, 2
	s_and_b32 s12, s12, 0xfffff000
	s_bfe_u32 s13, s19, 0xa0004
	s_add_i32 s12, s12, s14
	s_or_b32 s12, s12, s13
	s_ashr_i32 s13, s12, 31
	s_and_b32 s18, s19, 15
	v_lshl_or_b32 v231, s18, 8, v2
	v_lshlrev_b32_e32 v230, 2, v231
	s_lshl_b64 s[16:17], s[12:13], 14
	s_add_u32 s16, s10, s16
	s_addc_u32 s17, s11, s17
	global_load_dwordx4 v[220:223], v230, s[16:17]
	s_cmp_lt_u32 s18, 8
	s_cselect_b32 s18, s46, s2
	s_mul_i32 s16, s12, 0xe080
	s_mul_hi_i32 s17, s12, 0xe080
	s_add_u32 s16, s8, s16
	s_addc_u32 s17, s9, s17
	s_add_u32 s16, s16, s18
	s_addc_u32 s17, s17, 0
	global_load_dwordx4 v[224:227], v230, s[16:17] nt
	s_lshl_b64 s[12:13], s[12:13], 13
	s_add_u32 s12, s6, s12
	s_addc_u32 s13, s7, s13
	v_lshlrev_b32_e32 v228, 1, v231
	v_mov_b32_e32 v229, 0
	v_lshl_add_u64 v[228:229], s[12:13], 0, v[228:229]
	s_add_i32 s19, s19, s53
	s_waitcnt vmcnt(13)
; __device__ __forceinline__ void headnorm_phase(KP p, int wv, const int seg, const int gw, const int nw) {
;     ...
;   for (int it = gw; it < items; it += nw) {
;     const int tl = it >> 4, grp = it & 15;
;     const int tok = (tl >> 10) * SEQ + seg * 1024 + (tl & 1023);
;     const int c = grp * 256 + lane * 4;
;     const float4 o = *(const float4*)(p->oraw + (long)tok * 4096 + c);
;     float ss = o.x * o.x + o.y * o.y + o.z * o.z + o.w * o.w;
;     ss = halfsum32(ss, lane);
;     const float rs = rsqrtf(ss * (1.f / 128.f) + 1e-6f);
;     const float4 w = *(const float4*)((grp < 8 ? p->hgrn_nw : p->gdn_nw) + (lane & 31) * 4);
;     const float4 g = (grp < 8) ? *(const float4*)(p->proj + (long)tok * PW + 6144 + c)
;                                : *(const float4*)(p->proj + (long)tok * PW + 12288 + (c - 2048));
;     u16x4 r;
;     r[0] = f2bf(o.x * rs * w.x * g.x); r[1] = f2bf(o.y * rs * w.y * g.y);
;     r[2] = f2bf(o.z * rs * w.z * g.z); r[3] = f2bf(o.w * rs * w.w * g.w);
;     *(u16x4*)(p->h + (long)tok * D + c) = r;
	v_pk_mul_f32 v[232:233], v[148:149], v[148:149]
	v_pk_mul_f32 v[234:235], v[150:151], v[150:151]
	v_add_f32_e32 v158, v232, v233
	v_add_f32_e32 v158, v158, v234
	v_add_f32_e32 v158, v158, v235
	s_waitcnt vmcnt(11)
	v_pk_mul_f32 v[232:233], v[160:161], v[160:161]
	v_pk_mul_f32 v[234:235], v[162:163], v[162:163]
	v_add_f32_e32 v170, v232, v233
	v_add_f32_e32 v170, v170, v234
	v_add_f32_e32 v170, v170, v235
	s_waitcnt vmcnt(9)
	v_pk_mul_f32 v[232:233], v[172:173], v[172:173]
	v_pk_mul_f32 v[234:235], v[174:175], v[174:175]
	v_add_f32_e32 v182, v232, v233
	v_add_f32_e32 v182, v182, v234
	v_add_f32_e32 v182, v182, v235
	s_waitcnt vmcnt(7)
	v_pk_mul_f32 v[232:233], v[184:185], v[184:185]
	v_pk_mul_f32 v[234:235], v[186:187], v[186:187]
	v_add_f32_e32 v194, v232, v233
	v_add_f32_e32 v194, v194, v234
	v_add_f32_e32 v194, v194, v235
	s_waitcnt vmcnt(5)
	v_pk_mul_f32 v[232:233], v[196:197], v[196:197]
	v_pk_mul_f32 v[234:235], v[198:199], v[198:199]
	v_add_f32_e32 v206, v232, v233
	v_add_f32_e32 v206, v206, v234
	v_add_f32_e32 v206, v206, v235
	s_waitcnt vmcnt(3)
	v_pk_mul_f32 v[232:233], v[208:209], v[208:209]
	v_pk_mul_f32 v[234:235], v[210:211], v[210:211]
	v_add_f32_e32 v218, v232, v233
	v_add_f32_e32 v218, v218, v234
	v_add_f32_e32 v218, v218, v235
	s_waitcnt vmcnt(1)
	v_pk_mul_f32 v[232:233], v[220:221], v[220:221]
	v_pk_mul_f32 v[234:235], v[222:223], v[222:223]
	v_add_f32_e32 v230, v232, v233
	v_add_f32_e32 v230, v230, v234
	v_add_f32_e32 v230, v230, v235
	ds_bpermute_b32 v159, v3, v158
	ds_bpermute_b32 v171, v3, v170
	ds_bpermute_b32 v183, v3, v182
	ds_bpermute_b32 v195, v3, v194
	ds_bpermute_b32 v207, v3, v206
	ds_bpermute_b32 v219, v3, v218
	ds_bpermute_b32 v231, v3, v230
	s_waitcnt lgkmcnt(0)
	v_add_f32_e32 v158, v158, v159
	v_add_f32_e32 v170, v170, v171
	v_add_f32_e32 v182, v182, v183
	v_add_f32_e32 v194, v194, v195
	v_add_f32_e32 v206, v206, v207
	v_add_f32_e32 v218, v218, v219
	v_add_f32_e32 v230, v230, v231
	ds_bpermute_b32 v159, v4, v158
	ds_bpermute_b32 v171, v4, v170
	ds_bpermute_b32 v183, v4, v182
	ds_bpermute_b32 v195, v4, v194
	ds_bpermute_b32 v207, v4, v206
	ds_bpermute_b32 v219, v4, v218
	ds_bpermute_b32 v231, v4, v230
	s_waitcnt lgkmcnt(0)
	v_add_f32_e32 v158, v158, v159
	v_add_f32_e32 v170, v170, v171
	v_add_f32_e32 v182, v182, v183
	v_add_f32_e32 v194, v194, v195
	v_add_f32_e32 v206, v206, v207
	v_add_f32_e32 v218, v218, v219
	v_add_f32_e32 v230, v230, v231
	ds_bpermute_b32 v159, v5, v158
	ds_bpermute_b32 v171, v5, v170
	ds_bpermute_b32 v183, v5, v182
	ds_bpermute_b32 v195, v5, v194
	ds_bpermute_b32 v207, v5, v206
	ds_bpermute_b32 v219, v5, v218
	ds_bpermute_b32 v231, v5, v230
	s_waitcnt lgkmcnt(0)
	v_add_f32_e32 v158, v158, v159
	v_add_f32_e32 v170, v170, v171
	v_add_f32_e32 v182, v182, v183
	v_add_f32_e32 v194, v194, v195
	v_add_f32_e32 v206, v206, v207
	v_add_f32_e32 v218, v218, v219
	v_add_f32_e32 v230, v230, v231
	ds_bpermute_b32 v159, v6, v158
	ds_bpermute_b32 v171, v6, v170
	ds_bpermute_b32 v183, v6, v182
	ds_bpermute_b32 v195, v6, v194
	ds_bpermute_b32 v207, v6, v206
	ds_bpermute_b32 v219, v6, v218
	ds_bpermute_b32 v231, v6, v230
	s_waitcnt lgkmcnt(0)
	v_add_f32_e32 v158, v158, v159
	v_add_f32_e32 v170, v170, v171
	v_add_f32_e32 v182, v182, v183
	v_add_f32_e32 v194, v194, v195
	v_add_f32_e32 v206, v206, v207
	v_add_f32_e32 v218, v218, v219
	v_add_f32_e32 v230, v230, v231
	ds_bpermute_b32 v159, v7, v158
	ds_bpermute_b32 v171, v7, v170
	ds_bpermute_b32 v183, v7, v182
	ds_bpermute_b32 v195, v7, v194
	ds_bpermute_b32 v207, v7, v206
	ds_bpermute_b32 v219, v7, v218
	ds_bpermute_b32 v231, v7, v230
	s_waitcnt lgkmcnt(0)
	v_add_f32_e32 v158, v158, v159
	v_add_f32_e32 v170, v170, v171
	v_add_f32_e32 v182, v182, v183
	v_add_f32_e32 v194, v194, v195
	v_add_f32_e32 v206, v206, v207
	v_add_f32_e32 v218, v218, v219
	v_add_f32_e32 v230, v230, v231
	s_waitcnt vmcnt(0)
	s_mov_b32 s19, s15
	v_fmamk_f32 v158, v158, 0x3c000000, v103
	v_mul_f32_e32 v232, 0x4b800000, v158
	v_cmp_gt_f32_e32 vcc, s38, v158
	s_nop 1
	v_cndmask_b32_e32 v158, v158, v232, vcc
	v_rsq_f32_e32 v158, v158
	s_nop 0
	v_mul_f32_e32 v232, 0x45800000, v158
	v_cndmask_b32_e32 v158, v158, v232, vcc
	v_pk_mul_f32 v[148:149], v[148:149], v[158:159] op_sel_hi:[1,0]
	v_pk_mul_f32 v[150:151], v[150:151], v[158:159] op_sel_hi:[1,0]
	s_and_b32 s18, s19, 15
	s_cmp_lt_u32 s18, 8
	s_cselect_b64 vcc, -1, 0
	s_add_i32 s19, s19, s53
	s_nop 1
	v_cndmask_b32_e32 v244, v240, v236, vcc
	v_cndmask_b32_e32 v245, v241, v237, vcc
	v_cndmask_b32_e32 v246, v242, v238, vcc
	v_cndmask_b32_e32 v247, v243, v239, vcc
	v_pk_mul_f32 v[148:149], v[244:245], v[148:149]
	v_pk_mul_f32 v[150:151], v[246:247], v[150:151]
	v_pk_mul_f32 v[148:149], v[152:153], v[148:149]
	v_pk_mul_f32 v[150:151], v[154:155], v[150:151]
	v_bfe_u32 v232, v148, 16, 1
	v_bfe_u32 v233, v149, 16, 1
	v_bfe_u32 v234, v150, 16, 1
	v_bfe_u32 v235, v151, 16, 1
	v_add3_u32 v148, v148, v232, s97
	v_add3_u32 v149, v149, v233, s97
	v_add3_u32 v150, v150, v234, s97
	v_add3_u32 v151, v151, v235, s97
	v_perm_b32 v148, v149, v148, s49
	v_perm_b32 v149, v151, v150, s49
	global_store_dwordx2 v[156:157], v[148:149], off nt
	v_fmamk_f32 v170, v170, 0x3c000000, v103
	v_mul_f32_e32 v232, 0x4b800000, v170
	v_cmp_gt_f32_e32 vcc, s38, v170
	s_nop 1
	v_cndmask_b32_e32 v170, v170, v232, vcc
	v_rsq_f32_e32 v170, v170
	s_nop 0
	v_mul_f32_e32 v232, 0x45800000, v170
	v_cndmask_b32_e32 v170, v170, v232, vcc
	v_pk_mul_f32 v[160:161], v[160:161], v[170:171] op_sel_hi:[1,0]
	v_pk_mul_f32 v[162:163], v[162:163], v[170:171] op_sel_hi:[1,0]
	s_and_b32 s18, s19, 15
	s_cmp_lt_u32 s18, 8
	s_cselect_b64 vcc, -1, 0
	s_add_i32 s19, s19, s53
	s_nop 1
; __device__ __forceinline__ void headnorm_phase(KP p, int wv, const int seg, const int gw, const int nw) {
;     ...
;     const float rs = rsqrtf(ss * (1.f / 128.f) + 1e-6f);
;     const float4 w = *(const float4*)((grp < 8 ? p->hgrn_nw : p->gdn_nw) + (lane & 31) * 4);
;     const float4 g = (grp < 8) ? *(const float4*)(p->proj + (long)tok * PW + 6144 + c)
;                                : *(const float4*)(p->proj + (long)tok * PW + 12288 + (c - 2048));
;     u16x4 r;
;     r[0] = f2bf(o.x * rs * w.x * g.x); r[1] = f2bf(o.y * rs * w.y * g.y);
;     r[2] = f2bf(o.z * rs * w.z * g.z); r[3] = f2bf(o.w * rs * w.w * g.w);
;     *(u16x4*)(p->h + (long)tok * D + c) = r;
	v_cndmask_b32_e32 v244, v240, v236, vcc
	v_cndmask_b32_e32 v245, v241, v237, vcc
	v_cndmask_b32_e32 v246, v242, v238, vcc
	v_cndmask_b32_e32 v247, v243, v239, vcc
	v_pk_mul_f32 v[160:161], v[244:245], v[160:161]
	v_pk_mul_f32 v[162:163], v[246:247], v[162:163]
	v_pk_mul_f32 v[160:161], v[164:165], v[160:161]
	v_pk_mul_f32 v[162:163], v[166:167], v[162:163]
	v_bfe_u32 v232, v160, 16, 1
	v_bfe_u32 v233, v161, 16, 1
	v_bfe_u32 v234, v162, 16, 1
	v_bfe_u32 v235, v163, 16, 1
	v_add3_u32 v160, v160, v232, s97
	v_add3_u32 v161, v161, v233, s97
	v_add3_u32 v162, v162, v234, s97
	v_add3_u32 v163, v163, v235, s97
	v_perm_b32 v160, v161, v160, s49
	v_perm_b32 v161, v163, v162, s49
	global_store_dwordx2 v[168:169], v[160:161], off nt
	v_fmamk_f32 v182, v182, 0x3c000000, v103
	v_mul_f32_e32 v232, 0x4b800000, v182
	v_cmp_gt_f32_e32 vcc, s38, v182
	s_nop 1
	v_cndmask_b32_e32 v182, v182, v232, vcc
	v_rsq_f32_e32 v182, v182
	s_nop 0
	v_mul_f32_e32 v232, 0x45800000, v182
	v_cndmask_b32_e32 v182, v182, v232, vcc
	v_pk_mul_f32 v[172:173], v[172:173], v[182:183] op_sel_hi:[1,0]
	v_pk_mul_f32 v[174:175], v[174:175], v[182:183] op_sel_hi:[1,0]
	s_and_b32 s18, s19, 15
	s_cmp_lt_u32 s18, 8
	s_cselect_b64 vcc, -1, 0
	s_add_i32 s19, s19, s53
	s_nop 1
	v_cndmask_b32_e32 v244, v240, v236, vcc
	v_cndmask_b32_e32 v245, v241, v237, vcc
	v_cndmask_b32_e32 v246, v242, v238, vcc
	v_cndmask_b32_e32 v247, v243, v239, vcc
	v_pk_mul_f32 v[172:173], v[244:245], v[172:173]
	v_pk_mul_f32 v[174:175], v[246:247], v[174:175]
	v_pk_mul_f32 v[172:173], v[176:177], v[172:173]
	v_pk_mul_f32 v[174:175], v[178:179], v[174:175]
	v_bfe_u32 v232, v172, 16, 1
	v_bfe_u32 v233, v173, 16, 1
	v_bfe_u32 v234, v174, 16, 1
	v_bfe_u32 v235, v175, 16, 1
	v_add3_u32 v172, v172, v232, s97
	v_add3_u32 v173, v173, v233, s97
	v_add3_u32 v174, v174, v234, s97
	v_add3_u32 v175, v175, v235, s97
	v_perm_b32 v172, v173, v172, s49
	v_perm_b32 v173, v175, v174, s49
	global_store_dwordx2 v[180:181], v[172:173], off nt
	v_fmamk_f32 v194, v194, 0x3c000000, v103
	v_mul_f32_e32 v232, 0x4b800000, v194
	v_cmp_gt_f32_e32 vcc, s38, v194
	s_nop 1
	v_cndmask_b32_e32 v194, v194, v232, vcc
	v_rsq_f32_e32 v194, v194
	s_nop 0
	v_mul_f32_e32 v232, 0x45800000, v194
	v_cndmask_b32_e32 v194, v194, v232, vcc
	v_pk_mul_f32 v[184:185], v[184:185], v[194:195] op_sel_hi:[1,0]
	v_pk_mul_f32 v[186:187], v[186:187], v[194:195] op_sel_hi:[1,0]
	s_and_b32 s18, s19, 15
	s_cmp_lt_u32 s18, 8
	s_cselect_b64 vcc, -1, 0
	s_add_i32 s19, s19, s53
	s_nop 1
	v_cndmask_b32_e32 v244, v240, v236, vcc
	v_cndmask_b32_e32 v245, v241, v237, vcc
	v_cndmask_b32_e32 v246, v242, v238, vcc
	v_cndmask_b32_e32 v247, v243, v239, vcc
	v_pk_mul_f32 v[184:185], v[244:245], v[184:185]
	v_pk_mul_f32 v[186:187], v[246:247], v[186:187]
	v_pk_mul_f32 v[184:185], v[188:189], v[184:185]
	v_pk_mul_f32 v[186:187], v[190:191], v[186:187]
	v_bfe_u32 v232, v184, 16, 1
	v_bfe_u32 v233, v185, 16, 1
	v_bfe_u32 v234, v186, 16, 1
	v_bfe_u32 v235, v187, 16, 1
	v_add3_u32 v184, v184, v232, s97
	v_add3_u32 v185, v185, v233, s97
	v_add3_u32 v186, v186, v234, s97
	v_add3_u32 v187, v187, v235, s97
	v_perm_b32 v184, v185, v184, s49
	v_perm_b32 v185, v187, v186, s49
	global_store_dwordx2 v[192:193], v[184:185], off nt
	v_fmamk_f32 v206, v206, 0x3c000000, v103
	v_mul_f32_e32 v232, 0x4b800000, v206
	v_cmp_gt_f32_e32 vcc, s38, v206
	s_nop 1
	v_cndmask_b32_e32 v206, v206, v232, vcc
	v_rsq_f32_e32 v206, v206
	s_nop 0
	v_mul_f32_e32 v232, 0x45800000, v206
	v_cndmask_b32_e32 v206, v206, v232, vcc
	v_pk_mul_f32 v[196:197], v[196:197], v[206:207] op_sel_hi:[1,0]
	v_pk_mul_f32 v[198:199], v[198:199], v[206:207] op_sel_hi:[1,0]
	s_and_b32 s18, s19, 15
	s_cmp_lt_u32 s18, 8
	s_cselect_b64 vcc, -1, 0
	s_add_i32 s19, s19, s53
	s_nop 1
	v_cndmask_b32_e32 v244, v240, v236, vcc
	v_cndmask_b32_e32 v245, v241, v237, vcc
	v_cndmask_b32_e32 v246, v242, v238, vcc
	v_cndmask_b32_e32 v247, v243, v239, vcc
	v_pk_mul_f32 v[196:197], v[244:245], v[196:197]
	v_pk_mul_f32 v[198:199], v[246:247], v[198:199]
	v_pk_mul_f32 v[196:197], v[200:201], v[196:197]
	v_pk_mul_f32 v[198:199], v[202:203], v[198:199]
	v_bfe_u32 v232, v196, 16, 1
	v_bfe_u32 v233, v197, 16, 1
	v_bfe_u32 v234, v198, 16, 1
	v_bfe_u32 v235, v199, 16, 1
	v_add3_u32 v196, v196, v232, s97
	v_add3_u32 v197, v197, v233, s97
	v_add3_u32 v198, v198, v234, s97
	v_add3_u32 v199, v199, v235, s97
	v_perm_b32 v196, v197, v196, s49
	v_perm_b32 v197, v199, v198, s49
	global_store_dwordx2 v[204:205], v[196:197], off nt
	v_fmamk_f32 v218, v218, 0x3c000000, v103
	v_mul_f32_e32 v232, 0x4b800000, v218
	v_cmp_gt_f32_e32 vcc, s38, v218
	s_nop 1
	v_cndmask_b32_e32 v218, v218, v232, vcc
	v_rsq_f32_e32 v218, v218
	s_nop 0
	v_mul_f32_e32 v232, 0x45800000, v218
	v_cndmask_b32_e32 v218, v218, v232, vcc
	v_pk_mul_f32 v[208:209], v[208:209], v[218:219] op_sel_hi:[1,0]
	v_pk_mul_f32 v[210:211], v[210:211], v[218:219] op_sel_hi:[1,0]
	s_and_b32 s18, s19, 15
	s_cmp_lt_u32 s18, 8
	s_cselect_b64 vcc, -1, 0
	s_add_i32 s19, s19, s53
	s_nop 1
	v_cndmask_b32_e32 v244, v240, v236, vcc
	v_cndmask_b32_e32 v245, v241, v237, vcc
	v_cndmask_b32_e32 v246, v242, v238, vcc
	v_cndmask_b32_e32 v247, v243, v239, vcc
	v_pk_mul_f32 v[208:209], v[244:245], v[208:209]
	v_pk_mul_f32 v[210:211], v[246:247], v[210:211]
	v_pk_mul_f32 v[208:209], v[212:213], v[208:209]
	v_pk_mul_f32 v[210:211], v[214:215], v[210:211]
	v_bfe_u32 v232, v208, 16, 1
	v_bfe_u32 v233, v209, 16, 1
	v_bfe_u32 v234, v210, 16, 1
	v_bfe_u32 v235, v211, 16, 1
	v_add3_u32 v208, v208, v232, s97
	v_add3_u32 v209, v209, v233, s97
	v_add3_u32 v210, v210, v234, s97
	v_add3_u32 v211, v211, v235, s97
	v_perm_b32 v208, v209, v208, s49
	v_perm_b32 v209, v211, v210, s49
	global_store_dwordx2 v[216:217], v[208:209], off nt
	v_fmamk_f32 v230, v230, 0x3c000000, v103
	v_mul_f32_e32 v232, 0x4b800000, v230
	v_cmp_gt_f32_e32 vcc, s38, v230
	s_nop 1
	v_cndmask_b32_e32 v230, v230, v232, vcc
	v_rsq_f32_e32 v230, v230
	s_nop 0
	v_mul_f32_e32 v232, 0x45800000, v230
	v_cndmask_b32_e32 v230, v230, v232, vcc
	v_pk_mul_f32 v[220:221], v[220:221], v[230:231] op_sel_hi:[1,0]
	v_pk_mul_f32 v[222:223], v[222:223], v[230:231] op_sel_hi:[1,0]
	s_and_b32 s18, s19, 15
	s_cmp_lt_u32 s18, 8
	s_cselect_b64 vcc, -1, 0
	s_add_i32 s19, s19, s53
	s_nop 1
	v_cndmask_b32_e32 v244, v240, v236, vcc
	v_cndmask_b32_e32 v245, v241, v237, vcc
	v_cndmask_b32_e32 v246, v242, v238, vcc
	v_cndmask_b32_e32 v247, v243, v239, vcc
	v_pk_mul_f32 v[220:221], v[244:245], v[220:221]
	v_pk_mul_f32 v[222:223], v[246:247], v[222:223]
	v_pk_mul_f32 v[220:221], v[224:225], v[220:221]
	v_pk_mul_f32 v[222:223], v[226:227], v[222:223]
	v_bfe_u32 v232, v220, 16, 1
	v_bfe_u32 v233, v221, 16, 1
	v_bfe_u32 v234, v222, 16, 1
	v_bfe_u32 v235, v223, 16, 1
	v_add3_u32 v220, v220, v232, s97
	v_add3_u32 v221, v221, v233, s97
	v_add3_u32 v222, v222, v234, s97
	v_add3_u32 v223, v223, v235, s97
	v_perm_b32 v220, v221, v220, s49
	v_perm_b32 v221, v223, v222, s49
	global_store_dwordx2 v[228:229], v[220:221], off nt
	s_mov_b32 s15, s19
	s_branch .Lhn_a_top

; __device__ __forceinline__ void side_load(const SideJob& jb, float4 (&v)[8], const int lane) {
;   const int r8 = lane >> 3, c4 = (lane & 7) * 4;
; #pragma unroll
;   for (int i = 0; i < 8; ++i) v[i] = *(const float4*)(jb.W + (long)(jb.k0 + i * 8 + r8) * jb.N + jb.n0 + c4);
; }
; __device__ __forceinline__ void side_transpose(KP p, char* smem, int bid, int nb, int wv, const int part) {
;     ...
;   SideJob cur = side_job(p, j);
;   float4 va[8], vb[8];
;   side_load(cur, va, lane);
;   for (;;) {
;     const int jn = j + stride;
;     const bool more = jn < tot;
;     SideJob nxt = cur;
;     if (more) { nxt = side_job(p, jn); side_load(nxt, vb, lane); }
.Ld2_BB0_1033:
	s_load_dwordx2 s[10:11], s[10:11], 0x0
	v_bfe_u32 v68, v10, 3, 3
	v_lshlrev_b32_e32 v0, 2, v10
	v_or_b32_e32 v69, 8, v68
	v_or_b32_e32 v70, 16, v68
	v_and_b32_e32 v12, 28, v0
	v_add_u32_e32 v0, s4, v68
	v_add_u32_e32 v4, s4, v69
	v_add_u32_e32 v11, s4, v70
	v_or_b32_e32 v71, 24, v68
	v_mad_i64_i32 v[2:3], s[12:13], s8, v0, 0
	v_mad_i64_i32 v[4:5], s[16:17], s8, v4, 0
	v_mad_i64_i32 v[14:15], s[16:17], s8, v11, 0
	v_add_u32_e32 v11, s4, v71
	s_waitcnt lgkmcnt(0)
	v_lshl_add_u64 v[2:3], v[2:3], 2, s[10:11]
	s_lshl_b64 s[12:13], s[42:43], 2
	v_lshl_add_u64 v[4:5], v[4:5], 2, s[10:11]
	v_lshl_add_u64 v[14:15], v[14:15], 2, s[10:11]
	v_mad_i64_i32 v[16:17], s[16:17], s8, v11, 0
	v_lshl_add_u64 v[2:3], v[2:3], 0, s[12:13]
	v_lshlrev_b32_e32 v0, 2, v12
	v_lshl_add_u64 v[4:5], v[4:5], 0, s[12:13]
	v_lshl_add_u64 v[14:15], v[14:15], 0, s[12:13]
	v_lshl_add_u64 v[16:17], v[16:17], 2, s[10:11]
	v_or_b32_e32 v72, 32, v68
	v_lshl_add_u64 v[2:3], v[2:3], 0, v[0:1]
	v_lshl_add_u64 v[6:7], v[4:5], 0, v[0:1]
	v_lshl_add_u64 v[14:15], v[14:15], 0, v[0:1]
	v_lshl_add_u64 v[16:17], v[16:17], 0, s[12:13]
	v_add_u32_e32 v11, s4, v72
	v_or_b32_e32 v73, 40, v68
	global_load_dwordx4 v[2:5], v[2:3], off nt
	s_nop 0
	global_load_dwordx4 v[6:9], v[6:7], off nt
	v_lshl_add_u64 v[16:17], v[16:17], 0, v[0:1]
	global_load_dwordx4 v[18:21], v[14:15], off nt
	global_load_dwordx4 v[22:25], v[16:17], off nt
	v_mad_i64_i32 v[14:15], s[16:17], s8, v11, 0
	v_add_u32_e32 v11, s4, v73
	v_lshl_add_u64 v[14:15], v[14:15], 2, s[10:11]
	v_mad_i64_i32 v[16:17], s[16:17], s8, v11, 0
	v_lshl_add_u64 v[14:15], v[14:15], 0, s[12:13]
	v_lshl_add_u64 v[16:17], v[16:17], 2, s[10:11]
	v_or_b32_e32 v74, 48, v68
	v_lshl_add_u64 v[14:15], v[14:15], 0, v[0:1]
	v_lshl_add_u64 v[16:17], v[16:17], 0, s[12:13]
	v_add_u32_e32 v11, s4, v74
	v_or_b32_e32 v75, 56, v68
	v_lshl_add_u64 v[16:17], v[16:17], 0, v[0:1]
	global_load_dwordx4 v[30:33], v[14:15], off nt
	global_load_dwordx4 v[34:37], v[16:17], off nt
	v_mad_i64_i32 v[14:15], s[16:17], s8, v11, 0
	v_add_u32_e32 v11, s4, v75
	v_lshl_add_u64 v[14:15], v[14:15], 2, s[10:11]
	v_mad_i64_i32 v[16:17], s[8:9], s8, v11, 0
	v_lshl_add_u64 v[14:15], v[14:15], 0, s[12:13]
	v_lshl_add_u64 v[16:17], v[16:17], 2, s[10:11]
	v_lshl_add_u64 v[14:15], v[14:15], 0, v[0:1]
	v_lshl_add_u64 v[16:17], v[16:17], 0, s[12:13]
	v_lshl_add_u64 v[16:17], v[16:17], 0, v[0:1]
	global_load_dwordx4 v[42:45], v[14:15], off nt
	global_load_dwordx4 v[46:49], v[16:17], off nt
	s_add_u32 s8, s14, 0x58
	s_addc_u32 s9, s15, 0
	s_load_dwordx2 s[6:7], s[6:7], 0x0
	s_add_u32 s10, s14, 0x98
	s_addc_u32 s11, s15, 0
	s_add_u32 s12, s14, 0x48
	v_and_b32_e32 v0, 7, v10
	v_readlane_b32 s5, v253, 13
	s_addc_u32 s13, s15, 0
	v_mul_u32_u24_e32 v13, 0x84, v68
	v_lshl_add_u32 v11, v0, 4, s5
	v_lshlrev_b32_e32 v10, 3, v0
	v_mul_u32_u24_e32 v0, 0x420, v0
	v_lshlrev_b32_e32 v14, 2, v68
	s_add_u32 s14, s14, 0x90
	v_add3_u32 v76, s5, v0, v14
	s_addc_u32 s15, s15, 0
	v_lshlrev_b32_e32 v0, 2, v12
	v_add_u32_e32 v77, v11, v13
	v_lshlrev_b32_e32 v66, 1, v10
	v_readlane_b32 s28, v253, 31
	s_mov_b32 s29, s42
	s_waitcnt lgkmcnt(0)
	s_mov_b64 s[18:19], s[6:7]
	s_branch .Ld2_BB0_1036
.Ld2_BB0_1034:
	s_load_dwordx2 s[22:23], s[22:23], 0x0
	v_add_u32_e32 v10, s30, v68
	v_add_u32_e32 v12, s30, v69
	v_add_u32_e32 v26, s30, v70
	v_add_u32_e32 v28, s30, v71
	v_add_u32_e32 v50, s30, v72
	v_add_u32_e32 v52, s30, v73
	v_add_u32_e32 v58, s30, v74
	v_add_u32_e32 v60, s30, v75
	v_mad_i64_i32 v[10:11], s[36:37], s20, v10, 0
	v_mad_i64_i32 v[12:13], s[36:37], s20, v12, 0
	v_mad_i64_i32 v[26:27], s[36:37], s20, v26, 0
	v_mad_i64_i32 v[28:29], s[36:37], s20, v28, 0
	v_mad_i64_i32 v[50:51], s[36:37], s20, v50, 0
	v_mad_i64_i32 v[52:53], s[36:37], s20, v52, 0
	v_mad_i64_i32 v[58:59], s[36:37], s20, v58, 0
	v_mad_i64_i32 v[60:61], s[20:21], s20, v60, 0
	s_lshl_b64 s[24:25], s[42:43], 2
	s_waitcnt lgkmcnt(0)
	v_lshl_add_u64 v[10:11], v[10:11], 2, s[22:23]
	v_lshl_add_u64 v[12:13], v[12:13], 2, s[22:23]
	v_lshl_add_u64 v[26:27], v[26:27], 2, s[22:23]
	v_lshl_add_u64 v[28:29], v[28:29], 2, s[22:23]
	v_lshl_add_u64 v[50:51], v[50:51], 2, s[22:23]
	v_lshl_add_u64 v[52:53], v[52:53], 2, s[22:23]
	v_lshl_add_u64 v[58:59], v[58:59], 2, s[22:23]
	v_lshl_add_u64 v[60:61], v[60:61], 2, s[22:23]
	v_lshl_add_u64 v[10:11], v[10:11], 0, s[24:25]
	v_lshl_add_u64 v[12:13], v[12:13], 0, s[24:25]
	v_lshl_add_u64 v[26:27], v[26:27], 0, s[24:25]
	v_lshl_add_u64 v[28:29], v[28:29], 0, s[24:25]
	v_lshl_add_u64 v[50:51], v[50:51], 0, s[24:25]
	v_lshl_add_u64 v[52:53], v[52:53], 0, s[24:25]
	v_lshl_add_u64 v[58:59], v[58:59], 0, s[24:25]
	v_lshl_add_u64 v[60:61], v[60:61], 0, s[24:25]
	v_lshl_add_u64 v[10:11], v[10:11], 0, v[0:1]
	v_lshl_add_u64 v[14:15], v[12:13], 0, v[0:1]
	v_lshl_add_u64 v[26:27], v[26:27], 0, v[0:1]
	v_lshl_add_u64 v[38:39], v[28:29], 0, v[0:1]
	v_lshl_add_u64 v[50:51], v[50:51], 0, v[0:1]
	v_lshl_add_u64 v[54:55], v[52:53], 0, v[0:1]
	v_lshl_add_u64 v[58:59], v[58:59], 0, v[0:1]
	v_lshl_add_u64 v[62:63], v[60:61], 0, v[0:1]
	global_load_dwordx4 v[10:13], v[10:11], off nt
	s_nop 0
	global_load_dwordx4 v[14:17], v[14:15], off nt
	s_nop 0
	global_load_dwordx4 v[26:29], v[26:27], off nt
	s_nop 0
	global_load_dwordx4 v[38:41], v[38:39], off nt
	s_nop 0
	global_load_dwordx4 v[50:53], v[50:51], off nt
	s_nop 0
	global_load_dwordx4 v[54:57], v[54:55], off nt
	s_nop 0
	global_load_dwordx4 v[58:61], v[58:59], off nt
	s_nop 0
	global_load_dwordx4 v[62:65], v[62:63], off nt
	s_load_dwordx2 s[18:19], s[18:19], 0x0
	v_readlane_b32 s36, v253, 14
	v_readlane_b32 s37, v253, 15
	s_waitcnt vmcnt(8)
	s_branch .Ld2_st_body_b

; __device__ __forceinline__ void side_store(const SideJob& jb, const float4 (&v)[8], float* tile, const int lane) {
;   const int r8 = lane >> 3, c4 = (lane & 7) * 4;
; #pragma unroll
;   for (int i = 0; i < 8; ++i) {
;     float* d = tile + (i * 8 + r8) * 33 + c4;
;     d[0] = v[i].x; d[1] = v[i].y; d[2] = v[i].z; d[3] = v[i].w;
;   }
;   const int kk = lane & 7, nl = lane >> 3;
; #pragma unroll
;   for (int i = 0; i < 4; ++i) {
;     const int n = i * 8 + nl;
;     bf16x8 o;
; #pragma unroll
;     for (int j = 0; j < 8; ++j) o[j] = (short)f2bf(tile[(kk * 8 + j) * 33 + n]);
;     *(bf16x8*)(jb.Wt + (long)(jb.n0 + n) * jb.K + jb.k0 + kk * 8) = o;
;   }
; }
; __device__ __forceinline__ void side_transpose(KP p, char* smem, int bid, int nb, int wv, const int part) {
;     ...
;     side_store(cur, va, tile, lane);
;     if (!more) break;
; #pragma unroll
;     for (int i = 0; i < 8; ++i) va[i] = vb[i];
;     cur = nxt; j = jn;
.Ld2_st_body_b:
	ds_write2_b32 v77, v2, v3 offset1:1
	ds_write2_b32 v77, v4, v5 offset0:2 offset1:3
	v_add_u32_e32 v2, 0x420, v77
	ds_write2_b32 v2, v6, v7 offset1:1
	v_add_u32_e32 v2, 0x428, v77
	ds_write2_b32 v2, v8, v9 offset1:1
	v_add_u32_e32 v2, 0x840, v77
	ds_write2_b32 v2, v18, v19 offset1:1
	v_add_u32_e32 v2, 0x848, v77
	ds_write2_b32 v2, v20, v21 offset1:1
	v_add_u32_e32 v2, 0xc60, v77
	ds_write2_b32 v2, v22, v23 offset1:1
	v_add_u32_e32 v2, 0xc68, v77
	ds_write2_b32 v2, v24, v25 offset1:1
	v_add_u32_e32 v2, 0x1080, v77
	ds_write2_b32 v2, v30, v31 offset1:1
	v_add_u32_e32 v2, 0x1088, v77
	ds_write2_b32 v2, v32, v33 offset1:1
	v_add_u32_e32 v2, 0x14a0, v77
	ds_write2_b32 v2, v34, v35 offset1:1
	v_add_u32_e32 v2, 0x14a8, v77
	ds_write2_b32 v2, v36, v37 offset1:1
	v_add_u32_e32 v2, 0x18c0, v77
	ds_write2_b32 v2, v42, v43 offset1:1
	v_add_u32_e32 v2, 0x18c8, v77
	ds_write2_b32 v2, v44, v45 offset1:1
	v_add_u32_e32 v2, 0x1ce0, v77
	ds_write2_b32 v2, v46, v47 offset1:1
	v_add_u32_e32 v2, 0x1ce8, v77
	ds_write2_b32 v2, v48, v49 offset1:1
	ds_read2_b32 v[6:7], v76 offset0:33 offset1:41
	ds_read2_b32 v[8:9], v76 offset0:66 offset1:74
	ds_read2_b32 v[18:19], v76 offset0:231 offset1:239
	ds_read2_b32 v[20:21], v76 offset0:198 offset1:206
	ds_read2_b32 v[22:23], v76 offset0:165 offset1:173
	ds_read2_b32 v[24:25], v76 offset0:99 offset1:107
	ds_read2_b32 v[30:31], v76 offset0:132 offset1:140
	ds_read2_b32 v[32:33], v76 offset1:8
	s_waitcnt lgkmcnt(0)
	v_bfe_u32 v35, v8, 16, 1
	v_add3_u32 v8, v8, v35, s97
	v_bfe_u32 v34, v24, 16, 1
	v_add3_u32 v24, v24, v34, s97
	v_add_u32_e32 v34, s29, v68
	v_mov_b32_e32 v35, v1
	v_lshlrev_b64 v[34:35], 13, v[34:35]
	s_ashr_i32 s5, s4, 31
	v_bfe_u32 v2, v18, 16, 1
	v_bfe_u32 v3, v20, 16, 1
	v_bfe_u32 v4, v22, 16, 1
	v_bfe_u32 v5, v30, 16, 1
	v_bfe_u32 v36, v6, 16, 1
	v_bfe_u32 v37, v32, 16, 1
	v_lshl_add_u64 v[34:35], s[6:7], 0, v[34:35]
	s_lshl_b64 s[4:5], s[4:5], 1
	v_add3_u32 v32, v32, v37, s97
	v_add3_u32 v6, v6, v36, s97
	v_add3_u32 v30, v30, v5, s97
	v_add3_u32 v4, v22, v4, s97
	v_add3_u32 v3, v20, v3, s97
	v_add3_u32 v2, v18, v2, s97
	v_lshl_add_u64 v[34:35], v[34:35], 0, s[4:5]
	v_mov_b32_e32 v67, v1
	v_perm_b32 v5, v2, v3, s49
	v_perm_b32 v4, v4, v30, s49
	v_perm_b32 v3, v24, v8, s49
	v_perm_b32 v2, v6, v32, s49
	v_lshl_add_u64 v[34:35], v[34:35], 0, v[66:67]
	global_store_dwordx4 v[34:35], v[2:5], off nt
	v_bfe_u32 v6, v25, 16, 1
	v_bfe_u32 v8, v9, 16, 1
	v_bfe_u32 v2, v19, 16, 1
	v_bfe_u32 v3, v21, 16, 1
	v_bfe_u32 v18, v7, 16, 1
	v_bfe_u32 v20, v33, 16, 1
	v_bfe_u32 v5, v31, 16, 1
	v_add3_u32 v20, v33, v20, s97
	v_add3_u32 v7, v7, v18, s97
	v_add3_u32 v8, v9, v8, s97
	v_add3_u32 v6, v25, v6, s97
	v_add3_u32 v3, v21, v3, s97
	v_add3_u32 v2, v19, v2, s97
	v_add3_u32 v9, v31, v5, s97
	v_perm_b32 v5, v2, v3, s49
	v_perm_b32 v3, v6, v8, s49
	v_perm_b32 v2, v7, v20, s49
	v_add_u32_e32 v6, s29, v69
	v_mov_b32_e32 v7, v1
	v_lshlrev_b64 v[6:7], 13, v[6:7]
	v_bfe_u32 v4, v23, 16, 1
	v_lshl_add_u64 v[6:7], s[6:7], 0, v[6:7]
	v_add3_u32 v4, v23, v4, s97
	v_lshl_add_u64 v[6:7], v[6:7], 0, s[4:5]
	v_perm_b32 v4, v4, v9, s49
	v_lshl_add_u64 v[6:7], v[6:7], 0, v[66:67]
	global_store_dwordx4 v[6:7], v[2:5], off nt
	ds_read2_b32 v[6:7], v76 offset0:16 offset1:24
	ds_read2_b32 v[8:9], v76 offset0:49 offset1:57
	ds_read2_b32 v[18:19], v76 offset0:82 offset1:90
	ds_read2_b32 v[20:21], v76 offset0:247 offset1:255
	ds_read2_b32 v[22:23], v76 offset0:214 offset1:222
	ds_read2_b32 v[24:25], v76 offset0:181 offset1:189
	ds_read2_b32 v[30:31], v76 offset0:148 offset1:156
	ds_read2_b32 v[32:33], v76 offset0:115 offset1:123
	s_waitcnt lgkmcnt(5)
	v_bfe_u32 v35, v18, 16, 1
	v_add3_u32 v18, v18, v35, s97
	v_mov_b32_e32 v35, v1
	s_waitcnt lgkmcnt(4)
	v_bfe_u32 v2, v20, 16, 1
	s_waitcnt lgkmcnt(0)
	v_bfe_u32 v34, v32, 16, 1
	v_add3_u32 v32, v32, v34, s97
	v_add_u32_e32 v34, s29, v70
	v_lshlrev_b64 v[34:35], 13, v[34:35]
	v_bfe_u32 v3, v22, 16, 1
	v_bfe_u32 v4, v24, 16, 1
	v_bfe_u32 v5, v30, 16, 1
	v_bfe_u32 v36, v8, 16, 1
	v_bfe_u32 v37, v6, 16, 1
	v_lshl_add_u64 v[34:35], s[6:7], 0, v[34:35]
	v_add3_u32 v6, v6, v37, s97
	v_add3_u32 v8, v8, v36, s97
	v_add3_u32 v30, v30, v5, s97
	v_add3_u32 v4, v24, v4, s97
	v_add3_u32 v3, v22, v3, s97
	v_add3_u32 v2, v20, v2, s97
	v_lshl_add_u64 v[34:35], v[34:35], 0, s[4:5]
	v_perm_b32 v5, v2, v3, s49
	v_perm_b32 v4, v4, v30, s49
	v_perm_b32 v3, v32, v18, s49
	v_perm_b32 v2, v8, v6, s49
	v_lshl_add_u64 v[34:35], v[34:35], 0, v[66:67]
	global_store_dwordx4 v[34:35], v[2:5], off nt
	v_bfe_u32 v6, v33, 16, 1
	v_bfe_u32 v8, v19, 16, 1
	v_bfe_u32 v2, v21, 16, 1
	v_bfe_u32 v3, v23, 16, 1
	v_bfe_u32 v18, v9, 16, 1
	v_bfe_u32 v20, v7, 16, 1
	v_bfe_u32 v5, v31, 16, 1
	v_add3_u32 v7, v7, v20, s97
	v_add3_u32 v9, v9, v18, s97
	v_add3_u32 v8, v19, v8, s97
	v_add3_u32 v6, v33, v6, s97
	v_add3_u32 v3, v23, v3, s97
	v_add3_u32 v2, v21, v2, s97
	v_add3_u32 v18, v31, v5, s97
	v_perm_b32 v5, v2, v3, s49
	v_perm_b32 v3, v6, v8, s49
	v_perm_b32 v2, v9, v7, s49
	v_add_u32_e32 v6, s29, v71
	v_mov_b32_e32 v7, v1
	v_lshlrev_b64 v[6:7], 13, v[6:7]
	v_bfe_u32 v4, v25, 16, 1
	v_lshl_add_u64 v[6:7], s[6:7], 0, v[6:7]
	v_add3_u32 v4, v25, v4, s97
	v_lshl_add_u64 v[6:7], v[6:7], 0, s[4:5]
	v_perm_b32 v4, v4, v18, s49
	v_lshl_add_u64 v[6:7], v[6:7], 0, v[66:67]
	v_readlane_b32 s4, v253, 30
	global_store_dwordx4 v[6:7], v[2:5], off nt
	s_add_i32 s28, s28, s4
	s_andn2_b64 vcc, exec, s[16:17]
	s_mov_b32 s29, s42
	s_mov_b32 s4, s30
	s_mov_b64 s[6:7], s[18:19]
	s_waitcnt vmcnt(4)
	v_mov_b64_e32 v[2:3], v[10:11]
	v_mov_b64_e32 v[4:5], v[12:13]
	v_mov_b64_e32 v[6:7], v[14:15]
	v_mov_b64_e32 v[8:9], v[16:17]
	v_mov_b64_e32 v[18:19], v[26:27]
	v_mov_b64_e32 v[20:21], v[28:29]
	v_mov_b64_e32 v[22:23], v[38:39]
	v_mov_b64_e32 v[24:25], v[40:41]
	v_mov_b64_e32 v[30:31], v[50:51]
	v_mov_b64_e32 v[32:33], v[52:53]
	v_mov_b64_e32 v[34:35], v[54:55]
	v_mov_b64_e32 v[36:37], v[56:57]
	v_mov_b64_e32 v[42:43], v[58:59]
	v_mov_b64_e32 v[44:45], v[60:61]
	v_mov_b64_e32 v[46:47], v[62:63]
	v_mov_b64_e32 v[48:49], v[64:65]
	s_cbranch_vccz .Ld2_done

; __device__ __forceinline__ void hgrn_pre_phase(KP p, char* smem, int wv, const int seg, const int gw, const int nw) {
;     ...
;   for (int idx = gw; idx < 2048; idx += nw) {
;     const int bh = idx >> 6, c = seg * 64 + (idx & 63), task = bh * 256 + c, b = bh >> 4, h = bh & 15;
;     const long r0 = (long)b * SEQ + c * 16;
;     const float* qsrc = p->proj + r0 * PW + h * 128 + lane * 2;
;     float2 qv[16], fv[16];
; #pragma unroll
;     for (int i = 0; i < 16; ++i) { qv[i] = *(const float2*)(qsrc + (long)i * PW); fv[i] = *(const float2*)(qsrc + 2048 + (long)i * PW); }
.LBB0_994:
	s_and_b32 s14, s5, 63
	s_or_b32 s21, s14, s4
	s_ashr_i32 s14, s5, 10
	s_ashr_i32 s23, s5, 6
	s_ashr_i32 s15, s14, 31
	s_lshl_b32 s22, s23, 8
	s_lshl_b64 s[14:15], s[14:15], 12
	s_lshl_b32 s24, s21, 4
	s_add_u32 s14, s14, s24
	s_addc_u32 s15, s15, 0
	s_mul_i32 s15, s15, 0xe080
	s_mul_hi_u32 s24, s14, 0xe080
	s_add_i32 s24, s24, s15
	s_mul_i32 s14, s14, 0xe080
	s_waitcnt lgkmcnt(0)
	s_add_u32 s14, s18, s14
	s_addc_u32 s15, s19, s24
	s_lshl_b32 s23, s23, 9
	s_and_b32 s23, s23, 0x1e00
	s_add_u32 s14, s14, s23
	s_addc_u32 s15, s15, 0
	v_lshl_add_u64 v[4:5], s[14:15], 0, v[0:1]
	v_add_co_u32_e32 v2, vcc, s54, v4
	global_load_dwordx2 v[72:73], v0, s[14:15]
	s_nop 0
	v_addc_co_u32_e32 v3, vcc, 0, v5, vcc
	global_load_dwordx2 v[60:61], v[2:3], off nt
	v_add_co_u32_e32 v2, vcc, s55, v4
	s_nop 1
	v_addc_co_u32_e32 v3, vcc, 0, v5, vcc
	global_load_dwordx2 v[10:11], v[2:3], off offset:128 nt
	v_add_co_u32_e32 v2, vcc, s1, v4
	s_nop 1
	v_addc_co_u32_e32 v3, vcc, 0, v5, vcc
	global_load_dwordx2 v[62:63], v[2:3], off offset:128 nt
	v_add_co_u32_e32 v2, vcc, s2, v4
	s_nop 1
	v_addc_co_u32_e32 v3, vcc, 0, v5, vcc
	global_load_dwordx2 v[70:71], v[2:3], off offset:256 nt
	v_add_co_u32_e32 v2, vcc, s3, v4
	s_nop 1
	v_addc_co_u32_e32 v3, vcc, 0, v5, vcc
	global_load_dwordx2 v[66:67], v[2:3], off offset:256 nt
	v_add_co_u32_e32 v2, vcc, s35, v4
	s_nop 1
	v_addc_co_u32_e32 v3, vcc, 0, v5, vcc
	global_load_dwordx2 v[64:65], v[2:3], off offset:384 nt
	v_add_co_u32_e32 v2, vcc, s40, v4
	s_nop 1
	v_addc_co_u32_e32 v3, vcc, 0, v5, vcc
	global_load_dwordx2 v[68:69], v[2:3], off offset:384 nt
	v_add_co_u32_e32 v2, vcc, s29, v4
	s_nop 1
	v_addc_co_u32_e32 v3, vcc, 0, v5, vcc
	global_load_dwordx2 v[58:59], v[2:3], off offset:512 nt
	v_add_co_u32_e32 v2, vcc, s41, v4
	s_nop 1
	v_addc_co_u32_e32 v3, vcc, 0, v5, vcc
	global_load_dwordx2 v[52:53], v[2:3], off offset:512 nt
	v_add_co_u32_e32 v2, vcc, s36, v4
	s_nop 1
	v_addc_co_u32_e32 v3, vcc, 0, v5, vcc
	global_load_dwordx2 v[56:57], v[2:3], off offset:640 nt
	v_add_co_u32_e32 v2, vcc, s37, v4
	s_nop 1
	v_addc_co_u32_e32 v3, vcc, 0, v5, vcc
	global_load_dwordx2 v[54:55], v[2:3], off offset:640 nt
	v_add_co_u32_e32 v2, vcc, s42, v4
	s_nop 1
	v_addc_co_u32_e32 v3, vcc, 0, v5, vcc
	global_load_dwordx2 v[50:51], v[2:3], off offset:768 nt
	v_add_co_u32_e32 v2, vcc, s44, v4
	s_nop 1
	v_addc_co_u32_e32 v3, vcc, 0, v5, vcc
	global_load_dwordx2 v[44:45], v[2:3], off offset:768 nt
	v_add_co_u32_e32 v2, vcc, s45, v4
	s_nop 1
	v_addc_co_u32_e32 v3, vcc, 0, v5, vcc
	global_load_dwordx2 v[48:49], v[2:3], off offset:896 nt
	v_add_co_u32_e32 v2, vcc, s50, v4
	s_nop 1
	v_addc_co_u32_e32 v3, vcc, 0, v5, vcc
	global_load_dwordx2 v[46:47], v[2:3], off offset:896 nt
	v_add_co_u32_e32 v2, vcc, s51, v4
	s_nop 1
	v_addc_co_u32_e32 v3, vcc, 0, v5, vcc
	global_load_dwordx2 v[42:43], v[2:3], off offset:1024 nt
	v_add_co_u32_e32 v2, vcc, s52, v4
	s_nop 1
	v_addc_co_u32_e32 v3, vcc, 0, v5, vcc
	global_load_dwordx2 v[36:37], v[2:3], off offset:1024 nt
	v_add_co_u32_e32 v2, vcc, s82, v4
	s_nop 1
	v_addc_co_u32_e32 v3, vcc, 0, v5, vcc
	global_load_dwordx2 v[40:41], v[2:3], off offset:1152 nt
	v_add_co_u32_e32 v2, vcc, s83, v4
	s_nop 1
	v_addc_co_u32_e32 v3, vcc, 0, v5, vcc
	global_load_dwordx2 v[38:39], v[2:3], off offset:1152 nt
	v_add_co_u32_e32 v2, vcc, s88, v4
	s_nop 1
	v_addc_co_u32_e32 v3, vcc, 0, v5, vcc
	global_load_dwordx2 v[34:35], v[2:3], off offset:1280 nt
	v_add_co_u32_e32 v2, vcc, s89, v4
	s_nop 1
	v_addc_co_u32_e32 v3, vcc, 0, v5, vcc
	global_load_dwordx2 v[28:29], v[2:3], off offset:1280 nt
	v_add_co_u32_e32 v2, vcc, s90, v4
	s_nop 1
	v_addc_co_u32_e32 v3, vcc, 0, v5, vcc
	global_load_dwordx2 v[32:33], v[2:3], off offset:1408 nt
	v_add_co_u32_e32 v2, vcc, s91, v4
	s_nop 1
	v_addc_co_u32_e32 v3, vcc, 0, v5, vcc
	global_load_dwordx2 v[30:31], v[2:3], off offset:1408 nt
	v_add_co_u32_e32 v2, vcc, s92, v4
	s_nop 1
	v_addc_co_u32_e32 v3, vcc, 0, v5, vcc
	global_load_dwordx2 v[26:27], v[2:3], off offset:1536 nt
	v_add_co_u32_e32 v2, vcc, s93, v4
	s_nop 1
	v_addc_co_u32_e32 v3, vcc, 0, v5, vcc
	global_load_dwordx2 v[12:13], v[2:3], off offset:1536 nt
	v_add_co_u32_e32 v2, vcc, s94, v4
	s_nop 1
	v_addc_co_u32_e32 v3, vcc, 0, v5, vcc
	global_load_dwordx2 v[24:25], v[2:3], off offset:1664 nt
	v_add_co_u32_e32 v2, vcc, s95, v4
	s_nop 1
	v_addc_co_u32_e32 v3, vcc, 0, v5, vcc
	global_load_dwordx2 v[14:15], v[2:3], off offset:1664 nt
	v_add_co_u32_e32 v2, vcc, s20, v4
	s_nop 1
	v_addc_co_u32_e32 v3, vcc, 0, v5, vcc
	global_load_dwordx2 v[8:9], v[2:3], off offset:1792 nt
	v_add_co_u32_e32 v2, vcc, s25, v4
	s_nop 1
	v_addc_co_u32_e32 v3, vcc, 0, v5, vcc
	v_add_co_u32_e32 v6, vcc, s26, v4
	global_load_dwordx2 v[2:3], v[2:3], off offset:1792 nt
	s_nop 0
	v_addc_co_u32_e32 v7, vcc, 0, v5, vcc
	v_add_co_u32_e32 v4, vcc, s27, v4
	global_load_dwordx2 v[6:7], v[6:7], off offset:1920 nt
	s_nop 0
	v_addc_co_u32_e32 v5, vcc, 0, v5, vcc
	s_waitcnt vmcnt(0)
; __device__ __forceinline__ void hgrn_pre_phase(KP p, char* smem, int wv, const int seg, const int gw, const int nw) {
;     ...
;     for (int i = 0; i < 16; ++i) { qv[i] = *(const float2*)(qsrc + (long)i * PW); fv[i] = *(const float2*)(qsrc + 2048 + (long)i * PW); }
;     float lb0[16], lb1[16];
;     float c0 = 0.f, c1 = 0.f;
; #pragma unroll
;     for (int i = 0; i < 16; ++i) { c0 += __logf(fv[i].x); c1 += __logf(fv[i].y); lb0[i] = c0; lb1[i] = c1; }
	v_cmp_gt_f32_e32 vcc, s38, v60
	global_load_dwordx2 v[4:5], v[4:5], off offset:1920 nt
	s_nop 0
	v_cndmask_b32_e64 v16, 0, 32, vcc
	v_ldexp_f32 v16, v60, v16
	v_log_f32_e32 v16, v16
	s_nop 0
	v_mul_f32_e32 v17, 0x3f317217, v16
	v_fma_f32 v17, v16, s39, -v17
	v_fmac_f32_e32 v17, 0x3377d1cf, v16
	v_fmac_f32_e32 v17, 0x3f317217, v16
	v_cmp_lt_f32_e64 s[14:15], |v16|, s96
	s_nop 1
	v_cndmask_b32_e64 v16, v16, v17, s[14:15]
	v_cndmask_b32_e32 v17, 0, v99, vcc
	v_sub_f32_e32 v16, v16, v17
	v_cmp_gt_f32_e32 vcc, s38, v61
	v_add_f32_e32 v116, 0, v16
	s_nop 0
	v_cndmask_b32_e64 v16, 0, 32, vcc
	v_ldexp_f32 v16, v61, v16
	v_log_f32_e32 v16, v16
	s_nop 0
	v_mul_f32_e32 v17, 0x3f317217, v16
	v_fma_f32 v17, v16, s39, -v17
	v_fmac_f32_e32 v17, 0x3377d1cf, v16
	v_fmac_f32_e32 v17, 0x3f317217, v16
	v_cmp_lt_f32_e64 s[14:15], |v16|, s96
	s_nop 1
	v_cndmask_b32_e64 v16, v16, v17, s[14:15]
	v_cndmask_b32_e32 v17, 0, v99, vcc
	v_sub_f32_e32 v16, v16, v17
	v_cmp_gt_f32_e32 vcc, s38, v62
	v_add_f32_e32 v117, 0, v16
	s_nop 0
	v_cndmask_b32_e64 v16, 0, 32, vcc
	v_ldexp_f32 v16, v62, v16
	v_log_f32_e32 v16, v16
	s_nop 0
	v_mul_f32_e32 v17, 0x3f317217, v16
	v_fma_f32 v17, v16, s39, -v17
	v_fmac_f32_e32 v17, 0x3377d1cf, v16
	v_fmac_f32_e32 v17, 0x3f317217, v16
	v_cmp_lt_f32_e64 s[14:15], |v16|, s96
	s_nop 1
	v_cndmask_b32_e64 v16, v16, v17, s[14:15]
	v_cndmask_b32_e32 v17, 0, v99, vcc
	v_sub_f32_e32 v16, v16, v17
	v_cmp_gt_f32_e32 vcc, s38, v63
	v_add_f32_e32 v118, v116, v16
	s_nop 0
	v_cndmask_b32_e64 v16, 0, 32, vcc
	v_ldexp_f32 v16, v63, v16
	v_log_f32_e32 v16, v16
	s_nop 0
	v_mul_f32_e32 v17, 0x3f317217, v16
	v_fma_f32 v17, v16, s39, -v17
	v_fmac_f32_e32 v17, 0x3377d1cf, v16
	v_fmac_f32_e32 v17, 0x3f317217, v16
	v_cmp_lt_f32_e64 s[14:15], |v16|, s96
	s_nop 1
	v_cndmask_b32_e64 v16, v16, v17, s[14:15]
	v_cndmask_b32_e32 v17, 0, v99, vcc
	v_sub_f32_e32 v16, v16, v17
	v_cmp_gt_f32_e32 vcc, s38, v66
	v_add_f32_e32 v119, v117, v16
	s_nop 0
	v_cndmask_b32_e64 v16, 0, 32, vcc
	v_ldexp_f32 v16, v66, v16
	v_log_f32_e32 v16, v16
	s_nop 0
	v_mul_f32_e32 v17, 0x3f317217, v16
	v_fma_f32 v17, v16, s39, -v17
	v_fmac_f32_e32 v17, 0x3377d1cf, v16
	v_fmac_f32_e32 v17, 0x3f317217, v16
	v_cmp_lt_f32_e64 s[14:15], |v16|, s96
	s_nop 1
	v_cndmask_b32_e64 v16, v16, v17, s[14:15]
	v_cndmask_b32_e32 v17, 0, v99, vcc
	v_sub_f32_e32 v16, v16, v17
	v_cmp_gt_f32_e32 vcc, s38, v67
	v_add_f32_e32 v106, v118, v16
	s_nop 0
	v_cndmask_b32_e64 v16, 0, 32, vcc
	v_ldexp_f32 v16, v67, v16
	v_log_f32_e32 v16, v16
	s_nop 0
	v_mul_f32_e32 v17, 0x3f317217, v16
	v_fma_f32 v17, v16, s39, -v17
	v_fmac_f32_e32 v17, 0x3377d1cf, v16
	v_fmac_f32_e32 v17, 0x3f317217, v16
	v_cmp_lt_f32_e64 s[14:15], |v16|, s96
	s_nop 1
	v_cndmask_b32_e64 v16, v16, v17, s[14:15]
	v_cndmask_b32_e32 v17, 0, v99, vcc
	v_sub_f32_e32 v16, v16, v17
	v_cmp_gt_f32_e32 vcc, s38, v68
	v_add_f32_e32 v107, v119, v16
	s_nop 0
	v_cndmask_b32_e64 v16, 0, 32, vcc
	v_ldexp_f32 v16, v68, v16
	v_log_f32_e32 v16, v16
	s_nop 0
	v_mul_f32_e32 v17, 0x3f317217, v16
	v_fma_f32 v17, v16, s39, -v17
	v_fmac_f32_e32 v17, 0x3377d1cf, v16
	v_fmac_f32_e32 v17, 0x3f317217, v16
	v_cmp_lt_f32_e64 s[14:15], |v16|, s96
	s_nop 1
	v_cndmask_b32_e64 v16, v16, v17, s[14:15]
	v_cndmask_b32_e32 v17, 0, v99, vcc
	v_sub_f32_e32 v16, v16, v17
	v_cmp_gt_f32_e32 vcc, s38, v69
	v_add_f32_e32 v111, v106, v16
	s_nop 0
	v_cndmask_b32_e64 v16, 0, 32, vcc
	v_ldexp_f32 v16, v69, v16
	v_log_f32_e32 v16, v16
	s_nop 0
	v_mul_f32_e32 v17, 0x3f317217, v16
	v_fma_f32 v17, v16, s39, -v17
	v_fmac_f32_e32 v17, 0x3377d1cf, v16
	v_fmac_f32_e32 v17, 0x3f317217, v16
	v_cmp_lt_f32_e64 s[14:15], |v16|, s96
	s_nop 1
	v_cndmask_b32_e64 v16, v16, v17, s[14:15]
	v_cndmask_b32_e32 v17, 0, v99, vcc
	v_sub_f32_e32 v16, v16, v17
	v_cmp_gt_f32_e32 vcc, s38, v52
	v_add_f32_e32 v113, v107, v16
	s_nop 0
	v_cndmask_b32_e64 v16, 0, 32, vcc
	v_ldexp_f32 v16, v52, v16
	v_log_f32_e32 v16, v16
	s_nop 0
	v_mul_f32_e32 v17, 0x3f317217, v16
	v_fma_f32 v17, v16, s39, -v17
	v_fmac_f32_e32 v17, 0x3377d1cf, v16
	v_fmac_f32_e32 v17, 0x3f317217, v16
	v_cmp_lt_f32_e64 s[14:15], |v16|, s96
	s_nop 1
	v_cndmask_b32_e64 v16, v16, v17, s[14:15]
	v_cndmask_b32_e32 v17, 0, v99, vcc
	v_sub_f32_e32 v16, v16, v17
	v_cmp_gt_f32_e32 vcc, s38, v53
	v_add_f32_e32 v98, v111, v16
	s_nop 0
	v_cndmask_b32_e64 v16, 0, 32, vcc
	v_ldexp_f32 v16, v53, v16
	v_log_f32_e32 v16, v16
	s_nop 0
	v_mul_f32_e32 v17, 0x3f317217, v16
	v_fma_f32 v17, v16, s39, -v17
	v_fmac_f32_e32 v17, 0x3377d1cf, v16
	v_fmac_f32_e32 v17, 0x3f317217, v16
	v_cmp_lt_f32_e64 s[14:15], |v16|, s96
	s_nop 1
	v_cndmask_b32_e64 v16, v16, v17, s[14:15]
	v_cndmask_b32_e32 v17, 0, v99, vcc
	v_sub_f32_e32 v16, v16, v17
	v_cmp_gt_f32_e32 vcc, s38, v54
	v_add_f32_e32 v100, v113, v16
	s_nop 0
	v_cndmask_b32_e64 v16, 0, 32, vcc
	v_ldexp_f32 v16, v54, v16
	v_log_f32_e32 v16, v16
	s_nop 0
	v_mul_f32_e32 v17, 0x3f317217, v16
	v_fma_f32 v17, v16, s39, -v17
	v_fmac_f32_e32 v17, 0x3377d1cf, v16
	v_fmac_f32_e32 v17, 0x3f317217, v16
	v_cmp_lt_f32_e64 s[14:15], |v16|, s96
	s_nop 1
	v_cndmask_b32_e64 v16, v16, v17, s[14:15]
	v_cndmask_b32_e32 v17, 0, v99, vcc
	v_sub_f32_e32 v16, v16, v17
	v_cmp_gt_f32_e32 vcc, s38, v55
	v_add_f32_e32 v102, v98, v16
	s_nop 0
	v_cndmask_b32_e64 v16, 0, 32, vcc
	v_ldexp_f32 v16, v55, v16
	v_log_f32_e32 v16, v16
	s_nop 0
	v_mul_f32_e32 v17, 0x3f317217, v16
	v_fma_f32 v17, v16, s39, -v17
	v_fmac_f32_e32 v17, 0x3377d1cf, v16
	v_fmac_f32_e32 v17, 0x3f317217, v16
	v_cmp_lt_f32_e64 s[14:15], |v16|, s96
	s_nop 1
	v_cndmask_b32_e64 v16, v16, v17, s[14:15]
	v_cndmask_b32_e32 v17, 0, v99, vcc
	v_sub_f32_e32 v16, v16, v17
	v_cmp_gt_f32_e32 vcc, s38, v44
	v_add_f32_e32 v104, v100, v16
; __device__ __forceinline__ void hgrn_pre_phase(KP p, char* smem, int wv, const int seg, const int gw, const int nw) {
;     ...
;     for (int i = 0; i < 16; ++i) { c0 += __logf(fv[i].x); c1 += __logf(fv[i].y); lb0[i] = c0; lb1[i] = c1; }
	s_nop 0
	v_cndmask_b32_e64 v16, 0, 32, vcc
	v_ldexp_f32 v16, v44, v16
	v_log_f32_e32 v16, v16
	s_nop 0
	v_mul_f32_e32 v17, 0x3f317217, v16
	v_fma_f32 v17, v16, s39, -v17
	v_fmac_f32_e32 v17, 0x3377d1cf, v16
	v_fmac_f32_e32 v17, 0x3f317217, v16
	v_cmp_lt_f32_e64 s[14:15], |v16|, s96
	s_nop 1
	v_cndmask_b32_e64 v16, v16, v17, s[14:15]
	v_cndmask_b32_e32 v17, 0, v99, vcc
	v_sub_f32_e32 v16, v16, v17
	v_cmp_gt_f32_e32 vcc, s38, v45
	v_add_f32_e32 v94, v102, v16
	s_nop 0
	v_cndmask_b32_e64 v16, 0, 32, vcc
	v_ldexp_f32 v16, v45, v16
	v_log_f32_e32 v16, v16
	s_nop 0
	v_mul_f32_e32 v17, 0x3f317217, v16
	v_fma_f32 v17, v16, s39, -v17
	v_fmac_f32_e32 v17, 0x3377d1cf, v16
	v_fmac_f32_e32 v17, 0x3f317217, v16
	v_cmp_lt_f32_e64 s[14:15], |v16|, s96
	s_nop 1
	v_cndmask_b32_e64 v16, v16, v17, s[14:15]
	v_cndmask_b32_e32 v17, 0, v99, vcc
	v_sub_f32_e32 v16, v16, v17
	v_cmp_gt_f32_e32 vcc, s38, v46
	v_add_f32_e32 v95, v104, v16
	s_nop 0
	v_cndmask_b32_e64 v16, 0, 32, vcc
	v_ldexp_f32 v16, v46, v16
	v_log_f32_e32 v16, v16
	s_nop 0
	v_mul_f32_e32 v17, 0x3f317217, v16
	v_fma_f32 v17, v16, s39, -v17
	v_fmac_f32_e32 v17, 0x3377d1cf, v16
	v_fmac_f32_e32 v17, 0x3f317217, v16
	v_cmp_lt_f32_e64 s[14:15], |v16|, s96
	s_nop 1
	v_cndmask_b32_e64 v16, v16, v17, s[14:15]
	v_cndmask_b32_e32 v17, 0, v99, vcc
	v_sub_f32_e32 v16, v16, v17
	v_cmp_gt_f32_e32 vcc, s38, v47
	v_add_f32_e32 v96, v94, v16
	s_nop 0
	v_cndmask_b32_e64 v16, 0, 32, vcc
	v_ldexp_f32 v16, v47, v16
	v_log_f32_e32 v16, v16
	s_nop 0
	v_mul_f32_e32 v17, 0x3f317217, v16
	v_fma_f32 v17, v16, s39, -v17
	v_fmac_f32_e32 v17, 0x3377d1cf, v16
	v_fmac_f32_e32 v17, 0x3f317217, v16
	v_cmp_lt_f32_e64 s[14:15], |v16|, s96
	s_nop 1
	v_cndmask_b32_e64 v16, v16, v17, s[14:15]
	v_cndmask_b32_e32 v17, 0, v99, vcc
	v_sub_f32_e32 v16, v16, v17
	v_cmp_gt_f32_e32 vcc, s38, v36
	v_add_f32_e32 v97, v95, v16
	s_nop 0
	v_cndmask_b32_e64 v16, 0, 32, vcc
	v_ldexp_f32 v16, v36, v16
	v_log_f32_e32 v16, v16
	s_nop 0
	v_mul_f32_e32 v17, 0x3f317217, v16
	v_fma_f32 v17, v16, s39, -v17
	v_fmac_f32_e32 v17, 0x3377d1cf, v16
	v_fmac_f32_e32 v17, 0x3f317217, v16
	v_cmp_lt_f32_e64 s[14:15], |v16|, s96
	s_nop 1
	v_cndmask_b32_e64 v16, v16, v17, s[14:15]
	v_cndmask_b32_e32 v17, 0, v99, vcc
	v_sub_f32_e32 v16, v16, v17
	v_cmp_gt_f32_e32 vcc, s38, v37
	v_add_f32_e32 v90, v96, v16
	s_nop 0
	v_cndmask_b32_e64 v16, 0, 32, vcc
	v_ldexp_f32 v16, v37, v16
	v_log_f32_e32 v16, v16
	s_nop 0
	v_mul_f32_e32 v17, 0x3f317217, v16
	v_fma_f32 v17, v16, s39, -v17
	v_fmac_f32_e32 v17, 0x3377d1cf, v16
	v_fmac_f32_e32 v17, 0x3f317217, v16
	v_cmp_lt_f32_e64 s[14:15], |v16|, s96
	s_nop 1
	v_cndmask_b32_e64 v16, v16, v17, s[14:15]
	v_cndmask_b32_e32 v17, 0, v99, vcc
	v_sub_f32_e32 v16, v16, v17
	v_cmp_gt_f32_e32 vcc, s38, v38
	v_add_f32_e32 v91, v97, v16
	s_nop 0
	v_cndmask_b32_e64 v16, 0, 32, vcc
	v_ldexp_f32 v16, v38, v16
	v_log_f32_e32 v16, v16
	s_nop 0
	v_mul_f32_e32 v17, 0x3f317217, v16
	v_fma_f32 v17, v16, s39, -v17
	v_fmac_f32_e32 v17, 0x3377d1cf, v16
	v_fmac_f32_e32 v17, 0x3f317217, v16
	v_cmp_lt_f32_e64 s[14:15], |v16|, s96
	s_nop 1
	v_cndmask_b32_e64 v16, v16, v17, s[14:15]
	v_cndmask_b32_e32 v17, 0, v99, vcc
	v_sub_f32_e32 v16, v16, v17
	v_cmp_gt_f32_e32 vcc, s38, v39
	v_add_f32_e32 v92, v90, v16
	s_nop 0
	v_cndmask_b32_e64 v16, 0, 32, vcc
	v_ldexp_f32 v16, v39, v16
	v_log_f32_e32 v16, v16
	s_nop 0
	v_mul_f32_e32 v17, 0x3f317217, v16
	v_fma_f32 v17, v16, s39, -v17
	v_fmac_f32_e32 v17, 0x3377d1cf, v16
	v_fmac_f32_e32 v17, 0x3f317217, v16
	v_cmp_lt_f32_e64 s[14:15], |v16|, s96
	s_nop 1
	v_cndmask_b32_e64 v16, v16, v17, s[14:15]
	v_cndmask_b32_e32 v17, 0, v99, vcc
	v_sub_f32_e32 v16, v16, v17
	v_cmp_gt_f32_e32 vcc, s38, v28
	v_add_f32_e32 v93, v91, v16
	s_nop 0
	v_cndmask_b32_e64 v16, 0, 32, vcc
	v_ldexp_f32 v16, v28, v16
	v_log_f32_e32 v16, v16
	s_nop 0
	v_mul_f32_e32 v17, 0x3f317217, v16
	v_fma_f32 v17, v16, s39, -v17
	v_fmac_f32_e32 v17, 0x3377d1cf, v16
	v_fmac_f32_e32 v17, 0x3f317217, v16
	v_cmp_lt_f32_e64 s[14:15], |v16|, s96
	s_nop 1
	v_cndmask_b32_e64 v16, v16, v17, s[14:15]
	v_cndmask_b32_e32 v17, 0, v99, vcc
	v_sub_f32_e32 v16, v16, v17
	v_cmp_gt_f32_e32 vcc, s38, v29
	v_add_f32_e32 v86, v92, v16
	s_nop 0
	v_cndmask_b32_e64 v16, 0, 32, vcc
	v_ldexp_f32 v16, v29, v16
	v_log_f32_e32 v16, v16
	s_nop 0
	v_mul_f32_e32 v17, 0x3f317217, v16
	v_fma_f32 v17, v16, s39, -v17
	v_fmac_f32_e32 v17, 0x3377d1cf, v16
	v_fmac_f32_e32 v17, 0x3f317217, v16
	v_cmp_lt_f32_e64 s[14:15], |v16|, s96
	s_nop 1
	v_cndmask_b32_e64 v16, v16, v17, s[14:15]
	v_cndmask_b32_e32 v17, 0, v99, vcc
	v_sub_f32_e32 v16, v16, v17
	v_cmp_gt_f32_e32 vcc, s38, v30
	v_add_f32_e32 v87, v93, v16
	s_nop 0
	v_cndmask_b32_e64 v16, 0, 32, vcc
	v_ldexp_f32 v16, v30, v16
	v_log_f32_e32 v16, v16
	s_nop 0
	v_mul_f32_e32 v17, 0x3f317217, v16
	v_fma_f32 v17, v16, s39, -v17
	v_fmac_f32_e32 v17, 0x3377d1cf, v16
	v_fmac_f32_e32 v17, 0x3f317217, v16
	v_cmp_lt_f32_e64 s[14:15], |v16|, s96
	s_nop 1
	v_cndmask_b32_e64 v16, v16, v17, s[14:15]
	v_cndmask_b32_e32 v17, 0, v99, vcc
	v_sub_f32_e32 v16, v16, v17
	v_cmp_gt_f32_e32 vcc, s38, v31
	v_add_f32_e32 v88, v86, v16
	s_nop 0
	v_cndmask_b32_e64 v16, 0, 32, vcc
	v_ldexp_f32 v16, v31, v16
	v_log_f32_e32 v16, v16
	s_nop 0
	v_mul_f32_e32 v17, 0x3f317217, v16
	v_fma_f32 v17, v16, s39, -v17
	v_fmac_f32_e32 v17, 0x3377d1cf, v16
	v_fmac_f32_e32 v17, 0x3f317217, v16
	v_cmp_lt_f32_e64 s[14:15], |v16|, s96
	s_nop 1
	v_cndmask_b32_e64 v16, v16, v17, s[14:15]
	v_cndmask_b32_e32 v17, 0, v99, vcc
	v_sub_f32_e32 v16, v16, v17
	v_cmp_gt_f32_e32 vcc, s38, v12
	v_add_f32_e32 v89, v87, v16
	s_nop 0
	v_cndmask_b32_e64 v16, 0, 32, vcc
	v_ldexp_f32 v16, v12, v16
	v_log_f32_e32 v16, v16
; __device__ __forceinline__ void hgrn_pre_phase(KP p, char* smem, int wv, const int seg, const int gw, const int nw) {
;     ...
;     for (int i = 0; i < 16; ++i) { c0 += __logf(fv[i].x); c1 += __logf(fv[i].y); lb0[i] = c0; lb1[i] = c1; }
;     char* tb = scr + (long)task * HG_TASK_B;
;     *(float2*)(tb + 8704 + lane * 8) = make_float2(__expf(c0), __expf(c1));
;     unsigned short kh0[16], kh1[16];
;     const float ec0 = __expf(c0), ec1 = __expf(c1);
; #pragma unroll
;     for (int i = 0; i < 16; ++i) {
;       const float e0 = __expf(lb0[i]), e1 = __expf(lb1[i]);
;       const float k0 = (1.f - fv[i].x) * __frcp_rn(e0), k1 = (1.f - fv[i].y) * __frcp_rn(e1);
;       const unsigned qt = (unsigned)f2bf(qv[i].x * e0) | ((unsigned)f2bf(qv[i].y * e1) << 16);
;       const unsigned kt = (unsigned)f2bf(k0) | ((unsigned)f2bf(k1) << 16);
;       *(unsigned*)(wl + i * 136 + lane * 2) = qt;
;       *(unsigned*)(wl + 2176 + i * 136 + lane * 2) = kt;
;       kh0[i] = f2bf(k0 * ec0);
;       kh1[i] = f2bf(k1 * ec1);
	s_nop 0
	v_mul_f32_e32 v17, 0x3f317217, v16
	v_fma_f32 v17, v16, s39, -v17
	v_fmac_f32_e32 v17, 0x3377d1cf, v16
	v_fmac_f32_e32 v17, 0x3f317217, v16
	v_cmp_lt_f32_e64 s[14:15], |v16|, s96
	s_nop 1
	v_cndmask_b32_e64 v16, v16, v17, s[14:15]
	v_cndmask_b32_e32 v17, 0, v99, vcc
	v_sub_f32_e32 v16, v16, v17
	v_cmp_gt_f32_e32 vcc, s38, v13
	v_add_f32_e32 v82, v88, v16
	s_nop 0
	v_cndmask_b32_e64 v16, 0, 32, vcc
	v_ldexp_f32 v16, v13, v16
	v_log_f32_e32 v16, v16
	s_nop 0
	v_mul_f32_e32 v17, 0x3f317217, v16
	v_fma_f32 v17, v16, s39, -v17
	v_fmac_f32_e32 v17, 0x3377d1cf, v16
	v_fmac_f32_e32 v17, 0x3f317217, v16
	v_cmp_lt_f32_e64 s[14:15], |v16|, s96
	s_nop 1
	v_cndmask_b32_e64 v16, v16, v17, s[14:15]
	v_cndmask_b32_e32 v17, 0, v99, vcc
	v_sub_f32_e32 v16, v16, v17
	v_cmp_gt_f32_e32 vcc, s38, v14
	v_add_f32_e32 v83, v89, v16
	s_nop 0
	v_cndmask_b32_e64 v16, 0, 32, vcc
	v_ldexp_f32 v16, v14, v16
	v_log_f32_e32 v16, v16
	s_nop 0
	v_mul_f32_e32 v17, 0x3f317217, v16
	v_fma_f32 v17, v16, s39, -v17
	v_fmac_f32_e32 v17, 0x3377d1cf, v16
	v_fmac_f32_e32 v17, 0x3f317217, v16
	v_cmp_lt_f32_e64 s[14:15], |v16|, s96
	s_nop 1
	v_cndmask_b32_e64 v16, v16, v17, s[14:15]
	v_cndmask_b32_e32 v17, 0, v99, vcc
	v_sub_f32_e32 v16, v16, v17
	v_cmp_gt_f32_e32 vcc, s38, v15
	v_add_f32_e32 v84, v82, v16
	s_nop 0
	v_cndmask_b32_e64 v16, 0, 32, vcc
	v_ldexp_f32 v16, v15, v16
	v_log_f32_e32 v16, v16
	s_nop 0
	v_mul_f32_e32 v17, 0x3f317217, v16
	v_fma_f32 v17, v16, s39, -v17
	v_fmac_f32_e32 v17, 0x3377d1cf, v16
	v_fmac_f32_e32 v17, 0x3f317217, v16
	v_cmp_lt_f32_e64 s[14:15], |v16|, s96
	s_nop 1
	v_cndmask_b32_e64 v16, v16, v17, s[14:15]
	v_cndmask_b32_e32 v17, 0, v99, vcc
	v_sub_f32_e32 v16, v16, v17
	v_cmp_gt_f32_e32 vcc, s38, v2
	v_add_f32_e32 v85, v83, v16
	s_nop 0
	v_cndmask_b32_e64 v16, 0, 32, vcc
	v_ldexp_f32 v16, v2, v16
	v_log_f32_e32 v16, v16
	s_nop 0
	v_mul_f32_e32 v17, 0x3f317217, v16
	v_fma_f32 v17, v16, s39, -v17
	v_fmac_f32_e32 v17, 0x3377d1cf, v16
	v_fmac_f32_e32 v17, 0x3f317217, v16
	v_cmp_lt_f32_e64 s[14:15], |v16|, s96
	s_nop 1
	v_cndmask_b32_e64 v16, v16, v17, s[14:15]
	v_cndmask_b32_e32 v17, 0, v99, vcc
	v_sub_f32_e32 v16, v16, v17
	v_cmp_gt_f32_e32 vcc, s38, v3
	v_add_f32_e32 v80, v84, v16
	s_nop 0
	v_cndmask_b32_e64 v16, 0, 32, vcc
	v_ldexp_f32 v16, v3, v16
	v_log_f32_e32 v16, v16
	s_nop 0
	v_mul_f32_e32 v17, 0x3f317217, v16
	v_fma_f32 v17, v16, s39, -v17
	v_fmac_f32_e32 v17, 0x3377d1cf, v16
	v_fmac_f32_e32 v17, 0x3f317217, v16
	v_cmp_lt_f32_e64 s[14:15], |v16|, s96
	s_nop 1
	v_cndmask_b32_e64 v16, v16, v17, s[14:15]
	v_cndmask_b32_e32 v17, 0, v99, vcc
	v_sub_f32_e32 v16, v16, v17
	s_waitcnt vmcnt(0)
	v_cmp_gt_f32_e32 vcc, s38, v4
	v_add_f32_e32 v81, v85, v16
	s_nop 0
	v_cndmask_b32_e64 v16, 0, 32, vcc
	v_ldexp_f32 v16, v4, v16
	v_log_f32_e32 v16, v16
	s_nop 0
	v_mul_f32_e32 v17, 0x3f317217, v16
	v_fma_f32 v17, v16, s39, -v17
	v_fmac_f32_e32 v17, 0x3377d1cf, v16
	v_fmac_f32_e32 v17, 0x3f317217, v16
	v_cmp_lt_f32_e64 s[14:15], |v16|, s96
	s_nop 1
	v_cndmask_b32_e64 v16, v16, v17, s[14:15]
	v_cndmask_b32_e32 v17, 0, v99, vcc
	v_cmp_gt_f32_e32 vcc, s38, v5
	v_sub_f32_e32 v16, v16, v17
	v_add_f32_e32 v16, v80, v16
	v_cndmask_b32_e64 v17, 0, 32, vcc
	v_ldexp_f32 v17, v5, v17
	v_log_f32_e32 v17, v17
	v_mul_f32_e32 v16, 0x3fb8aa3b, v16
	v_exp_f32_e32 v16, v16
	v_mul_f32_e32 v114, 0x3f317217, v17
	v_fma_f32 v114, v17, s39, -v114
	v_fmac_f32_e32 v114, 0x3377d1cf, v17
	v_fmac_f32_e32 v114, 0x3f317217, v17
	v_cmp_lt_f32_e64 s[14:15], |v17|, s96
	v_mul_f32_e32 v6, v6, v16
	s_nop 0
	v_cndmask_b32_e64 v17, v17, v114, s[14:15]
	v_cndmask_b32_e32 v114, 0, v99, vcc
	v_sub_f32_e32 v17, v17, v114
	s_add_i32 s14, s22, s21
	v_add_f32_e32 v17, v81, v17
	s_mul_hi_i32 s15, s14, 0x2400
	s_mulk_i32 s14, 0x2400
	s_add_u32 s14, s16, s14
	v_mul_f32_e32 v17, 0x3fb8aa3b, v17
	s_addc_u32 s15, s17, s15
	v_exp_f32_e32 v17, v17
	v_lshl_add_u64 v[114:115], s[14:15], 0, v[18:19]
	v_add_co_u32_e32 v114, vcc, s54, v114
	v_mul_f32_e32 v7, v7, v17
	s_nop 0
	v_addc_co_u32_e32 v115, vcc, 0, v115, vcc
	global_store_dwordx2 v[114:115], v[16:17], off offset:512
	v_mul_f32_e32 v114, 0x3fb8aa3b, v116
	v_exp_f32_e32 v114, v114
	v_mul_f32_e32 v115, 0x3fb8aa3b, v117
	v_exp_f32_e32 v115, v115
	v_mul_f32_e32 v72, v72, v114
	v_bfe_u32 v116, v72, 16, 1
	v_mul_f32_e32 v73, v73, v115
	v_add3_u32 v72, v72, v116, s97
	v_bfe_u32 v116, v73, 16, 1
	v_lshrrev_b32_e32 v72, 16, v72
	v_add3_u32 v73, v73, v116, s97
	v_and_or_b32 v72, v73, s48, v72
	v_mul_f32_e32 v73, 0x3fb8aa3b, v118
	v_exp_f32_e32 v73, v73
	v_mul_f32_e32 v116, 0x3fb8aa3b, v119
	v_exp_f32_e32 v116, v116
	v_mul_f32_e32 v10, v10, v73
	v_bfe_u32 v117, v10, 16, 1
	v_mul_f32_e32 v11, v11, v116
	v_add3_u32 v10, v10, v117, s97
	v_bfe_u32 v117, v11, 16, 1
	v_lshrrev_b32_e32 v10, 16, v10
	v_add3_u32 v11, v11, v117, s97
	v_and_or_b32 v10, v11, s48, v10
	ds_write2_b32 v74, v72, v10 offset1:68
	v_mov_b32_e32 v10, v60
	v_div_scale_f32 v60, s[22:23], v73, v73, 1.0
	v_mov_b32_e32 v11, v62
	v_rcp_f32_e32 v62, v60
	v_pk_add_f32 v[10:11], v[10:11], 1.0 op_sel_hi:[1,0] neg_lo:[1,0] neg_hi:[1,0]
	v_fma_f32 v72, -v60, v62, 1.0
	v_fmac_f32_e32 v62, v72, v62
	v_div_scale_f32 v72, vcc, 1.0, v73, 1.0
	v_mul_f32_e32 v117, v72, v62
	v_fma_f32 v118, -v60, v117, v72
	v_fmac_f32_e32 v117, v118, v62
	v_fma_f32 v60, -v60, v117, v72
	v_div_fmas_f32 v60, v60, v62, v117
	v_div_fixup_f32 v73, v60, v73, 1.0
	v_div_scale_f32 v60, s[22:23], v114, v114, 1.0
	v_rcp_f32_e32 v62, v60
	s_nop 0
	v_fma_f32 v72, -v60, v62, 1.0
	v_fmac_f32_e32 v62, v72, v62
	v_div_scale_f32 v72, vcc, 1.0, v114, 1.0
	v_mul_f32_e32 v117, v72, v62
	v_fma_f32 v118, -v60, v117, v72
	v_fmac_f32_e32 v117, v118, v62
; __device__ __forceinline__ void hgrn_pre_phase(KP p, char* smem, int wv, const int seg, const int gw, const int nw) {
;     ...
;     const float ec0 = __expf(c0), ec1 = __expf(c1);
; #pragma unroll
;     for (int i = 0; i < 16; ++i) {
;       const float e0 = __expf(lb0[i]), e1 = __expf(lb1[i]);
;       const float k0 = (1.f - fv[i].x) * __frcp_rn(e0), k1 = (1.f - fv[i].y) * __frcp_rn(e1);
;       const unsigned qt = (unsigned)f2bf(qv[i].x * e0) | ((unsigned)f2bf(qv[i].y * e1) << 16);
;       const unsigned kt = (unsigned)f2bf(k0) | ((unsigned)f2bf(k1) << 16);
;       *(unsigned*)(wl + i * 136 + lane * 2) = qt;
;       *(unsigned*)(wl + 2176 + i * 136 + lane * 2) = kt;
;       kh0[i] = f2bf(k0 * ec0);
;       kh1[i] = f2bf(k1 * ec1);
;     }
	v_fma_f32 v60, -v60, v117, v72
	v_div_fmas_f32 v60, v60, v62, v117
	v_div_fixup_f32 v72, v60, v114, 1.0
	v_pk_mul_f32 v[10:11], v[10:11], v[72:73]
	v_mov_b32_e32 v62, v61
	v_bfe_u32 v60, v10, 16, 1
	v_add3_u32 v60, v10, v60, s97
	v_lshrrev_b32_e32 v72, 16, v60
	v_bfe_u32 v60, v11, 16, 1
	v_add3_u32 v60, v11, v60, s97
	v_lshrrev_b32_e32 v73, 16, v60
	v_pk_add_f32 v[60:61], v[62:63], 1.0 op_sel_hi:[1,0] neg_lo:[1,0] neg_hi:[1,0]
	v_div_scale_f32 v62, s[22:23], v116, v116, 1.0
	v_rcp_f32_e32 v63, v62
	v_pk_mul_f32 v[10:11], v[10:11], v[16:17] op_sel_hi:[1,0]
	v_fma_f32 v114, -v62, v63, 1.0
	v_fmac_f32_e32 v63, v114, v63
	v_div_scale_f32 v114, vcc, 1.0, v116, 1.0
	v_mul_f32_e32 v117, v114, v63
	v_fma_f32 v118, -v62, v117, v114
	v_fmac_f32_e32 v117, v118, v63
	v_fma_f32 v62, -v62, v117, v114
	v_div_fmas_f32 v62, v62, v63, v117
	v_div_fixup_f32 v63, v62, v116, 1.0
	v_div_scale_f32 v62, s[22:23], v115, v115, 1.0
	v_rcp_f32_e32 v114, v62
	s_nop 0
	v_fma_f32 v116, -v62, v114, 1.0
	v_fmac_f32_e32 v114, v116, v114
	v_div_scale_f32 v116, vcc, 1.0, v115, 1.0
	v_mul_f32_e32 v117, v116, v114
	v_fma_f32 v118, -v62, v117, v116
	v_fmac_f32_e32 v117, v118, v114
	v_fma_f32 v62, -v62, v117, v116
	v_div_fmas_f32 v62, v62, v114, v117
	v_div_fixup_f32 v62, v62, v115, 1.0
	v_pk_mul_f32 v[60:61], v[60:61], v[62:63]
	s_nop 0
	v_bfe_u32 v62, v60, 16, 1
	v_bfe_u32 v63, v61, 16, 1
	v_add3_u32 v62, v60, v62, s97
	v_add3_u32 v63, v61, v63, s97
	v_and_or_b32 v62, v62, s48, v72
	v_and_or_b32 v63, v63, s48, v73
	v_add_u32_e32 v72, 0x1000, v74
	ds_write2_b32 v72, v62, v63 offset0:64 offset1:132
	v_mov_b32_e32 v62, v17
	v_pk_mul_f32 v[60:61], v[60:61], v[62:63] op_sel_hi:[1,0]
	v_mul_f32_e32 v63, 0x3fb8aa3b, v106
	v_exp_f32_e32 v63, v63
	v_mul_f32_e32 v72, 0x3fb8aa3b, v107
	v_exp_f32_e32 v72, v72
	v_mul_f32_e32 v70, v70, v63
	v_bfe_u32 v73, v70, 16, 1
	v_mul_f32_e32 v71, v71, v72
	v_add3_u32 v70, v70, v73, s97
	v_bfe_u32 v73, v71, 16, 1
	v_lshrrev_b32_e32 v70, 16, v70
	v_add3_u32 v71, v71, v73, s97
	v_and_or_b32 v70, v71, s48, v70
	v_mul_f32_e32 v71, 0x3fb8aa3b, v111
	v_exp_f32_e32 v71, v71
	v_mul_f32_e32 v73, 0x3fb8aa3b, v113
	v_exp_f32_e32 v73, v73
	v_mul_f32_e32 v64, v64, v71
	v_bfe_u32 v106, v64, 16, 1
	v_mul_f32_e32 v65, v65, v73
	v_add3_u32 v64, v64, v106, s97
	v_bfe_u32 v106, v65, 16, 1
	v_lshrrev_b32_e32 v64, 16, v64
	v_add3_u32 v65, v65, v106, s97
	v_and_or_b32 v64, v65, s48, v64
	ds_write2_b32 v74, v70, v64 offset0:136 offset1:204
	v_mov_b32_e32 v64, v66
	v_div_scale_f32 v66, s[22:23], v63, v63, 1.0
	v_mov_b32_e32 v65, v68
	v_rcp_f32_e32 v68, v66
	v_pk_add_f32 v[64:65], v[64:65], 1.0 op_sel_hi:[1,0] neg_lo:[1,0] neg_hi:[1,0]
	v_fma_f32 v70, -v66, v68, 1.0
	v_fmac_f32_e32 v68, v70, v68
	v_div_scale_f32 v70, vcc, 1.0, v63, 1.0
	v_mul_f32_e32 v106, v70, v68
	v_fma_f32 v107, -v66, v106, v70
	v_fmac_f32_e32 v106, v107, v68
	v_fma_f32 v66, -v66, v106, v70
	v_div_fmas_f32 v66, v66, v68, v106
	v_div_fixup_f32 v70, v66, v63, 1.0
	v_div_scale_f32 v63, s[22:23], v71, v71, 1.0
	v_rcp_f32_e32 v66, v63
	s_nop 0
	v_fma_f32 v68, -v63, v66, 1.0
	v_fmac_f32_e32 v66, v68, v66
	v_div_scale_f32 v68, vcc, 1.0, v71, 1.0
	v_mul_f32_e32 v106, v68, v66
	v_fma_f32 v107, -v63, v106, v68
	v_fmac_f32_e32 v106, v107, v66
	v_fma_f32 v63, -v63, v106, v68
	v_div_fmas_f32 v63, v63, v66, v106
	v_div_fixup_f32 v71, v63, v71, 1.0
	v_pk_mul_f32 v[64:65], v[64:65], v[70:71]
	v_mov_b32_e32 v68, v67
	v_bfe_u32 v66, v65, 16, 1
	v_add3_u32 v66, v65, v66, s97
	v_lshrrev_b32_e32 v70, 16, v66
	v_pk_add_f32 v[66:67], v[68:69], 1.0 op_sel_hi:[1,0] neg_lo:[1,0] neg_hi:[1,0]
	v_div_scale_f32 v68, s[22:23], v72, v72, 1.0
	v_rcp_f32_e32 v69, v68
	v_bfe_u32 v63, v64, 16, 1
	v_add3_u32 v63, v64, v63, s97
	v_lshrrev_b32_e32 v63, 16, v63
	v_fma_f32 v71, -v68, v69, 1.0
	v_fmac_f32_e32 v69, v71, v69
	v_div_scale_f32 v71, vcc, 1.0, v72, 1.0
	v_mul_f32_e32 v106, v71, v69
	v_fma_f32 v107, -v68, v106, v71
	v_fmac_f32_e32 v106, v107, v69
	v_fma_f32 v68, -v68, v106, v71
	v_div_fmas_f32 v68, v68, v69, v106
	v_div_scale_f32 v69, s[22:23], v73, v73, 1.0
	v_rcp_f32_e32 v71, v69
	v_div_fixup_f32 v68, v68, v72, 1.0
	v_pk_mul_f32 v[64:65], v[64:65], v[16:17] op_sel_hi:[1,0]
	v_fma_f32 v72, -v69, v71, 1.0
	v_fmac_f32_e32 v71, v72, v71
	v_div_scale_f32 v72, vcc, 1.0, v73, 1.0
	v_mul_f32_e32 v106, v72, v71
	v_fma_f32 v107, -v69, v106, v72
	v_fmac_f32_e32 v106, v107, v71
	v_fma_f32 v69, -v69, v106, v72
	v_div_fmas_f32 v69, v69, v71, v106
	v_div_fixup_f32 v69, v69, v73, 1.0
	v_pk_mul_f32 v[66:67], v[66:67], v[68:69]
	v_add_u32_e32 v69, 0x1200, v74
	v_bfe_u32 v68, v66, 16, 1
	v_add3_u32 v68, v66, v68, s97
	v_and_or_b32 v63, v68, s48, v63
	v_bfe_u32 v68, v67, 16, 1
	v_add3_u32 v68, v67, v68, s97
	v_and_or_b32 v68, v68, s48, v70
	ds_write2_b32 v69, v63, v68 offset0:72 offset1:140
	v_pk_mul_f32 v[66:67], v[66:67], v[62:63] op_sel_hi:[1,0]
	v_mul_f32_e32 v63, 0x3fb8aa3b, v98
	v_exp_f32_e32 v63, v63
	v_mul_f32_e32 v68, 0x3fb8aa3b, v100
	v_exp_f32_e32 v68, v68
	v_mul_f32_e32 v58, v58, v63
	v_bfe_u32 v69, v58, 16, 1
	v_mul_f32_e32 v59, v59, v68
	v_add3_u32 v58, v58, v69, s97
	v_bfe_u32 v69, v59, 16, 1
	v_lshrrev_b32_e32 v58, 16, v58
	v_add3_u32 v59, v59, v69, s97
	v_and_or_b32 v58, v59, s48, v58
	v_mul_f32_e32 v59, 0x3fb8aa3b, v102
	v_exp_f32_e32 v59, v59
	v_mul_f32_e32 v69, 0x3fb8aa3b, v104
	v_exp_f32_e32 v69, v69
	v_mul_f32_e32 v56, v56, v59
	v_bfe_u32 v70, v56, 16, 1
	v_mul_f32_e32 v57, v57, v69
	v_add3_u32 v56, v56, v70, s97
	v_bfe_u32 v70, v57, 16, 1
	v_lshrrev_b32_e32 v56, 16, v56
	v_add3_u32 v57, v57, v70, s97
	v_and_or_b32 v56, v57, s48, v56
	v_add_u32_e32 v70, 0x400, v74
	ds_write2_b32 v70, v58, v56 offset0:16 offset1:84
	v_mov_b32_e32 v56, v52
; __device__ __forceinline__ void hgrn_pre_phase(KP p, char* smem, int wv, const int seg, const int gw, const int nw) {
;     ...
;     const float ec0 = __expf(c0), ec1 = __expf(c1);
; #pragma unroll
;     for (int i = 0; i < 16; ++i) {
;       const float e0 = __expf(lb0[i]), e1 = __expf(lb1[i]);
;       const float k0 = (1.f - fv[i].x) * __frcp_rn(e0), k1 = (1.f - fv[i].y) * __frcp_rn(e1);
;       const unsigned qt = (unsigned)f2bf(qv[i].x * e0) | ((unsigned)f2bf(qv[i].y * e1) << 16);
;       const unsigned kt = (unsigned)f2bf(k0) | ((unsigned)f2bf(k1) << 16);
;       *(unsigned*)(wl + i * 136 + lane * 2) = qt;
;       *(unsigned*)(wl + 2176 + i * 136 + lane * 2) = kt;
;       kh0[i] = f2bf(k0 * ec0);
;       kh1[i] = f2bf(k1 * ec1);
;     }
	v_div_scale_f32 v52, s[22:23], v63, v63, 1.0
	v_mov_b32_e32 v57, v54
	v_rcp_f32_e32 v54, v52
	v_pk_add_f32 v[56:57], v[56:57], 1.0 op_sel_hi:[1,0] neg_lo:[1,0] neg_hi:[1,0]
	v_fma_f32 v58, -v52, v54, 1.0
	v_fmac_f32_e32 v54, v58, v54
	v_div_scale_f32 v58, vcc, 1.0, v63, 1.0
	v_mul_f32_e32 v71, v58, v54
	v_fma_f32 v72, -v52, v71, v58
	v_fmac_f32_e32 v71, v72, v54
	v_fma_f32 v52, -v52, v71, v58
	v_div_fmas_f32 v52, v52, v54, v71
	v_div_fixup_f32 v58, v52, v63, 1.0
	v_div_scale_f32 v52, s[22:23], v59, v59, 1.0
	v_rcp_f32_e32 v54, v52
	s_nop 0
	v_fma_f32 v63, -v52, v54, 1.0
	v_fmac_f32_e32 v54, v63, v54
	v_div_scale_f32 v63, vcc, 1.0, v59, 1.0
	v_mul_f32_e32 v71, v63, v54
	v_fma_f32 v72, -v52, v71, v63
	v_fmac_f32_e32 v71, v72, v54
	v_fma_f32 v52, -v52, v71, v63
	v_div_fmas_f32 v52, v52, v54, v71
	v_div_fixup_f32 v59, v52, v59, 1.0
	v_pk_mul_f32 v[56:57], v[56:57], v[58:59]
	v_mov_b32_e32 v54, v53
	v_bfe_u32 v52, v56, 16, 1
	v_add3_u32 v52, v56, v52, s97
	v_lshrrev_b32_e32 v58, 16, v52
	v_bfe_u32 v52, v57, 16, 1
	v_add3_u32 v52, v57, v52, s97
	v_lshrrev_b32_e32 v59, 16, v52
	v_pk_add_f32 v[52:53], v[54:55], 1.0 op_sel_hi:[1,0] neg_lo:[1,0] neg_hi:[1,0]
	v_div_scale_f32 v54, s[22:23], v68, v68, 1.0
	v_rcp_f32_e32 v55, v54
	v_pk_mul_f32 v[56:57], v[56:57], v[16:17] op_sel_hi:[1,0]
	v_fma_f32 v63, -v54, v55, 1.0
	v_fmac_f32_e32 v55, v63, v55
	v_div_scale_f32 v63, vcc, 1.0, v68, 1.0
	v_mul_f32_e32 v71, v63, v55
	v_fma_f32 v72, -v54, v71, v63
	v_fmac_f32_e32 v71, v72, v55
	v_fma_f32 v54, -v54, v71, v63
	v_div_fmas_f32 v54, v54, v55, v71
	v_div_scale_f32 v55, s[22:23], v69, v69, 1.0
	v_rcp_f32_e32 v63, v55
	v_div_fixup_f32 v54, v54, v68, 1.0
	v_fma_f32 v68, -v55, v63, 1.0
	v_fmac_f32_e32 v63, v68, v63
	v_div_scale_f32 v68, vcc, 1.0, v69, 1.0
	v_mul_f32_e32 v71, v68, v63
	v_fma_f32 v72, -v55, v71, v68
	v_fmac_f32_e32 v71, v72, v63
	v_fma_f32 v55, -v55, v71, v68
	v_div_fmas_f32 v55, v55, v63, v71
	v_div_fixup_f32 v55, v55, v69, 1.0
	v_pk_mul_f32 v[52:53], v[52:53], v[54:55]
	s_nop 0
	v_bfe_u32 v54, v52, 16, 1
	v_bfe_u32 v55, v53, 16, 1
	v_add3_u32 v54, v52, v54, s97
	v_add3_u32 v55, v53, v55, s97
	v_and_or_b32 v54, v54, s48, v58
	v_and_or_b32 v55, v55, s48, v59
	v_add_u32_e32 v58, 0x1400, v74
	ds_write2_b32 v58, v54, v55 offset0:80 offset1:148
	v_mul_f32_e32 v54, 0x3fb8aa3b, v94
	v_exp_f32_e32 v54, v54
	v_mul_f32_e32 v55, 0x3fb8aa3b, v95
	v_exp_f32_e32 v55, v55
	v_pk_mul_f32 v[52:53], v[52:53], v[62:63] op_sel_hi:[1,0]
	v_mul_f32_e32 v50, v50, v54
	v_bfe_u32 v58, v50, 16, 1
	v_mul_f32_e32 v51, v51, v55
	v_add3_u32 v50, v50, v58, s97
	v_bfe_u32 v58, v51, 16, 1
	v_lshrrev_b32_e32 v50, 16, v50
	v_add3_u32 v51, v51, v58, s97
	v_and_or_b32 v50, v51, s48, v50
	v_mul_f32_e32 v51, 0x3fb8aa3b, v96
	v_exp_f32_e32 v51, v51
	v_mul_f32_e32 v58, 0x3fb8aa3b, v97
	v_exp_f32_e32 v58, v58
	v_mul_f32_e32 v48, v48, v51
	v_bfe_u32 v59, v48, 16, 1
	v_mul_f32_e32 v49, v49, v58
	v_add3_u32 v48, v48, v59, s97
	v_bfe_u32 v59, v49, 16, 1
	v_lshrrev_b32_e32 v48, 16, v48
	v_add3_u32 v49, v49, v59, s97
	v_and_or_b32 v48, v49, s48, v48
	ds_write2_b32 v70, v50, v48 offset0:152 offset1:220
	v_mov_b32_e32 v48, v44
	v_div_scale_f32 v44, s[22:23], v54, v54, 1.0
	v_mov_b32_e32 v49, v46
	v_rcp_f32_e32 v46, v44
	v_pk_add_f32 v[48:49], v[48:49], 1.0 op_sel_hi:[1,0] neg_lo:[1,0] neg_hi:[1,0]
	v_fma_f32 v50, -v44, v46, 1.0
	v_fmac_f32_e32 v46, v50, v46
	v_div_scale_f32 v50, vcc, 1.0, v54, 1.0
	v_mul_f32_e32 v59, v50, v46
	v_fma_f32 v63, -v44, v59, v50
	v_fmac_f32_e32 v59, v63, v46
	v_fma_f32 v44, -v44, v59, v50
	v_div_fmas_f32 v44, v44, v46, v59
	v_div_fixup_f32 v50, v44, v54, 1.0
	v_div_scale_f32 v44, s[22:23], v51, v51, 1.0
	v_rcp_f32_e32 v46, v44
	s_nop 0
	v_fma_f32 v54, -v44, v46, 1.0
	v_fmac_f32_e32 v46, v54, v46
	v_div_scale_f32 v54, vcc, 1.0, v51, 1.0
	v_mul_f32_e32 v59, v54, v46
	v_fma_f32 v63, -v44, v59, v54
	v_fmac_f32_e32 v59, v63, v46
	v_fma_f32 v44, -v44, v59, v54
	v_div_fmas_f32 v44, v44, v46, v59
	v_div_fixup_f32 v51, v44, v51, 1.0
	v_pk_mul_f32 v[48:49], v[48:49], v[50:51]
	v_mov_b32_e32 v46, v45
	v_bfe_u32 v44, v48, 16, 1
	v_add3_u32 v44, v48, v44, s97
	v_lshrrev_b32_e32 v50, 16, v44
	v_bfe_u32 v44, v49, 16, 1
	v_add3_u32 v44, v49, v44, s97
	v_lshrrev_b32_e32 v51, 16, v44
	v_pk_add_f32 v[44:45], v[46:47], 1.0 op_sel_hi:[1,0] neg_lo:[1,0] neg_hi:[1,0]
	v_div_scale_f32 v46, s[22:23], v55, v55, 1.0
	v_rcp_f32_e32 v47, v46
	v_pk_mul_f32 v[48:49], v[48:49], v[16:17] op_sel_hi:[1,0]
	v_fma_f32 v54, -v46, v47, 1.0
	v_fmac_f32_e32 v47, v54, v47
	v_div_scale_f32 v54, vcc, 1.0, v55, 1.0
	v_mul_f32_e32 v59, v54, v47
	v_fma_f32 v63, -v46, v59, v54
	v_fmac_f32_e32 v59, v63, v47
	v_fma_f32 v46, -v46, v59, v54
	v_div_fmas_f32 v46, v46, v47, v59
	v_div_scale_f32 v47, s[22:23], v58, v58, 1.0
	v_rcp_f32_e32 v54, v47
	v_div_fixup_f32 v46, v46, v55, 1.0
	v_fma_f32 v55, -v47, v54, 1.0
	v_fmac_f32_e32 v54, v55, v54
	v_div_scale_f32 v55, vcc, 1.0, v58, 1.0
	v_mul_f32_e32 v59, v55, v54
	v_fma_f32 v63, -v47, v59, v55
	v_fmac_f32_e32 v59, v63, v54
	v_fma_f32 v47, -v47, v59, v55
	v_div_fmas_f32 v47, v47, v54, v59
	v_div_fixup_f32 v47, v47, v58, 1.0
	v_pk_mul_f32 v[44:45], v[44:45], v[46:47]
	s_nop 0
	v_bfe_u32 v46, v44, 16, 1
	v_bfe_u32 v47, v45, 16, 1
	v_add3_u32 v46, v44, v46, s97
	v_add3_u32 v47, v45, v47, s97
	v_and_or_b32 v46, v46, s48, v50
	v_and_or_b32 v47, v47, s48, v51
	v_add_u32_e32 v50, 0x1600, v74
	ds_write2_b32 v50, v46, v47 offset0:88 offset1:156
	v_mul_f32_e32 v46, 0x3fb8aa3b, v90
	v_exp_f32_e32 v46, v46
	v_mul_f32_e32 v47, 0x3fb8aa3b, v91
	v_exp_f32_e32 v47, v47
	v_pk_mul_f32 v[44:45], v[44:45], v[62:63] op_sel_hi:[1,0]
	v_mul_f32_e32 v42, v42, v46
	v_bfe_u32 v50, v42, 16, 1
; __device__ __forceinline__ void hgrn_pre_phase(KP p, char* smem, int wv, const int seg, const int gw, const int nw) {
;     ...
;     const float ec0 = __expf(c0), ec1 = __expf(c1);
; #pragma unroll
;     for (int i = 0; i < 16; ++i) {
;       const float e0 = __expf(lb0[i]), e1 = __expf(lb1[i]);
;       const float k0 = (1.f - fv[i].x) * __frcp_rn(e0), k1 = (1.f - fv[i].y) * __frcp_rn(e1);
;       const unsigned qt = (unsigned)f2bf(qv[i].x * e0) | ((unsigned)f2bf(qv[i].y * e1) << 16);
;       const unsigned kt = (unsigned)f2bf(k0) | ((unsigned)f2bf(k1) << 16);
;       *(unsigned*)(wl + i * 136 + lane * 2) = qt;
;       *(unsigned*)(wl + 2176 + i * 136 + lane * 2) = kt;
;       kh0[i] = f2bf(k0 * ec0);
;       kh1[i] = f2bf(k1 * ec1);
;     }
	v_mul_f32_e32 v43, v43, v47
	v_add3_u32 v42, v42, v50, s97
	v_bfe_u32 v50, v43, 16, 1
	v_lshrrev_b32_e32 v42, 16, v42
	v_add3_u32 v43, v43, v50, s97
	v_and_or_b32 v42, v43, s48, v42
	v_mul_f32_e32 v43, 0x3fb8aa3b, v92
	v_exp_f32_e32 v43, v43
	v_mul_f32_e32 v50, 0x3fb8aa3b, v93
	v_exp_f32_e32 v50, v50
	v_mul_f32_e32 v40, v40, v43
	v_bfe_u32 v51, v40, 16, 1
	v_mul_f32_e32 v41, v41, v50
	v_add3_u32 v40, v40, v51, s97
	v_bfe_u32 v51, v41, 16, 1
	v_lshrrev_b32_e32 v40, 16, v40
	v_add3_u32 v41, v41, v51, s97
	v_and_or_b32 v40, v41, s48, v40
	v_add_u32_e32 v51, 0x800, v74
	ds_write2_b32 v51, v42, v40 offset0:32 offset1:100
	v_mov_b32_e32 v40, v36
	v_div_scale_f32 v36, s[22:23], v46, v46, 1.0
	v_mov_b32_e32 v41, v38
	v_rcp_f32_e32 v38, v36
	v_pk_add_f32 v[40:41], v[40:41], 1.0 op_sel_hi:[1,0] neg_lo:[1,0] neg_hi:[1,0]
	v_fma_f32 v42, -v36, v38, 1.0
	v_fmac_f32_e32 v38, v42, v38
	v_div_scale_f32 v42, vcc, 1.0, v46, 1.0
	v_mul_f32_e32 v54, v42, v38
	v_fma_f32 v55, -v36, v54, v42
	v_fmac_f32_e32 v54, v55, v38
	v_fma_f32 v36, -v36, v54, v42
	v_div_fmas_f32 v36, v36, v38, v54
	v_div_fixup_f32 v42, v36, v46, 1.0
	v_div_scale_f32 v36, s[22:23], v43, v43, 1.0
	v_rcp_f32_e32 v38, v36
	s_nop 0
	v_fma_f32 v46, -v36, v38, 1.0
	v_fmac_f32_e32 v38, v46, v38
	v_div_scale_f32 v46, vcc, 1.0, v43, 1.0
	v_mul_f32_e32 v54, v46, v38
	v_fma_f32 v55, -v36, v54, v46
	v_fmac_f32_e32 v54, v55, v38
	v_fma_f32 v36, -v36, v54, v46
	v_div_fmas_f32 v36, v36, v38, v54
	v_div_fixup_f32 v43, v36, v43, 1.0
	v_pk_mul_f32 v[40:41], v[40:41], v[42:43]
	v_mov_b32_e32 v38, v37
	v_bfe_u32 v36, v40, 16, 1
	v_add3_u32 v36, v40, v36, s97
	v_lshrrev_b32_e32 v42, 16, v36
	v_bfe_u32 v36, v41, 16, 1
	v_add3_u32 v36, v41, v36, s97
	v_lshrrev_b32_e32 v43, 16, v36
	v_pk_add_f32 v[36:37], v[38:39], 1.0 op_sel_hi:[1,0] neg_lo:[1,0] neg_hi:[1,0]
	v_div_scale_f32 v38, s[22:23], v47, v47, 1.0
	v_rcp_f32_e32 v39, v38
	v_pk_mul_f32 v[40:41], v[40:41], v[16:17] op_sel_hi:[1,0]
	v_fma_f32 v46, -v38, v39, 1.0
	v_fmac_f32_e32 v39, v46, v39
	v_div_scale_f32 v46, vcc, 1.0, v47, 1.0
	v_mul_f32_e32 v54, v46, v39
	v_fma_f32 v55, -v38, v54, v46
	v_fmac_f32_e32 v54, v55, v39
	v_fma_f32 v38, -v38, v54, v46
	v_div_fmas_f32 v38, v38, v39, v54
	v_div_scale_f32 v39, s[22:23], v50, v50, 1.0
	v_rcp_f32_e32 v46, v39
	v_div_fixup_f32 v38, v38, v47, 1.0
	v_fma_f32 v47, -v39, v46, 1.0
	v_fmac_f32_e32 v46, v47, v46
	v_div_scale_f32 v47, vcc, 1.0, v50, 1.0
	v_mul_f32_e32 v54, v47, v46
	v_fma_f32 v55, -v39, v54, v47
	v_fmac_f32_e32 v54, v55, v46
	v_fma_f32 v39, -v39, v54, v47
	v_div_fmas_f32 v39, v39, v46, v54
	v_div_fixup_f32 v39, v39, v50, 1.0
	v_pk_mul_f32 v[36:37], v[36:37], v[38:39]
	s_nop 0
	v_bfe_u32 v38, v36, 16, 1
	v_bfe_u32 v39, v37, 16, 1
	v_add3_u32 v38, v36, v38, s97
	v_add3_u32 v39, v37, v39, s97
	v_and_or_b32 v38, v38, s48, v42
	v_and_or_b32 v39, v39, s48, v43
	v_add_u32_e32 v42, 0x1800, v74
	ds_write2_b32 v42, v38, v39 offset0:96 offset1:164
	v_mul_f32_e32 v38, 0x3fb8aa3b, v86
	v_exp_f32_e32 v38, v38
	v_mul_f32_e32 v39, 0x3fb8aa3b, v87
	v_exp_f32_e32 v39, v39
	v_pk_mul_f32 v[36:37], v[36:37], v[62:63] op_sel_hi:[1,0]
	v_mul_f32_e32 v34, v34, v38
	v_bfe_u32 v42, v34, 16, 1
	v_mul_f32_e32 v35, v35, v39
	v_add3_u32 v34, v34, v42, s97
	v_bfe_u32 v42, v35, 16, 1
	v_lshrrev_b32_e32 v34, 16, v34
	v_add3_u32 v35, v35, v42, s97
	v_and_or_b32 v34, v35, s48, v34
	v_mul_f32_e32 v35, 0x3fb8aa3b, v88
	v_exp_f32_e32 v35, v35
	v_mul_f32_e32 v42, 0x3fb8aa3b, v89
	v_exp_f32_e32 v42, v42
	v_mul_f32_e32 v32, v32, v35
	v_bfe_u32 v43, v32, 16, 1
	v_mul_f32_e32 v33, v33, v42
	v_add3_u32 v32, v32, v43, s97
	v_bfe_u32 v43, v33, 16, 1
	v_lshrrev_b32_e32 v32, 16, v32
	v_add3_u32 v33, v33, v43, s97
	v_and_or_b32 v32, v33, s48, v32
	ds_write2_b32 v51, v34, v32 offset0:168 offset1:236
	v_mov_b32_e32 v32, v28
	v_div_scale_f32 v28, s[22:23], v38, v38, 1.0
	v_mov_b32_e32 v33, v30
	v_rcp_f32_e32 v30, v28
	v_pk_add_f32 v[32:33], v[32:33], 1.0 op_sel_hi:[1,0] neg_lo:[1,0] neg_hi:[1,0]
	v_fma_f32 v34, -v28, v30, 1.0
	v_fmac_f32_e32 v30, v34, v30
	v_div_scale_f32 v34, vcc, 1.0, v38, 1.0
	v_mul_f32_e32 v43, v34, v30
	v_fma_f32 v46, -v28, v43, v34
	v_fmac_f32_e32 v43, v46, v30
	v_fma_f32 v28, -v28, v43, v34
	v_div_fmas_f32 v28, v28, v30, v43
	v_div_fixup_f32 v34, v28, v38, 1.0
	v_div_scale_f32 v28, s[22:23], v35, v35, 1.0
	v_rcp_f32_e32 v30, v28
	s_nop 0
	v_fma_f32 v38, -v28, v30, 1.0
	v_fmac_f32_e32 v30, v38, v30
	v_div_scale_f32 v38, vcc, 1.0, v35, 1.0
	v_mul_f32_e32 v43, v38, v30
	v_fma_f32 v46, -v28, v43, v38
	v_fmac_f32_e32 v43, v46, v30
	v_fma_f32 v28, -v28, v43, v38
	v_div_fmas_f32 v28, v28, v30, v43
	v_div_fixup_f32 v35, v28, v35, 1.0
	v_pk_mul_f32 v[32:33], v[32:33], v[34:35]
	v_mov_b32_e32 v30, v29
	v_bfe_u32 v28, v32, 16, 1
	v_add3_u32 v28, v32, v28, s97
	v_lshrrev_b32_e32 v34, 16, v28
	v_bfe_u32 v28, v33, 16, 1
	v_add3_u32 v28, v33, v28, s97
	v_lshrrev_b32_e32 v35, 16, v28
	v_pk_add_f32 v[28:29], v[30:31], 1.0 op_sel_hi:[1,0] neg_lo:[1,0] neg_hi:[1,0]
	v_div_scale_f32 v30, s[22:23], v39, v39, 1.0
	v_rcp_f32_e32 v31, v30
	v_pk_mul_f32 v[32:33], v[32:33], v[16:17] op_sel_hi:[1,0]
	v_fma_f32 v38, -v30, v31, 1.0
	v_fmac_f32_e32 v31, v38, v31
	v_div_scale_f32 v38, vcc, 1.0, v39, 1.0
	v_mul_f32_e32 v43, v38, v31
	v_fma_f32 v46, -v30, v43, v38
	v_fmac_f32_e32 v43, v46, v31
	v_fma_f32 v30, -v30, v43, v38
	v_div_fmas_f32 v30, v30, v31, v43
	v_div_scale_f32 v31, s[22:23], v42, v42, 1.0
	v_rcp_f32_e32 v38, v31
	v_div_fixup_f32 v30, v30, v39, 1.0
	v_fma_f32 v39, -v31, v38, 1.0
	v_fmac_f32_e32 v38, v39, v38
	v_div_scale_f32 v39, vcc, 1.0, v42, 1.0
	v_mul_f32_e32 v43, v39, v38
	v_fma_f32 v46, -v31, v43, v39
	v_fmac_f32_e32 v43, v46, v38
; __device__ __forceinline__ void hgrn_pre_phase(KP p, char* smem, int wv, const int seg, const int gw, const int nw) {
;     ...
;     const float ec0 = __expf(c0), ec1 = __expf(c1);
; #pragma unroll
;     for (int i = 0; i < 16; ++i) {
;       const float e0 = __expf(lb0[i]), e1 = __expf(lb1[i]);
;       const float k0 = (1.f - fv[i].x) * __frcp_rn(e0), k1 = (1.f - fv[i].y) * __frcp_rn(e1);
;       const unsigned qt = (unsigned)f2bf(qv[i].x * e0) | ((unsigned)f2bf(qv[i].y * e1) << 16);
;       const unsigned kt = (unsigned)f2bf(k0) | ((unsigned)f2bf(k1) << 16);
;       *(unsigned*)(wl + i * 136 + lane * 2) = qt;
;       *(unsigned*)(wl + 2176 + i * 136 + lane * 2) = kt;
;       kh0[i] = f2bf(k0 * ec0);
;       kh1[i] = f2bf(k1 * ec1);
;     }
	v_fma_f32 v31, -v31, v43, v39
	v_div_fmas_f32 v31, v31, v38, v43
	v_div_fixup_f32 v31, v31, v42, 1.0
	v_pk_mul_f32 v[28:29], v[28:29], v[30:31]
	s_nop 0
	v_bfe_u32 v30, v28, 16, 1
	v_bfe_u32 v31, v29, 16, 1
	v_add3_u32 v30, v28, v30, s97
	v_add3_u32 v31, v29, v31, s97
	v_and_or_b32 v30, v30, s48, v34
	v_and_or_b32 v31, v31, s48, v35
	v_add_u32_e32 v34, 0x1a00, v74
	ds_write2_b32 v34, v30, v31 offset0:104 offset1:172
	v_mul_f32_e32 v30, 0x3fb8aa3b, v82
	v_exp_f32_e32 v30, v30
	v_mul_f32_e32 v31, 0x3fb8aa3b, v83
	v_exp_f32_e32 v31, v31
	v_pk_mul_f32 v[28:29], v[28:29], v[62:63] op_sel_hi:[1,0]
	v_mul_f32_e32 v26, v26, v30
	v_bfe_u32 v34, v26, 16, 1
	v_mul_f32_e32 v27, v27, v31
	v_add3_u32 v26, v26, v34, s97
	v_bfe_u32 v34, v27, 16, 1
	v_lshrrev_b32_e32 v26, 16, v26
	v_add3_u32 v27, v27, v34, s97
	v_and_or_b32 v26, v27, s48, v26
	v_mul_f32_e32 v27, 0x3fb8aa3b, v84
	v_exp_f32_e32 v27, v27
	v_mul_f32_e32 v34, 0x3fb8aa3b, v85
	v_exp_f32_e32 v34, v34
	v_mul_f32_e32 v24, v24, v27
	v_bfe_u32 v35, v24, 16, 1
	v_mul_f32_e32 v25, v25, v34
	v_add3_u32 v24, v24, v35, s97
	v_bfe_u32 v35, v25, 16, 1
	v_lshrrev_b32_e32 v24, 16, v24
	v_add3_u32 v25, v25, v35, s97
	v_and_or_b32 v24, v25, s48, v24
	v_add_u32_e32 v35, 0xc00, v74
	ds_write2_b32 v35, v26, v24 offset0:48 offset1:116
	v_mov_b32_e32 v24, v12
	v_div_scale_f32 v12, s[22:23], v30, v30, 1.0
	v_mov_b32_e32 v25, v14
	v_rcp_f32_e32 v14, v12
	v_pk_add_f32 v[24:25], v[24:25], 1.0 op_sel_hi:[1,0] neg_lo:[1,0] neg_hi:[1,0]
	v_fma_f32 v26, -v12, v14, 1.0
	v_fmac_f32_e32 v14, v26, v14
	v_div_scale_f32 v26, vcc, 1.0, v30, 1.0
	v_mul_f32_e32 v38, v26, v14
	v_fma_f32 v39, -v12, v38, v26
	v_fmac_f32_e32 v38, v39, v14
	v_fma_f32 v12, -v12, v38, v26
	v_div_fmas_f32 v12, v12, v14, v38
	v_div_fixup_f32 v26, v12, v30, 1.0
	v_div_scale_f32 v12, s[22:23], v27, v27, 1.0
	v_rcp_f32_e32 v14, v12
	s_nop 0
	v_fma_f32 v30, -v12, v14, 1.0
	v_fmac_f32_e32 v14, v30, v14
	v_div_scale_f32 v30, vcc, 1.0, v27, 1.0
	v_mul_f32_e32 v38, v30, v14
	v_fma_f32 v39, -v12, v38, v30
	v_fmac_f32_e32 v38, v39, v14
	v_fma_f32 v12, -v12, v38, v30
	v_div_fmas_f32 v12, v12, v14, v38
	v_div_fixup_f32 v27, v12, v27, 1.0
	v_pk_mul_f32 v[24:25], v[24:25], v[26:27]
	v_mov_b32_e32 v14, v13
	v_bfe_u32 v12, v24, 16, 1
	v_add3_u32 v12, v24, v12, s97
	v_lshrrev_b32_e32 v26, 16, v12
	v_bfe_u32 v12, v25, 16, 1
	v_add3_u32 v12, v25, v12, s97
	v_lshrrev_b32_e32 v27, 16, v12
	v_pk_add_f32 v[12:13], v[14:15], 1.0 op_sel_hi:[1,0] neg_lo:[1,0] neg_hi:[1,0]
	v_div_scale_f32 v14, s[22:23], v31, v31, 1.0
	v_rcp_f32_e32 v15, v14
	v_pk_mul_f32 v[24:25], v[24:25], v[16:17] op_sel_hi:[1,0]
	v_fma_f32 v30, -v14, v15, 1.0
	v_fmac_f32_e32 v15, v30, v15
	v_div_scale_f32 v30, vcc, 1.0, v31, 1.0
	v_mul_f32_e32 v38, v30, v15
	v_fma_f32 v39, -v14, v38, v30
	v_fmac_f32_e32 v38, v39, v15
	v_fma_f32 v14, -v14, v38, v30
	v_div_fmas_f32 v14, v14, v15, v38
	v_div_scale_f32 v15, s[22:23], v34, v34, 1.0
	v_rcp_f32_e32 v30, v15
	v_div_fixup_f32 v14, v14, v31, 1.0
	v_fma_f32 v31, -v15, v30, 1.0
	v_fmac_f32_e32 v30, v31, v30
	v_div_scale_f32 v31, vcc, 1.0, v34, 1.0
	v_mul_f32_e32 v38, v31, v30
	v_fma_f32 v39, -v15, v38, v31
	v_fmac_f32_e32 v38, v39, v30
	v_fma_f32 v15, -v15, v38, v31
	v_div_fmas_f32 v15, v15, v30, v38
	v_div_fixup_f32 v15, v15, v34, 1.0
	v_pk_mul_f32 v[12:13], v[12:13], v[14:15]
	s_nop 0
	v_bfe_u32 v14, v12, 16, 1
	v_bfe_u32 v15, v13, 16, 1
	v_add3_u32 v14, v12, v14, s97
	v_add3_u32 v15, v13, v15, s97
	v_and_or_b32 v14, v14, s48, v26
	v_and_or_b32 v15, v15, s48, v27
	v_add_u32_e32 v26, 0x1c00, v74
	ds_write2_b32 v26, v14, v15 offset0:112 offset1:180
	v_pk_mul_f32 v[14:15], v[12:13], v[62:63] op_sel_hi:[1,0]
	v_mul_f32_e32 v12, 0x3fb8aa3b, v80
	v_exp_f32_e32 v12, v12
	v_mul_f32_e32 v13, 0x3fb8aa3b, v81
	v_exp_f32_e32 v13, v13
	v_bfe_u32 v31, v14, 16, 1
	v_mul_f32_e32 v8, v8, v12
	v_bfe_u32 v26, v8, 16, 1
	v_mul_f32_e32 v9, v9, v13
	v_add3_u32 v8, v8, v26, s97
	v_bfe_u32 v26, v9, 16, 1
	v_lshrrev_b32_e32 v8, 16, v8
	v_add3_u32 v9, v9, v26, s97
	v_and_or_b32 v8, v9, s48, v8
	v_bfe_u32 v9, v6, 16, 1
	v_add3_u32 v6, v6, v9, s97
	v_bfe_u32 v9, v7, 16, 1
	v_lshrrev_b32_e32 v6, 16, v6
	v_add3_u32 v7, v7, v9, s97
	v_and_or_b32 v6, v7, s48, v6
	ds_write2_b32 v35, v8, v6 offset0:184 offset1:252
	v_mov_b32_e32 v6, v2
	v_div_scale_f32 v2, s[22:23], v12, v12, 1.0
	v_mov_b32_e32 v7, v4
	v_rcp_f32_e32 v4, v2
	v_pk_add_f32 v[6:7], v[6:7], 1.0 op_sel_hi:[1,0] neg_lo:[1,0] neg_hi:[1,0]
	v_bfe_u32 v30, v15, 16, 1
	v_add3_u32 v30, v15, v30, s97
	v_fma_f32 v8, -v2, v4, 1.0
	v_fmac_f32_e32 v4, v8, v4
	v_div_scale_f32 v8, vcc, 1.0, v12, 1.0
	v_mul_f32_e32 v9, v8, v4
	v_fma_f32 v26, -v2, v9, v8
	v_fmac_f32_e32 v9, v26, v4
	v_fma_f32 v2, -v2, v9, v8
	v_div_fmas_f32 v2, v2, v4, v9
	v_div_fixup_f32 v8, v2, v12, 1.0
	v_div_scale_f32 v2, s[22:23], v16, v16, 1.0
	v_rcp_f32_e32 v4, v2
	s_nop 0
	v_fma_f32 v9, -v2, v4, 1.0
	v_fmac_f32_e32 v4, v9, v4
	v_div_scale_f32 v9, vcc, 1.0, v16, 1.0
	v_mul_f32_e32 v12, v9, v4
	v_fma_f32 v26, -v2, v12, v9
	v_fmac_f32_e32 v12, v26, v4
	v_fma_f32 v2, -v2, v12, v9
	v_div_fmas_f32 v2, v2, v4, v12
	v_div_fixup_f32 v9, v2, v16, 1.0
	v_pk_mul_f32 v[6:7], v[6:7], v[8:9]
	v_mov_b32_e32 v4, v3
	v_bfe_u32 v2, v6, 16, 1
	v_add3_u32 v2, v6, v2, s97
	v_lshrrev_b32_e32 v8, 16, v2
	v_bfe_u32 v2, v7, 16, 1
	v_add3_u32 v2, v7, v2, s97
	v_lshrrev_b32_e32 v9, 16, v2
	v_pk_add_f32 v[2:3], v[4:5], 1.0 op_sel_hi:[1,0] neg_lo:[1,0] neg_hi:[1,0]
	v_div_scale_f32 v4, s[22:23], v13, v13, 1.0
; __device__ __forceinline__ void hgrn_pre_phase(KP p, char* smem, int wv, const int seg, const int gw, const int nw) {
;     ...
;     {
;       const int ch0 = lane * 2, ch1 = ch0 + 1;
;       bf16x8 a, bq, cc, dd;
; #pragma unroll
;       for (int j = 0; j < 8; ++j) { a[j] = (short)kh0[j]; bq[j] = (short)kh0[8 + j]; cc[j] = (short)kh1[j]; dd[j] = (short)kh1[8 + j]; }
;       char* kb = tb + 4096;
;       *(bf16x8*)(kb + (((ch0 >> 4) * 32) + (ch0 & 15)) * 16) = a;
;       *(bf16x8*)(kb + (((ch0 >> 4) * 32) + 16 + (ch0 & 15)) * 16) = bq;
;       *(bf16x8*)(kb + (((ch1 >> 4) * 32) + (ch1 & 15)) * 16) = cc;
;       *(bf16x8*)(kb + (((ch1 >> 4) * 32) + 16 + (ch1 & 15)) * 16) = dd;
;     }
;     f32x4 acc = {0.f, 0.f, 0.f, 0.f};
; #pragma unroll
;     for (int sidx = 0; sidx < 4; ++sidx) {
;       const bf16x8 af = *(const bf16x8*)(wl + fr * 136 + sidx * 32 + fq * 8);
;       const bf16x8 bfm = *(const bf16x8*)(wl + 2176 + fr * 136 + sidx * 32 + fq * 8);
;       *(bf16x8*)(tb + (sidx * 64 + lane) * 16) = af;
;       acc = __builtin_amdgcn_mfma_f32_16x16x32_bf16(af, bfm, acc, 0, 0, 0);
;     }
;     unsigned short* at = (unsigned short*)(tb + 8192);
; #pragma unroll
;     for (int r = 0; r < 4; ++r) {
;       const int i = 4 * fq + r, j = fr;
;       at[((j >> 3) * 16 + i) * 8 + (j & 7)] = (j <= i) ? f2bf(acc[r]) : (unsigned short)0;
;     }
	v_rcp_f32_e32 v5, v4
	v_pk_mul_f32 v[6:7], v[6:7], v[16:17] op_sel_hi:[1,0]
	v_fma_f32 v12, -v4, v5, 1.0
	v_fmac_f32_e32 v5, v12, v5
	v_div_scale_f32 v12, vcc, 1.0, v13, 1.0
	v_mul_f32_e32 v16, v12, v5
	v_fma_f32 v26, -v4, v16, v12
	v_fmac_f32_e32 v16, v26, v5
	v_fma_f32 v4, -v4, v16, v12
	v_div_fmas_f32 v4, v4, v5, v16
	v_div_scale_f32 v5, s[22:23], v17, v17, 1.0
	v_rcp_f32_e32 v12, v5
	v_div_fixup_f32 v4, v4, v13, 1.0
	v_bfe_u32 v27, v6, 16, 1
	v_add3_u32 v27, v6, v27, s97
	v_fma_f32 v13, -v5, v12, 1.0
	v_fmac_f32_e32 v12, v13, v12
	v_div_scale_f32 v13, vcc, 1.0, v17, 1.0
	v_mul_f32_e32 v16, v13, v12
	v_fma_f32 v26, -v5, v16, v13
	v_fmac_f32_e32 v16, v26, v12
	v_fma_f32 v5, -v5, v16, v13
	v_div_fmas_f32 v5, v5, v12, v16
	v_div_fixup_f32 v5, v5, v17, 1.0
	v_pk_mul_f32 v[2:3], v[2:3], v[4:5]
	v_bfe_u32 v12, v11, 16, 1
	v_bfe_u32 v4, v2, 16, 1
	v_bfe_u32 v5, v3, 16, 1
	v_add3_u32 v4, v2, v4, s97
	v_add3_u32 v5, v3, v5, s97
	v_and_or_b32 v4, v4, s48, v8
	v_and_or_b32 v5, v5, s48, v9
	v_add_u32_e32 v8, 0x1e00, v74
	ds_write2_b32 v8, v4, v5 offset0:120 offset1:188
	v_bfe_u32 v4, v57, 16, 1
	v_bfe_u32 v5, v56, 16, 1
	v_bfe_u32 v8, v49, 16, 1
	v_bfe_u32 v9, v48, 16, 1
	v_pk_mul_f32 v[16:17], v[2:3], v[62:63] op_sel_hi:[1,0]
	v_bfe_u32 v2, v65, 16, 1
	v_bfe_u32 v3, v64, 16, 1
	v_bfe_u32 v13, v10, 16, 1
	v_add3_u32 v9, v48, v9, s97
	v_add3_u32 v8, v49, v8, s97
	v_add3_u32 v5, v56, v5, s97
	v_add3_u32 v4, v57, v4, s97
	v_add3_u32 v3, v64, v3, s97
	v_add3_u32 v2, v65, v2, s97
	v_add3_u32 v10, v10, v13, s97
	v_add3_u32 v11, v11, v12, s97
	v_perm_b32 v4, v4, v5, s49
	v_perm_b32 v5, v8, v9, s49
	v_bfe_u32 v8, v41, 16, 1
	v_bfe_u32 v9, v40, 16, 1
	v_bfe_u32 v12, v25, 16, 1
	v_bfe_u32 v13, v24, 16, 1
	v_perm_b32 v3, v2, v3, s49
	v_perm_b32 v2, v11, v10, s49
	v_bfe_u32 v10, v33, 16, 1
	v_bfe_u32 v11, v32, 16, 1
	v_bfe_u32 v26, v7, 16, 1
	v_add3_u32 v13, v24, v13, s97
	v_add3_u32 v12, v25, v12, s97
	v_add3_u32 v6, v40, v9, s97
	v_add3_u32 v8, v41, v8, s97
	v_add3_u32 v26, v7, v26, s97
	v_add3_u32 v7, v32, v11, s97
	v_add3_u32 v10, v33, v10, s97
	v_perm_b32 v6, v8, v6, s49
	v_perm_b32 v8, v12, v13, s49
	v_bfe_u32 v12, v53, 16, 1
	v_bfe_u32 v13, v52, 16, 1
	v_bfe_u32 v24, v45, 16, 1
	v_bfe_u32 v25, v44, 16, 1
	v_perm_b32 v7, v10, v7, s49
	v_perm_b32 v9, v26, v27, s49
	v_bfe_u32 v10, v67, 16, 1
	v_bfe_u32 v11, v66, 16, 1
	v_bfe_u32 v26, v61, 16, 1
	v_bfe_u32 v27, v60, 16, 1
	v_add3_u32 v25, v44, v25, s97
	v_add3_u32 v24, v45, v24, s97
	v_add3_u32 v13, v52, v13, s97
	v_add3_u32 v12, v53, v12, s97
	v_add3_u32 v11, v66, v11, s97
	v_add3_u32 v10, v67, v10, s97
	v_add3_u32 v27, v60, v27, s97
	v_add3_u32 v26, v61, v26, s97
	v_perm_b32 v12, v12, v13, s49
	v_perm_b32 v13, v24, v25, s49
	v_bfe_u32 v24, v37, 16, 1
	v_bfe_u32 v25, v36, 16, 1
	v_bfe_u32 v33, v16, 16, 1
	v_perm_b32 v11, v10, v11, s49
	v_perm_b32 v10, v26, v27, s49
	v_bfe_u32 v26, v29, 16, 1
	v_bfe_u32 v27, v28, 16, 1
	v_add3_u32 v33, v16, v33, s97
	v_add3_u32 v16, v14, v31, s97
	v_add3_u32 v14, v36, v25, s97
	v_add3_u32 v24, v37, v24, s97
	v_add3_u32 v15, v28, v27, s97
	v_add3_u32 v26, v29, v26, s97
	v_perm_b32 v14, v24, v14, s49
	v_lshl_add_u64 v[24:25], s[14:15], 0, v[20:21]
	v_bfe_u32 v32, v17, 16, 1
	v_perm_b32 v15, v26, v15, s49
	v_lshl_add_u64 v[26:27], v[24:25], 0, s[30:31]
	v_add_co_u32_e32 v24, vcc, s28, v24
	v_add3_u32 v17, v17, v32, s97
	s_nop 0
	v_addc_co_u32_e32 v25, vcc, 0, v25, vcc
	v_perm_b32 v16, v30, v16, s49
	v_perm_b32 v17, v17, v33, s49
	global_store_dwordx4 v[24:25], v[2:5], off
	global_store_dwordx4 v[26:27], v[6:9], off offset:256
	global_store_dwordx4 v[26:27], v[10:13], off offset:16
	global_store_dwordx4 v[26:27], v[14:17], off offset:272
	ds_read_b128 v[2:5], v75
	ds_read_b128 v[6:9], v75 offset:4352
	v_lshl_add_u64 v[14:15], s[14:15], 0, v[22:23]
	s_add_u32 s14, s14, 0x2000
	s_addc_u32 s15, s15, 0
	s_waitcnt lgkmcnt(1)
	global_store_dwordx4 v[14:15], v[2:5], off
	s_add_i32 s5, s5, s53
	s_cmpk_lt_i32 s5, 0x800
	s_waitcnt lgkmcnt(0)
	v_mfma_f32_16x16x32_bf16 v[2:5], v[2:5], v[6:9], 0
	ds_read_b128 v[6:9], v75 offset:64
	ds_read_b128 v[10:13], v75 offset:4416
	s_waitcnt lgkmcnt(1)
	global_store_dwordx4 v[14:15], v[6:9], off offset:1024
	s_waitcnt lgkmcnt(0)
	v_mfma_f32_16x16x32_bf16 v[2:5], v[6:9], v[10:13], v[2:5]
	ds_read_b128 v[6:9], v75 offset:128
	ds_read_b128 v[10:13], v75 offset:4480
	s_waitcnt lgkmcnt(1)
	global_store_dwordx4 v[14:15], v[6:9], off offset:2048
	s_waitcnt lgkmcnt(0)
	v_mfma_f32_16x16x32_bf16 v[2:5], v[6:9], v[10:13], v[2:5]
	ds_read_b128 v[6:9], v75 offset:192
	ds_read_b128 v[10:13], v75 offset:4544
	s_waitcnt lgkmcnt(1)
	global_store_dwordx4 v[14:15], v[6:9], off offset:3072
	s_waitcnt lgkmcnt(0)
	v_mfma_f32_16x16x32_bf16 v[2:5], v[6:9], v[10:13], v[2:5]
	s_nop 7
	v_bfe_u32 v6, v2, 16, 1
	v_add3_u32 v2, v2, v6, s97
	v_lshrrev_b32_e32 v2, 16, v2
	v_cndmask_b32_e64 v2, v2, 0, s[6:7]
	global_store_short v76, v2, s[14:15]
	v_bfe_u32 v2, v3, 16, 1
	v_add3_u32 v2, v3, v2, s97
	v_lshrrev_b32_e32 v2, 16, v2
	v_cndmask_b32_e64 v2, v2, 0, s[8:9]
	global_store_short v77, v2, s[14:15]
	v_bfe_u32 v2, v4, 16, 1
	v_add3_u32 v2, v4, v2, s97
	v_lshrrev_b32_e32 v2, 16, v2
	v_cndmask_b32_e64 v2, v2, 0, s[10:11]
	global_store_short v78, v2, s[14:15]
	v_bfe_u32 v2, v5, 16, 1
	v_add3_u32 v2, v5, v2, s97
	v_lshrrev_b32_e32 v2, 16, v2
	v_cndmask_b32_e64 v2, v2, 0, s[12:13]
	global_store_short v79, v2, s[14:15]
	s_cbranch_scc1 .LBB0_994

; __device__ __forceinline__ void headnorm_phase(KP p, int wv, const int seg, const int gw, const int nw) {
;     ...
;   for (int it = gw; it < items; it += nw) {
;     const int tl = it >> 4, grp = it & 15;
;     const int tok = (tl >> 10) * SEQ + seg * 1024 + (tl & 1023);
;     const int c = grp * 256 + lane * 4;
;     const float4 o = *(const float4*)(p->oraw + (long)tok * 4096 + c);
;     float ss = o.x * o.x + o.y * o.y + o.z * o.z + o.w * o.w;
;     ss = halfsum32(ss, lane);
;     const float rs = rsqrtf(ss * (1.f / 128.f) + 1e-6f);
;     const float4 w = *(const float4*)((grp < 8 ? p->hgrn_nw : p->gdn_nw) + (lane & 31) * 4);
;     const float4 g = (grp < 8) ? *(const float4*)(p->proj + (long)tok * PW + 6144 + c)
;                                : *(const float4*)(p->proj + (long)tok * PW + 12288 + (c - 2048));
.Lhn_c_top:
	s_mul_i32 s21, s37, 7
	s_add_i32 s21, s21, s36
	s_cmp_lt_i32 s21, 0x8000
	s_cbranch_scc0 .Lhn_c_rem
	s_mov_b32 s20, s36
	s_ashr_i32 s12, s20, 2
	s_and_b32 s12, s12, 0xfffff000
	s_bfe_u32 s13, s20, 0xa0004
	s_or_b32 s12, s13, s12
	s_or_b32 s12, s12, 0xc00
	s_ashr_i32 s13, s12, 31
	s_and_b32 s17, s20, 15
	v_lshl_or_b32 v159, s17, 8, v2
	v_lshlrev_b32_e32 v158, 2, v159
	s_lshl_b64 s[18:19], s[12:13], 14
	s_add_u32 s18, s6, s18
	s_addc_u32 s19, s7, s19
	global_load_dwordx4 v[148:151], v158, s[18:19]
	s_cmp_lt_u32 s17, 8
	s_cselect_b32 s17, s8, s10
	s_mul_i32 s18, s12, 0xe080
	s_mul_hi_i32 s19, s12, 0xe080
	s_add_u32 s18, s4, s18
	s_addc_u32 s19, s5, s19
	s_add_u32 s18, s18, s17
	s_addc_u32 s19, s19, 0
	global_load_dwordx4 v[152:155], v158, s[18:19] nt
	s_lshl_b64 s[12:13], s[12:13], 13
	s_add_u32 s12, s2, s12
	s_addc_u32 s13, s3, s13
	v_lshlrev_b32_e32 v156, 1, v159
	v_mov_b32_e32 v157, 0
	v_lshl_add_u64 v[156:157], s[12:13], 0, v[156:157]
	s_add_i32 s20, s20, s37
	s_ashr_i32 s12, s20, 2
	s_and_b32 s12, s12, 0xfffff000
	s_bfe_u32 s13, s20, 0xa0004
	s_or_b32 s12, s13, s12
	s_or_b32 s12, s12, 0xc00
	s_ashr_i32 s13, s12, 31
	s_and_b32 s17, s20, 15
	v_lshl_or_b32 v171, s17, 8, v2
	v_lshlrev_b32_e32 v170, 2, v171
	s_lshl_b64 s[18:19], s[12:13], 14
	s_add_u32 s18, s6, s18
	s_addc_u32 s19, s7, s19
	global_load_dwordx4 v[160:163], v170, s[18:19]
	s_cmp_lt_u32 s17, 8
	s_cselect_b32 s17, s8, s10
	s_mul_i32 s18, s12, 0xe080
	s_mul_hi_i32 s19, s12, 0xe080
	s_add_u32 s18, s4, s18
	s_addc_u32 s19, s5, s19
	s_add_u32 s18, s18, s17
	s_addc_u32 s19, s19, 0
	global_load_dwordx4 v[164:167], v170, s[18:19] nt
	s_lshl_b64 s[12:13], s[12:13], 13
	s_add_u32 s12, s2, s12
	s_addc_u32 s13, s3, s13
	v_lshlrev_b32_e32 v168, 1, v171
	v_mov_b32_e32 v169, 0
	v_lshl_add_u64 v[168:169], s[12:13], 0, v[168:169]
	s_add_i32 s20, s20, s37
	s_ashr_i32 s12, s20, 2
	s_and_b32 s12, s12, 0xfffff000
	s_bfe_u32 s13, s20, 0xa0004
	s_or_b32 s12, s13, s12
	s_or_b32 s12, s12, 0xc00
	s_ashr_i32 s13, s12, 31
	s_and_b32 s17, s20, 15
	v_lshl_or_b32 v183, s17, 8, v2
	v_lshlrev_b32_e32 v182, 2, v183
	s_lshl_b64 s[18:19], s[12:13], 14
	s_add_u32 s18, s6, s18
	s_addc_u32 s19, s7, s19
	global_load_dwordx4 v[172:175], v182, s[18:19]
	s_cmp_lt_u32 s17, 8
	s_cselect_b32 s17, s8, s10
	s_mul_i32 s18, s12, 0xe080
	s_mul_hi_i32 s19, s12, 0xe080
	s_add_u32 s18, s4, s18
	s_addc_u32 s19, s5, s19
	s_add_u32 s18, s18, s17
	s_addc_u32 s19, s19, 0
	global_load_dwordx4 v[176:179], v182, s[18:19] nt
	s_lshl_b64 s[12:13], s[12:13], 13
	s_add_u32 s12, s2, s12
	s_addc_u32 s13, s3, s13
	v_lshlrev_b32_e32 v180, 1, v183
	v_mov_b32_e32 v181, 0
	v_lshl_add_u64 v[180:181], s[12:13], 0, v[180:181]
	s_add_i32 s20, s20, s37
	s_ashr_i32 s12, s20, 2
	s_and_b32 s12, s12, 0xfffff000
	s_bfe_u32 s13, s20, 0xa0004
	s_or_b32 s12, s13, s12
	s_or_b32 s12, s12, 0xc00
	s_ashr_i32 s13, s12, 31
	s_and_b32 s17, s20, 15
	v_lshl_or_b32 v195, s17, 8, v2
	v_lshlrev_b32_e32 v194, 2, v195
	s_lshl_b64 s[18:19], s[12:13], 14
	s_add_u32 s18, s6, s18
	s_addc_u32 s19, s7, s19
	global_load_dwordx4 v[184:187], v194, s[18:19]
	s_cmp_lt_u32 s17, 8
	s_cselect_b32 s17, s8, s10
	s_mul_i32 s18, s12, 0xe080
	s_mul_hi_i32 s19, s12, 0xe080
	s_add_u32 s18, s4, s18
	s_addc_u32 s19, s5, s19
	s_add_u32 s18, s18, s17
	s_addc_u32 s19, s19, 0
	global_load_dwordx4 v[188:191], v194, s[18:19] nt
	s_lshl_b64 s[12:13], s[12:13], 13
	s_add_u32 s12, s2, s12
	s_addc_u32 s13, s3, s13
	v_lshlrev_b32_e32 v192, 1, v195
	v_mov_b32_e32 v193, 0
	v_lshl_add_u64 v[192:193], s[12:13], 0, v[192:193]
	s_add_i32 s20, s20, s37
	s_ashr_i32 s12, s20, 2
	s_and_b32 s12, s12, 0xfffff000
	s_bfe_u32 s13, s20, 0xa0004
	s_or_b32 s12, s13, s12
	s_or_b32 s12, s12, 0xc00
	s_ashr_i32 s13, s12, 31
	s_and_b32 s17, s20, 15
	v_lshl_or_b32 v207, s17, 8, v2
	v_lshlrev_b32_e32 v206, 2, v207
	s_lshl_b64 s[18:19], s[12:13], 14
	s_add_u32 s18, s6, s18
	s_addc_u32 s19, s7, s19
	global_load_dwordx4 v[196:199], v206, s[18:19]
	s_cmp_lt_u32 s17, 8
	s_cselect_b32 s17, s8, s10
	s_mul_i32 s18, s12, 0xe080
	s_mul_hi_i32 s19, s12, 0xe080
	s_add_u32 s18, s4, s18
	s_addc_u32 s19, s5, s19
	s_add_u32 s18, s18, s17
	s_addc_u32 s19, s19, 0
	global_load_dwordx4 v[200:203], v206, s[18:19] nt
	s_lshl_b64 s[12:13], s[12:13], 13
	s_add_u32 s12, s2, s12
	s_addc_u32 s13, s3, s13
	v_lshlrev_b32_e32 v204, 1, v207
	v_mov_b32_e32 v205, 0
	v_lshl_add_u64 v[204:205], s[12:13], 0, v[204:205]
	s_add_i32 s20, s20, s37
	s_ashr_i32 s12, s20, 2
	s_and_b32 s12, s12, 0xfffff000
	s_bfe_u32 s13, s20, 0xa0004
	s_or_b32 s12, s13, s12
	s_or_b32 s12, s12, 0xc00
	s_ashr_i32 s13, s12, 31
	s_and_b32 s17, s20, 15
	v_lshl_or_b32 v219, s17, 8, v2
	v_lshlrev_b32_e32 v218, 2, v219
	s_lshl_b64 s[18:19], s[12:13], 14
	s_add_u32 s18, s6, s18
	s_addc_u32 s19, s7, s19
	global_load_dwordx4 v[208:211], v218, s[18:19]
	s_cmp_lt_u32 s17, 8
	s_cselect_b32 s17, s8, s10
	s_mul_i32 s18, s12, 0xe080
	s_mul_hi_i32 s19, s12, 0xe080
	s_add_u32 s18, s4, s18
	s_addc_u32 s19, s5, s19
	s_add_u32 s18, s18, s17
	s_addc_u32 s19, s19, 0
	global_load_dwordx4 v[212:215], v218, s[18:19] nt
	s_lshl_b64 s[12:13], s[12:13], 13
	s_add_u32 s12, s2, s12
	s_addc_u32 s13, s3, s13
	v_lshlrev_b32_e32 v216, 1, v219
	v_mov_b32_e32 v217, 0
	v_lshl_add_u64 v[216:217], s[12:13], 0, v[216:217]
	s_add_i32 s20, s20, s37
	s_ashr_i32 s12, s20, 2
	s_and_b32 s12, s12, 0xfffff000
	s_bfe_u32 s13, s20, 0xa0004
	s_or_b32 s12, s13, s12
	s_or_b32 s12, s12, 0xc00
	s_ashr_i32 s13, s12, 31
	s_and_b32 s17, s20, 15
	v_lshl_or_b32 v231, s17, 8, v2
	v_lshlrev_b32_e32 v230, 2, v231
	s_lshl_b64 s[18:19], s[12:13], 14
	s_add_u32 s18, s6, s18
	s_addc_u32 s19, s7, s19
	global_load_dwordx4 v[220:223], v230, s[18:19]
	s_cmp_lt_u32 s17, 8
	s_cselect_b32 s17, s8, s10
	s_mul_i32 s18, s12, 0xe080
	s_mul_hi_i32 s19, s12, 0xe080
	s_add_u32 s18, s4, s18
	s_addc_u32 s19, s5, s19
	s_add_u32 s18, s18, s17
	s_addc_u32 s19, s19, 0
	global_load_dwordx4 v[224:227], v230, s[18:19] nt
	s_lshl_b64 s[12:13], s[12:13], 13
	s_add_u32 s12, s2, s12
	s_addc_u32 s13, s3, s13
	v_lshlrev_b32_e32 v228, 1, v231
	v_mov_b32_e32 v229, 0
	v_lshl_add_u64 v[228:229], s[12:13], 0, v[228:229]
	s_add_i32 s20, s20, s37
	s_ashr_i32 s12, s20, 2
	s_and_b32 s12, s12, 0xfffff000
	s_bfe_u32 s13, s20, 0xa0004
	s_or_b32 s12, s13, s12
	s_or_b32 s12, s12, 0xc00
	s_ashr_i32 s13, s12, 31
	s_and_b32 s17, s20, 15
	v_lshl_or_b32 v111, s17, 8, v2
	v_lshlrev_b32_e32 v110, 2, v111
	s_lshl_b64 s[18:19], s[12:13], 14
	s_add_u32 s18, s6, s18
	s_addc_u32 s19, s7, s19
	global_load_dwordx4 v[100:103], v110, s[18:19]
	s_cmp_lt_u32 s17, 8
	s_cselect_b32 s17, s8, s10
	s_mul_i32 s18, s12, 0xe080
	s_mul_hi_i32 s19, s12, 0xe080
	s_add_u32 s18, s4, s18
	s_addc_u32 s19, s5, s19
	s_add_u32 s18, s18, s17
	s_addc_u32 s19, s19, 0
	global_load_dwordx4 v[104:107], v110, s[18:19] nt
	s_lshl_b64 s[12:13], s[12:13], 13
	s_add_u32 s12, s2, s12
	s_addc_u32 s13, s3, s13
	v_lshlrev_b32_e32 v108, 1, v111
	v_mov_b32_e32 v109, 0
	v_lshl_add_u64 v[108:109], s[12:13], 0, v[108:109]
	s_add_i32 s20, s20, s37
	s_waitcnt vmcnt(15)
; __device__ __forceinline__ void headnorm_phase(KP p, int wv, const int seg, const int gw, const int nw) {
;     ...
;     const float4 o = *(const float4*)(p->oraw + (long)tok * 4096 + c);
;     float ss = o.x * o.x + o.y * o.y + o.z * o.z + o.w * o.w;
;     ss = halfsum32(ss, lane);
	v_pk_mul_f32 v[232:233], v[148:149], v[148:149]
	v_pk_mul_f32 v[234:235], v[150:151], v[150:151]
	v_add_f32_e32 v158, v232, v233
	v_add_f32_e32 v158, v158, v234
	v_add_f32_e32 v158, v158, v235
	s_waitcnt vmcnt(13)
	v_pk_mul_f32 v[232:233], v[160:161], v[160:161]
	v_pk_mul_f32 v[234:235], v[162:163], v[162:163]
	v_add_f32_e32 v170, v232, v233
	v_add_f32_e32 v170, v170, v234
	v_add_f32_e32 v170, v170, v235
	s_waitcnt vmcnt(11)
	v_pk_mul_f32 v[232:233], v[172:173], v[172:173]
	v_pk_mul_f32 v[234:235], v[174:175], v[174:175]
	v_add_f32_e32 v182, v232, v233
	v_add_f32_e32 v182, v182, v234
	v_add_f32_e32 v182, v182, v235
	s_waitcnt vmcnt(9)
	v_pk_mul_f32 v[232:233], v[184:185], v[184:185]
	v_pk_mul_f32 v[234:235], v[186:187], v[186:187]
	v_add_f32_e32 v194, v232, v233
	v_add_f32_e32 v194, v194, v234
	v_add_f32_e32 v194, v194, v235
	s_waitcnt vmcnt(7)
	v_pk_mul_f32 v[232:233], v[196:197], v[196:197]
	v_pk_mul_f32 v[234:235], v[198:199], v[198:199]
	v_add_f32_e32 v206, v232, v233
	v_add_f32_e32 v206, v206, v234
	v_add_f32_e32 v206, v206, v235
	s_waitcnt vmcnt(5)
	v_pk_mul_f32 v[232:233], v[208:209], v[208:209]
	v_pk_mul_f32 v[234:235], v[210:211], v[210:211]
	v_add_f32_e32 v218, v232, v233
	v_add_f32_e32 v218, v218, v234
	v_add_f32_e32 v218, v218, v235
	s_waitcnt vmcnt(3)
	v_pk_mul_f32 v[232:233], v[220:221], v[220:221]
	v_pk_mul_f32 v[234:235], v[222:223], v[222:223]
	v_add_f32_e32 v230, v232, v233
	v_add_f32_e32 v230, v230, v234
	v_add_f32_e32 v230, v230, v235
	s_waitcnt vmcnt(1)
	v_pk_mul_f32 v[232:233], v[100:101], v[100:101]
	v_pk_mul_f32 v[234:235], v[102:103], v[102:103]
	v_add_f32_e32 v110, v232, v233
	v_add_f32_e32 v110, v110, v234
	v_add_f32_e32 v110, v110, v235
	ds_bpermute_b32 v159, v3, v158
	ds_bpermute_b32 v171, v3, v170
	ds_bpermute_b32 v183, v3, v182
	ds_bpermute_b32 v195, v3, v194
	ds_bpermute_b32 v207, v3, v206
	ds_bpermute_b32 v219, v3, v218
	ds_bpermute_b32 v231, v3, v230
	ds_bpermute_b32 v111, v3, v110
	s_waitcnt lgkmcnt(0)
	v_add_f32_e32 v158, v158, v159
	v_add_f32_e32 v170, v170, v171
	v_add_f32_e32 v182, v182, v183
	v_add_f32_e32 v194, v194, v195
	v_add_f32_e32 v206, v206, v207
	v_add_f32_e32 v218, v218, v219
	v_add_f32_e32 v230, v230, v231
	v_add_f32_e32 v110, v110, v111
	ds_bpermute_b32 v159, v4, v158
	ds_bpermute_b32 v171, v4, v170
	ds_bpermute_b32 v183, v4, v182
	ds_bpermute_b32 v195, v4, v194
	ds_bpermute_b32 v207, v4, v206
	ds_bpermute_b32 v219, v4, v218
	ds_bpermute_b32 v231, v4, v230
	ds_bpermute_b32 v111, v4, v110
	s_waitcnt lgkmcnt(0)
	v_add_f32_e32 v158, v158, v159
	v_add_f32_e32 v170, v170, v171
	v_add_f32_e32 v182, v182, v183
	v_add_f32_e32 v194, v194, v195
	v_add_f32_e32 v206, v206, v207
	v_add_f32_e32 v218, v218, v219
	v_add_f32_e32 v230, v230, v231
	v_add_f32_e32 v110, v110, v111
	ds_bpermute_b32 v159, v5, v158
	ds_bpermute_b32 v171, v5, v170
	ds_bpermute_b32 v183, v5, v182
	ds_bpermute_b32 v195, v5, v194
	ds_bpermute_b32 v207, v5, v206
	ds_bpermute_b32 v219, v5, v218
	ds_bpermute_b32 v231, v5, v230
	ds_bpermute_b32 v111, v5, v110
	s_waitcnt lgkmcnt(0)
	v_add_f32_e32 v158, v158, v159
	v_add_f32_e32 v170, v170, v171
	v_add_f32_e32 v182, v182, v183
	v_add_f32_e32 v194, v194, v195
	v_add_f32_e32 v206, v206, v207
	v_add_f32_e32 v218, v218, v219
	v_add_f32_e32 v230, v230, v231
	v_add_f32_e32 v110, v110, v111
	ds_bpermute_b32 v159, v6, v158
	ds_bpermute_b32 v171, v6, v170
	ds_bpermute_b32 v183, v6, v182
	ds_bpermute_b32 v195, v6, v194
	ds_bpermute_b32 v207, v6, v206
	ds_bpermute_b32 v219, v6, v218
	ds_bpermute_b32 v231, v6, v230
	ds_bpermute_b32 v111, v6, v110
	s_waitcnt lgkmcnt(0)
	v_add_f32_e32 v158, v158, v159
	v_add_f32_e32 v170, v170, v171
	v_add_f32_e32 v182, v182, v183
	v_add_f32_e32 v194, v194, v195
	v_add_f32_e32 v206, v206, v207
	v_add_f32_e32 v218, v218, v219
	v_add_f32_e32 v230, v230, v231
	v_add_f32_e32 v110, v110, v111
	ds_bpermute_b32 v159, v7, v158
	ds_bpermute_b32 v171, v7, v170
	ds_bpermute_b32 v183, v7, v182
	ds_bpermute_b32 v195, v7, v194
	ds_bpermute_b32 v207, v7, v206
	ds_bpermute_b32 v219, v7, v218
	ds_bpermute_b32 v231, v7, v230
	ds_bpermute_b32 v111, v7, v110
	s_waitcnt lgkmcnt(0)
	v_add_f32_e32 v158, v158, v159
	v_add_f32_e32 v170, v170, v171
	v_add_f32_e32 v182, v182, v183
	v_add_f32_e32 v194, v194, v195
	v_add_f32_e32 v206, v206, v207
	v_add_f32_e32 v218, v218, v219
	v_add_f32_e32 v230, v230, v231
	v_add_f32_e32 v110, v110, v111
	s_waitcnt vmcnt(0)
; __device__ __forceinline__ void headnorm_phase(KP p, int wv, const int seg, const int gw, const int nw) {
;     ...
;     const float rs = rsqrtf(ss * (1.f / 128.f) + 1e-6f);
;     const float4 w = *(const float4*)((grp < 8 ? p->hgrn_nw : p->gdn_nw) + (lane & 31) * 4);
;     const float4 g = (grp < 8) ? *(const float4*)(p->proj + (long)tok * PW + 6144 + c)
;                                : *(const float4*)(p->proj + (long)tok * PW + 12288 + (c - 2048));
;     u16x4 r;
;     r[0] = f2bf(o.x * rs * w.x * g.x); r[1] = f2bf(o.y * rs * w.y * g.y);
;     r[2] = f2bf(o.z * rs * w.z * g.z); r[3] = f2bf(o.w * rs * w.w * g.w);
;     *(u16x4*)(p->h + (long)tok * D + c) = r;
	s_mov_b32 s20, s36
	v_fmamk_f32 v158, v158, 0x3c000000, v9
	v_mul_f32_e32 v232, 0x4b800000, v158
	v_cmp_gt_f32_e32 vcc, s15, v158
	s_nop 1
	v_cndmask_b32_e32 v158, v158, v232, vcc
	v_rsq_f32_e32 v158, v158
	s_nop 0
	v_mul_f32_e32 v232, 0x45800000, v158
	v_cndmask_b32_e32 v158, v158, v232, vcc
	v_pk_mul_f32 v[148:149], v[148:149], v[158:159] op_sel_hi:[1,0]
	v_pk_mul_f32 v[150:151], v[150:151], v[158:159] op_sel_hi:[1,0]
	s_and_b32 s17, s20, 15
	s_cmp_lt_u32 s17, 8
	s_cselect_b64 vcc, -1, 0
	s_add_i32 s20, s20, s37
	s_nop 1
	v_cndmask_b32_e32 v244, v240, v236, vcc
	v_cndmask_b32_e32 v245, v241, v237, vcc
	v_cndmask_b32_e32 v246, v242, v238, vcc
	v_cndmask_b32_e32 v247, v243, v239, vcc
	v_pk_mul_f32 v[148:149], v[244:245], v[148:149]
	v_pk_mul_f32 v[150:151], v[246:247], v[150:151]
	v_pk_mul_f32 v[148:149], v[152:153], v[148:149]
	v_pk_mul_f32 v[150:151], v[154:155], v[150:151]
	v_bfe_u32 v232, v148, 16, 1
	v_bfe_u32 v233, v149, 16, 1
	v_bfe_u32 v234, v150, 16, 1
	v_bfe_u32 v235, v151, 16, 1
	v_add3_u32 v148, v148, v232, s14
	v_add3_u32 v149, v149, v233, s14
	v_add3_u32 v150, v150, v234, s14
	v_add3_u32 v151, v151, v235, s14
	v_perm_b32 v148, v149, v148, s16
	v_perm_b32 v149, v151, v150, s16
	global_store_dwordx2 v[156:157], v[148:149], off nt
	v_fmamk_f32 v170, v170, 0x3c000000, v9
	v_mul_f32_e32 v232, 0x4b800000, v170
	v_cmp_gt_f32_e32 vcc, s15, v170
	s_nop 1
	v_cndmask_b32_e32 v170, v170, v232, vcc
	v_rsq_f32_e32 v170, v170
	s_nop 0
	v_mul_f32_e32 v232, 0x45800000, v170
	v_cndmask_b32_e32 v170, v170, v232, vcc
	v_pk_mul_f32 v[160:161], v[160:161], v[170:171] op_sel_hi:[1,0]
	v_pk_mul_f32 v[162:163], v[162:163], v[170:171] op_sel_hi:[1,0]
	s_and_b32 s17, s20, 15
	s_cmp_lt_u32 s17, 8
	s_cselect_b64 vcc, -1, 0
	s_add_i32 s20, s20, s37
	s_nop 1
	v_cndmask_b32_e32 v244, v240, v236, vcc
	v_cndmask_b32_e32 v245, v241, v237, vcc
	v_cndmask_b32_e32 v246, v242, v238, vcc
	v_cndmask_b32_e32 v247, v243, v239, vcc
	v_pk_mul_f32 v[160:161], v[244:245], v[160:161]
	v_pk_mul_f32 v[162:163], v[246:247], v[162:163]
	v_pk_mul_f32 v[160:161], v[164:165], v[160:161]
	v_pk_mul_f32 v[162:163], v[166:167], v[162:163]
	v_bfe_u32 v232, v160, 16, 1
	v_bfe_u32 v233, v161, 16, 1
	v_bfe_u32 v234, v162, 16, 1
	v_bfe_u32 v235, v163, 16, 1
	v_add3_u32 v160, v160, v232, s14
	v_add3_u32 v161, v161, v233, s14
	v_add3_u32 v162, v162, v234, s14
	v_add3_u32 v163, v163, v235, s14
	v_perm_b32 v160, v161, v160, s16
	v_perm_b32 v161, v163, v162, s16
	global_store_dwordx2 v[168:169], v[160:161], off nt
	v_fmamk_f32 v182, v182, 0x3c000000, v9
	v_mul_f32_e32 v232, 0x4b800000, v182
	v_cmp_gt_f32_e32 vcc, s15, v182
	s_nop 1
	v_cndmask_b32_e32 v182, v182, v232, vcc
	v_rsq_f32_e32 v182, v182
	s_nop 0
	v_mul_f32_e32 v232, 0x45800000, v182
	v_cndmask_b32_e32 v182, v182, v232, vcc
	v_pk_mul_f32 v[172:173], v[172:173], v[182:183] op_sel_hi:[1,0]
	v_pk_mul_f32 v[174:175], v[174:175], v[182:183] op_sel_hi:[1,0]
	s_and_b32 s17, s20, 15
	s_cmp_lt_u32 s17, 8
	s_cselect_b64 vcc, -1, 0
	s_add_i32 s20, s20, s37
	s_nop 1
	v_cndmask_b32_e32 v244, v240, v236, vcc
	v_cndmask_b32_e32 v245, v241, v237, vcc
	v_cndmask_b32_e32 v246, v242, v238, vcc
	v_cndmask_b32_e32 v247, v243, v239, vcc
	v_pk_mul_f32 v[172:173], v[244:245], v[172:173]
	v_pk_mul_f32 v[174:175], v[246:247], v[174:175]
	v_pk_mul_f32 v[172:173], v[176:177], v[172:173]
	v_pk_mul_f32 v[174:175], v[178:179], v[174:175]
	v_bfe_u32 v232, v172, 16, 1
	v_bfe_u32 v233, v173, 16, 1
	v_bfe_u32 v234, v174, 16, 1
	v_bfe_u32 v235, v175, 16, 1
	v_add3_u32 v172, v172, v232, s14
	v_add3_u32 v173, v173, v233, s14
	v_add3_u32 v174, v174, v234, s14
	v_add3_u32 v175, v175, v235, s14
	v_perm_b32 v172, v173, v172, s16
	v_perm_b32 v173, v175, v174, s16
	global_store_dwordx2 v[180:181], v[172:173], off nt
	v_fmamk_f32 v194, v194, 0x3c000000, v9
	v_mul_f32_e32 v232, 0x4b800000, v194
	v_cmp_gt_f32_e32 vcc, s15, v194
	s_nop 1
	v_cndmask_b32_e32 v194, v194, v232, vcc
	v_rsq_f32_e32 v194, v194
	s_nop 0
	v_mul_f32_e32 v232, 0x45800000, v194
	v_cndmask_b32_e32 v194, v194, v232, vcc
	v_pk_mul_f32 v[184:185], v[184:185], v[194:195] op_sel_hi:[1,0]
	v_pk_mul_f32 v[186:187], v[186:187], v[194:195] op_sel_hi:[1,0]
	s_and_b32 s17, s20, 15
	s_cmp_lt_u32 s17, 8
	s_cselect_b64 vcc, -1, 0
	s_add_i32 s20, s20, s37
	s_nop 1
	v_cndmask_b32_e32 v244, v240, v236, vcc
	v_cndmask_b32_e32 v245, v241, v237, vcc
	v_cndmask_b32_e32 v246, v242, v238, vcc
	v_cndmask_b32_e32 v247, v243, v239, vcc
	v_pk_mul_f32 v[184:185], v[244:245], v[184:185]
	v_pk_mul_f32 v[186:187], v[246:247], v[186:187]
	v_pk_mul_f32 v[184:185], v[188:189], v[184:185]
	v_pk_mul_f32 v[186:187], v[190:191], v[186:187]
	v_bfe_u32 v232, v184, 16, 1
	v_bfe_u32 v233, v185, 16, 1
	v_bfe_u32 v234, v186, 16, 1
	v_bfe_u32 v235, v187, 16, 1
	v_add3_u32 v184, v184, v232, s14
	v_add3_u32 v185, v185, v233, s14
	v_add3_u32 v186, v186, v234, s14
	v_add3_u32 v187, v187, v235, s14
	v_perm_b32 v184, v185, v184, s16
	v_perm_b32 v185, v187, v186, s16
	global_store_dwordx2 v[192:193], v[184:185], off nt
; __device__ __forceinline__ void headnorm_phase(KP p, int wv, const int seg, const int gw, const int nw) {
;     ...
;     const float rs = rsqrtf(ss * (1.f / 128.f) + 1e-6f);
;     const float4 w = *(const float4*)((grp < 8 ? p->hgrn_nw : p->gdn_nw) + (lane & 31) * 4);
;     const float4 g = (grp < 8) ? *(const float4*)(p->proj + (long)tok * PW + 6144 + c)
;                                : *(const float4*)(p->proj + (long)tok * PW + 12288 + (c - 2048));
;     u16x4 r;
;     r[0] = f2bf(o.x * rs * w.x * g.x); r[1] = f2bf(o.y * rs * w.y * g.y);
;     r[2] = f2bf(o.z * rs * w.z * g.z); r[3] = f2bf(o.w * rs * w.w * g.w);
;     *(u16x4*)(p->h + (long)tok * D + c) = r;
	v_fmamk_f32 v206, v206, 0x3c000000, v9
	v_mul_f32_e32 v232, 0x4b800000, v206
	v_cmp_gt_f32_e32 vcc, s15, v206
	s_nop 1
	v_cndmask_b32_e32 v206, v206, v232, vcc
	v_rsq_f32_e32 v206, v206
	s_nop 0
	v_mul_f32_e32 v232, 0x45800000, v206
	v_cndmask_b32_e32 v206, v206, v232, vcc
	v_pk_mul_f32 v[196:197], v[196:197], v[206:207] op_sel_hi:[1,0]
	v_pk_mul_f32 v[198:199], v[198:199], v[206:207] op_sel_hi:[1,0]
	s_and_b32 s17, s20, 15
	s_cmp_lt_u32 s17, 8
	s_cselect_b64 vcc, -1, 0
	s_add_i32 s20, s20, s37
	s_nop 1
	v_cndmask_b32_e32 v244, v240, v236, vcc
	v_cndmask_b32_e32 v245, v241, v237, vcc
	v_cndmask_b32_e32 v246, v242, v238, vcc
	v_cndmask_b32_e32 v247, v243, v239, vcc
	v_pk_mul_f32 v[196:197], v[244:245], v[196:197]
	v_pk_mul_f32 v[198:199], v[246:247], v[198:199]
	v_pk_mul_f32 v[196:197], v[200:201], v[196:197]
	v_pk_mul_f32 v[198:199], v[202:203], v[198:199]
	v_bfe_u32 v232, v196, 16, 1
	v_bfe_u32 v233, v197, 16, 1
	v_bfe_u32 v234, v198, 16, 1
	v_bfe_u32 v235, v199, 16, 1
	v_add3_u32 v196, v196, v232, s14
	v_add3_u32 v197, v197, v233, s14
	v_add3_u32 v198, v198, v234, s14
	v_add3_u32 v199, v199, v235, s14
	v_perm_b32 v196, v197, v196, s16
	v_perm_b32 v197, v199, v198, s16
	global_store_dwordx2 v[204:205], v[196:197], off nt
	v_fmamk_f32 v218, v218, 0x3c000000, v9
	v_mul_f32_e32 v232, 0x4b800000, v218
	v_cmp_gt_f32_e32 vcc, s15, v218
	s_nop 1
	v_cndmask_b32_e32 v218, v218, v232, vcc
	v_rsq_f32_e32 v218, v218
	s_nop 0
	v_mul_f32_e32 v232, 0x45800000, v218
	v_cndmask_b32_e32 v218, v218, v232, vcc
	v_pk_mul_f32 v[208:209], v[208:209], v[218:219] op_sel_hi:[1,0]
	v_pk_mul_f32 v[210:211], v[210:211], v[218:219] op_sel_hi:[1,0]
	s_and_b32 s17, s20, 15
	s_cmp_lt_u32 s17, 8
	s_cselect_b64 vcc, -1, 0
	s_add_i32 s20, s20, s37
	s_nop 1
	v_cndmask_b32_e32 v244, v240, v236, vcc
	v_cndmask_b32_e32 v245, v241, v237, vcc
	v_cndmask_b32_e32 v246, v242, v238, vcc
	v_cndmask_b32_e32 v247, v243, v239, vcc
	v_pk_mul_f32 v[208:209], v[244:245], v[208:209]
	v_pk_mul_f32 v[210:211], v[246:247], v[210:211]
	v_pk_mul_f32 v[208:209], v[212:213], v[208:209]
	v_pk_mul_f32 v[210:211], v[214:215], v[210:211]
	v_bfe_u32 v232, v208, 16, 1
	v_bfe_u32 v233, v209, 16, 1
	v_bfe_u32 v234, v210, 16, 1
	v_bfe_u32 v235, v211, 16, 1
	v_add3_u32 v208, v208, v232, s14
	v_add3_u32 v209, v209, v233, s14
	v_add3_u32 v210, v210, v234, s14
	v_add3_u32 v211, v211, v235, s14
	v_perm_b32 v208, v209, v208, s16
	v_perm_b32 v209, v211, v210, s16
	global_store_dwordx2 v[216:217], v[208:209], off nt
	v_fmamk_f32 v230, v230, 0x3c000000, v9
	v_mul_f32_e32 v232, 0x4b800000, v230
	v_cmp_gt_f32_e32 vcc, s15, v230
	s_nop 1
	v_cndmask_b32_e32 v230, v230, v232, vcc
	v_rsq_f32_e32 v230, v230
	s_nop 0
	v_mul_f32_e32 v232, 0x45800000, v230
	v_cndmask_b32_e32 v230, v230, v232, vcc
	v_pk_mul_f32 v[220:221], v[220:221], v[230:231] op_sel_hi:[1,0]
	v_pk_mul_f32 v[222:223], v[222:223], v[230:231] op_sel_hi:[1,0]
	s_and_b32 s17, s20, 15
	s_cmp_lt_u32 s17, 8
	s_cselect_b64 vcc, -1, 0
	s_add_i32 s20, s20, s37
	s_nop 1
	v_cndmask_b32_e32 v244, v240, v236, vcc
	v_cndmask_b32_e32 v245, v241, v237, vcc
	v_cndmask_b32_e32 v246, v242, v238, vcc
	v_cndmask_b32_e32 v247, v243, v239, vcc
	v_pk_mul_f32 v[220:221], v[244:245], v[220:221]
	v_pk_mul_f32 v[222:223], v[246:247], v[222:223]
	v_pk_mul_f32 v[220:221], v[224:225], v[220:221]
	v_pk_mul_f32 v[222:223], v[226:227], v[222:223]
	v_bfe_u32 v232, v220, 16, 1
	v_bfe_u32 v233, v221, 16, 1
	v_bfe_u32 v234, v222, 16, 1
	v_bfe_u32 v235, v223, 16, 1
	v_add3_u32 v220, v220, v232, s14
	v_add3_u32 v221, v221, v233, s14
	v_add3_u32 v222, v222, v234, s14
	v_add3_u32 v223, v223, v235, s14
	v_perm_b32 v220, v221, v220, s16
	v_perm_b32 v221, v223, v222, s16
	global_store_dwordx2 v[228:229], v[220:221], off nt
	v_fmamk_f32 v110, v110, 0x3c000000, v9
	v_mul_f32_e32 v232, 0x4b800000, v110
	v_cmp_gt_f32_e32 vcc, s15, v110
	s_nop 1
	v_cndmask_b32_e32 v110, v110, v232, vcc
	v_rsq_f32_e32 v110, v110
	s_nop 0
	v_mul_f32_e32 v232, 0x45800000, v110
	v_cndmask_b32_e32 v110, v110, v232, vcc
	v_pk_mul_f32 v[100:101], v[100:101], v[110:111] op_sel_hi:[1,0]
	v_pk_mul_f32 v[102:103], v[102:103], v[110:111] op_sel_hi:[1,0]
	s_and_b32 s17, s20, 15
	s_cmp_lt_u32 s17, 8
	s_cselect_b64 vcc, -1, 0
	s_add_i32 s20, s20, s37
	s_nop 1
	v_cndmask_b32_e32 v244, v240, v236, vcc
	v_cndmask_b32_e32 v245, v241, v237, vcc
	v_cndmask_b32_e32 v246, v242, v238, vcc
	v_cndmask_b32_e32 v247, v243, v239, vcc
	v_pk_mul_f32 v[100:101], v[244:245], v[100:101]
	v_pk_mul_f32 v[102:103], v[246:247], v[102:103]
	v_pk_mul_f32 v[100:101], v[104:105], v[100:101]
	v_pk_mul_f32 v[102:103], v[106:107], v[102:103]
	v_bfe_u32 v232, v100, 16, 1
	v_bfe_u32 v233, v101, 16, 1
	v_bfe_u32 v234, v102, 16, 1
	v_bfe_u32 v235, v103, 16, 1
	v_add3_u32 v100, v100, v232, s14
	v_add3_u32 v101, v101, v233, s14
	v_add3_u32 v102, v102, v234, s14
	v_add3_u32 v103, v103, v235, s14
	v_perm_b32 v100, v101, v100, s16
	v_perm_b32 v101, v103, v102, s16
	global_store_dwordx2 v[108:109], v[100:101], off nt
	s_mov_b32 s36, s20
	s_branch .Lhn_c_top
